# hand-written retention intra units with state and value pieces staged in LDS; group-norm pass batched; state scan batched; bias-vector loop unrolled; max-reductions via permlane swaps
# speedup vs baseline: 1.1891x; 1.0696x over previous
.LBB0_15:
	s_cmp_ge_i32 s39, s56
	s_mov_b64 s[0:1], -1
	s_cbranch_scc0 .LBB0_41
	s_cmp_ge_i32 s39, s29
	s_cbranch_scc0 .LBB0_38
	s_cmp_ge_i32 s39, s57
	s_cbranch_scc0 .LBB0_35
	s_cmp_ge_i32 s39, s48
	s_cbranch_scc0 .LBB0_32
	s_cmp_ge_i32 s39, s50
	s_cbranch_scc0 .LBB0_29
	s_cmp_ge_i32 s39, s54
	s_cbranch_scc0 .LBB0_26
	s_sub_i32 s0, s39, s54
	s_cmp_eq_u32 s0, 1
	s_cselect_b64 s[0:1], -1, 0
	s_and_b64 s[2:3], s[0:1], exec
	s_cselect_b32 s3, s15, s13
	s_cselect_b32 s2, s14, s12
	s_cselect_b32 s5, s21, s17
	s_cselect_b32 s4, s20, s16
	v_lshl_add_u64 v[28:29], s[2:3], 0, v[24:25]
	v_lshl_add_u64 v[30:31], s[4:5], 0, v[26:27]
	v_mov_b32_e32 v47, 0
	s_mov_b64 s[2:3], 0
	v_mov_b32_e32 v48, v46
	s_mov_b32 s4, 64
.LBB0_22:
	global_load_dword v49, v[28:29], off offset:0
	global_load_dword v50, v[28:29], off offset:4
	global_load_dword v51, v[28:29], off offset:8
	global_load_dword v52, v[28:29], off offset:12
	global_load_dword v53, v[28:29], off offset:16
	global_load_dword v54, v[28:29], off offset:20
	global_load_dword v55, v[28:29], off offset:24
	global_load_dword v56, v[28:29], off offset:28
	global_load_dword v57, v[30:31], off offset:0
	global_load_dword v58, v[30:31], off offset:512
	global_load_dword v59, v[30:31], off offset:1024
	global_load_dword v60, v[30:31], off offset:1536
	global_load_dword v61, v[30:31], off offset:2048
	global_load_dword v62, v[30:31], off offset:2560
	global_load_dword v63, v[30:31], off offset:3072
	global_load_dword v64, v[30:31], off offset:3584
	v_lshl_add_u64 v[28:29], v[28:29], 0, 32
	v_lshl_add_u64 v[30:31], v[30:31], 0, s[74:75]
	s_waitcnt vmcnt(0)
	v_fmac_f32_e32 v47, v49, v57
	v_fmac_f32_e32 v47, v50, v58
	v_fmac_f32_e32 v47, v51, v59
	v_fmac_f32_e32 v47, v52, v60
	v_fmac_f32_e32 v47, v53, v61
	v_fmac_f32_e32 v47, v54, v62
	v_fmac_f32_e32 v47, v55, v63
	v_fmac_f32_e32 v47, v56, v64
	s_add_i32 s4, s4, -1
	s_cmp_lg_u32 s4, 0
	s_cbranch_scc1 .LBB0_22
	s_mov_b64 s[2:3], exec
	s_or_b64 exec, exec, s[2:3]
	ds_write_b32 v3, v47
	s_waitcnt lgkmcnt(0)
	s_barrier
	s_and_saveexec_b64 s[2:3], s[8:9]
	s_cbranch_execz .LBB0_25
	ds_read2st64_b32 v[28:29], v3 offset1:2
	ds_read2st64_b32 v[30:31], v3 offset0:4 offset1:6
	s_and_b64 s[0:1], s[0:1], exec
	s_cselect_b32 s0, 0x80, 0
	v_add_u32_e32 v48, s0, v1
	s_waitcnt lgkmcnt(1)
	v_add_f32_e32 v28, v28, v29
	s_waitcnt lgkmcnt(0)
	v_add_f32_e32 v28, v28, v30
	v_ashrrev_i32_e32 v49, 31, v48
	v_add_f32_e32 v30, v28, v31
	v_lshl_add_u64 v[28:29], v[48:49], 2, s[90:91]
	flat_store_dword v[28:29], v30

.Lw_pfgos:
	s_add_i32 s2, s18, 7
	s_and_b32 s2, s2, 7
	s_lshl_b32 s0, s2, 13
	s_add_i32 m0, s0, s23
	s_lshl_b32 s0, s11, 11
	s_add_u32 s16, s12, s0
	s_addc_u32 s17, s13, 0
	global_load_lds_dwordx4 v96, s[16:17]
	s_lshl_b32 s0, s18, 13
	v_add_u32_e32 v40, s0, v97
	ds_read_b128 v[56:59], v40 offset:0
	ds_read_b128 v[60:63], v40 offset:1024
	ds_read_b128 v[68:71], v40 offset:2048
	ds_read_b128 v[72:75], v40 offset:3072
	ds_read_b128 v[76:79], v40 offset:4096
	ds_read_b128 v[80:83], v40 offset:5120
	ds_read_b128 v[84:87], v40 offset:6144
	ds_read_b128 v[92:95], v40 offset:7168
	s_add_i32 s18, s18, 1
	s_and_b32 s18, s18, 7
	s_waitcnt lgkmcnt(4)
	v_mfma_f32_16x16x32_bf16 v[32:35], v[56:59], v[16:19], 0
	v_mfma_f32_16x16x32_bf16 v[36:39], v[68:71], v[16:19], 0
	v_mfma_f32_16x16x32_bf16 v[32:35], v[60:63], v[20:23], v[32:35]
	v_mfma_f32_16x16x32_bf16 v[36:39], v[72:75], v[20:23], v[36:39]
	ds_read_b32 v40, v50 offset:76
	ds_read_b32 v41, v50 offset:72
	ds_read_b32 v42, v50 offset:68
	ds_read_b32 v43, v50 offset:64
	ds_read_b32 v44, v50 offset:12
	ds_read_b32 v45, v50 offset:8
	ds_read_b32 v46, v50 offset:4
	ds_read_b32 v47, v50 offset:0
	v_add_u32_e32 v50, 0xffffff80, v50
	s_waitcnt lgkmcnt(0)
	v_pk_fma_f32 v[32:33], v[32:33], s[40:41], v[40:41] op_sel_hi:[1,0,1]
	v_pk_fma_f32 v[34:35], v[34:35], s[40:41], v[42:43] op_sel_hi:[1,0,1]
	v_pk_fma_f32 v[36:37], v[36:37], s[40:41], v[44:45] op_sel_hi:[1,0,1]
	v_pk_fma_f32 v[38:39], v[38:39], s[40:41], v[46:47] op_sel_hi:[1,0,1]
	v_max3_f32 v40, v32, v33, v34
	v_max3_f32 v41, v35, v36, v37
	v_max3_f32 v40, v40, v38, v39
	v_max_f32_e32 v40, v40, v41
	v_mov_b32_e32 v41, v40
	s_nop 1
	v_permlane16_swap_b32_e32 v41, v40
	v_max_f32_e32 v40, v40, v41
	v_mov_b32_e32 v41, v40
	s_nop 1
	v_permlane32_swap_b32_e32 v41, v40
	v_max_f32_e32 v42, v40, v41
	v_cmp_gt_f32_e32 vcc, v42, v48
	s_cbranch_vccz .Lw_noresc
	v_max_f32_e32 v42, v48, v42
	v_sub_f32_e32 v40, v48, v42
	v_exp_f32_e32 v40, v40
	v_mov_b32_e32 v48, v42
	s_nop 0
	v_pk_mul_f32 v[0:1], v[0:1], v[40:41] op_sel_hi:[1,0]
	v_pk_mul_f32 v[2:3], v[2:3], v[40:41] op_sel_hi:[1,0]
	v_pk_mul_f32 v[4:5], v[4:5], v[40:41] op_sel_hi:[1,0]
	v_pk_mul_f32 v[6:7], v[6:7], v[40:41] op_sel_hi:[1,0]
	v_pk_mul_f32 v[8:9], v[8:9], v[40:41] op_sel_hi:[1,0]
	v_pk_mul_f32 v[10:11], v[10:11], v[40:41] op_sel_hi:[1,0]
	v_pk_mul_f32 v[12:13], v[12:13], v[40:41] op_sel_hi:[1,0]
	v_pk_mul_f32 v[14:15], v[14:15], v[40:41] op_sel_hi:[1,0]
	v_mul_f32_e32 v49, v49, v40

.LBB0_446:
	s_andn2_b64 vcc, exec, s[0:1]
	s_cbranch_vccnz .LBB0_493
	s_branch .LBB0_493
	s_or_b64 exec, exec, s[38:39]

.LBB0_556:
	v_ashrrev_i32_e32 v2, 15, v8
	v_cvt_f32_i32_e32 v0, v2
	s_mov_b32 s0, 0xc2fc0000
	v_ashrrev_i32_e32 v3, 31, v2
	v_lshlrev_b32_e32 v5, 1, v9
	v_sub_f32_e32 v0, 0xc0a00000, v0
	v_cmp_gt_f32_e32 vcc, s0, v0
	v_lshlrev_b64 v[2:3], 24, v[2:3]
	v_mov_b32_e32 v4, 0
	v_cndmask_b32_e32 v1, 0, v212, vcc
	v_add_f32_e32 v0, v0, v1
	v_exp_f32_e32 v0, v0
	v_cndmask_b32_e32 v1, 0, v213, vcc
	s_mov_b64 s[12:13], 0
	v_mov_b32_e32 v6, v4
	v_ldexp_f32 v0, v0, v1
	v_sub_f32_e32 v0, 1.0, v0
	v_log_f32_e32 v0, v0
	v_mov_b32_e32 v7, v4
	v_mul_f32_e32 v1, 0x43800000, v0
	v_cmp_gt_f32_e32 vcc, s0, v1
	s_mov_b32 s0, 0x3fff8
	v_and_or_b32 v2, v5, s0, v2
	v_cndmask_b32_e32 v1, 0, v212, vcc
	v_fmac_f32_e32 v1, 0x43800000, v0
	v_exp_f32_e32 v0, v1
	v_cndmask_b32_e32 v1, 0, v213, vcc
	v_lshl_add_u64 v[2:3], s[20:21], 0, v[2:3]
	v_mov_b32_e32 v5, v4
	v_ldexp_f32 v0, v0, v1
	v_mov_b32_e32 v1, v0
	v_add_co_u32_e32 v14, vcc, 0x2d00000, v2
	s_nop 1
	v_addc_co_u32_e32 v15, vcc, 0, v3, vcc
	v_mov_b64_e32 v[16:17], v[14:15]
	v_mov_b32_e32 v10, 0
	v_mov_b32_e32 v11, 0
	v_mov_b32_e32 v12, 0
	v_mov_b32_e32 v13, 0
	s_mov_b64 s[12:13], 0x40000
	s_mov_b32 s0, 4
.LBB0_557:
	global_load_dwordx2 v[70:71], v[14:15], off
	v_lshl_add_u64 v[14:15], v[14:15], 0, s[12:13]
	global_load_dwordx2 v[72:73], v[14:15], off
	v_lshl_add_u64 v[14:15], v[14:15], 0, s[12:13]
	global_load_dwordx2 v[74:75], v[14:15], off
	v_lshl_add_u64 v[14:15], v[14:15], 0, s[12:13]
	global_load_dwordx2 v[76:77], v[14:15], off
	v_lshl_add_u64 v[14:15], v[14:15], 0, s[12:13]
	global_load_dwordx2 v[78:79], v[14:15], off
	v_lshl_add_u64 v[14:15], v[14:15], 0, s[12:13]
	global_load_dwordx2 v[80:81], v[14:15], off
	v_lshl_add_u64 v[14:15], v[14:15], 0, s[12:13]
	global_load_dwordx2 v[82:83], v[14:15], off
	v_lshl_add_u64 v[14:15], v[14:15], 0, s[12:13]
	global_load_dwordx2 v[84:85], v[14:15], off
	v_lshl_add_u64 v[14:15], v[14:15], 0, s[12:13]
	global_load_dwordx2 v[86:87], v[14:15], off
	v_lshl_add_u64 v[14:15], v[14:15], 0, s[12:13]
	global_load_dwordx2 v[88:89], v[14:15], off
	v_lshl_add_u64 v[14:15], v[14:15], 0, s[12:13]
	global_load_dwordx2 v[90:91], v[14:15], off
	v_lshl_add_u64 v[14:15], v[14:15], 0, s[12:13]
	global_load_dwordx2 v[92:93], v[14:15], off
	v_lshl_add_u64 v[14:15], v[14:15], 0, s[12:13]
	global_load_dwordx2 v[94:95], v[14:15], off
	v_lshl_add_u64 v[14:15], v[14:15], 0, s[12:13]
	global_load_dwordx2 v[96:97], v[14:15], off
	v_lshl_add_u64 v[14:15], v[14:15], 0, s[12:13]
	global_load_dwordx2 v[98:99], v[14:15], off
	v_lshl_add_u64 v[14:15], v[14:15], 0, s[12:13]
	global_load_dwordx2 v[100:101], v[14:15], off
	v_lshl_add_u64 v[14:15], v[14:15], 0, s[12:13]
	s_waitcnt vmcnt(15)
	v_cvt_pk_bf16_f32 v18, v10, v11
	v_cvt_pk_bf16_f32 v19, v12, v13
	global_store_dwordx2 v[16:17], v[18:19], off
	v_lshl_add_u64 v[16:17], v[16:17], 0, s[12:13]
	v_lshlrev_b32_e32 v20, 16, v70
	v_and_b32_e32 v21, 0xffff0000, v70
	v_lshlrev_b32_e32 v22, 16, v71
	v_and_b32_e32 v23, 0xffff0000, v71
	v_pk_add_f32 v[10:11], v[10:11], v[20:21]
	v_pk_add_f32 v[12:13], v[12:13], v[22:23]
	v_pk_mul_f32 v[10:11], v[0:1], v[10:11]
	v_pk_mul_f32 v[12:13], v[0:1], v[12:13]
	s_waitcnt vmcnt(15)
	v_cvt_pk_bf16_f32 v18, v10, v11
	v_cvt_pk_bf16_f32 v19, v12, v13
	global_store_dwordx2 v[16:17], v[18:19], off
	v_lshl_add_u64 v[16:17], v[16:17], 0, s[12:13]
	v_lshlrev_b32_e32 v20, 16, v72
	v_and_b32_e32 v21, 0xffff0000, v72
	v_lshlrev_b32_e32 v22, 16, v73
	v_and_b32_e32 v23, 0xffff0000, v73
	v_pk_add_f32 v[10:11], v[10:11], v[20:21]
	v_pk_add_f32 v[12:13], v[12:13], v[22:23]
	v_pk_mul_f32 v[10:11], v[0:1], v[10:11]
	v_pk_mul_f32 v[12:13], v[0:1], v[12:13]
	s_waitcnt vmcnt(15)
	v_cvt_pk_bf16_f32 v18, v10, v11
	v_cvt_pk_bf16_f32 v19, v12, v13
	global_store_dwordx2 v[16:17], v[18:19], off
	v_lshl_add_u64 v[16:17], v[16:17], 0, s[12:13]
	v_lshlrev_b32_e32 v20, 16, v74
	v_and_b32_e32 v21, 0xffff0000, v74
	v_lshlrev_b32_e32 v22, 16, v75
	v_and_b32_e32 v23, 0xffff0000, v75
	v_pk_add_f32 v[10:11], v[10:11], v[20:21]
	v_pk_add_f32 v[12:13], v[12:13], v[22:23]
	v_pk_mul_f32 v[10:11], v[0:1], v[10:11]
	v_pk_mul_f32 v[12:13], v[0:1], v[12:13]
	s_waitcnt vmcnt(15)
	v_cvt_pk_bf16_f32 v18, v10, v11
	v_cvt_pk_bf16_f32 v19, v12, v13
	global_store_dwordx2 v[16:17], v[18:19], off
	v_lshl_add_u64 v[16:17], v[16:17], 0, s[12:13]
	v_lshlrev_b32_e32 v20, 16, v76
	v_and_b32_e32 v21, 0xffff0000, v76
	v_lshlrev_b32_e32 v22, 16, v77
	v_and_b32_e32 v23, 0xffff0000, v77
	v_pk_add_f32 v[10:11], v[10:11], v[20:21]
	v_pk_add_f32 v[12:13], v[12:13], v[22:23]
	v_pk_mul_f32 v[10:11], v[0:1], v[10:11]
	v_pk_mul_f32 v[12:13], v[0:1], v[12:13]
	s_waitcnt vmcnt(15)
	v_cvt_pk_bf16_f32 v18, v10, v11
	v_cvt_pk_bf16_f32 v19, v12, v13
	global_store_dwordx2 v[16:17], v[18:19], off
	v_lshl_add_u64 v[16:17], v[16:17], 0, s[12:13]
	v_lshlrev_b32_e32 v20, 16, v78
	v_and_b32_e32 v21, 0xffff0000, v78
	v_lshlrev_b32_e32 v22, 16, v79
	v_and_b32_e32 v23, 0xffff0000, v79
	v_pk_add_f32 v[10:11], v[10:11], v[20:21]
	v_pk_add_f32 v[12:13], v[12:13], v[22:23]
	v_pk_mul_f32 v[10:11], v[0:1], v[10:11]
	v_pk_mul_f32 v[12:13], v[0:1], v[12:13]
	s_waitcnt vmcnt(15)
	v_cvt_pk_bf16_f32 v18, v10, v11
	v_cvt_pk_bf16_f32 v19, v12, v13
	global_store_dwordx2 v[16:17], v[18:19], off
	v_lshl_add_u64 v[16:17], v[16:17], 0, s[12:13]
	v_lshlrev_b32_e32 v20, 16, v80
	v_and_b32_e32 v21, 0xffff0000, v80
	v_lshlrev_b32_e32 v22, 16, v81
	v_and_b32_e32 v23, 0xffff0000, v81
	v_pk_add_f32 v[10:11], v[10:11], v[20:21]
	v_pk_add_f32 v[12:13], v[12:13], v[22:23]
	v_pk_mul_f32 v[10:11], v[0:1], v[10:11]
	v_pk_mul_f32 v[12:13], v[0:1], v[12:13]
	s_waitcnt vmcnt(15)
	v_cvt_pk_bf16_f32 v18, v10, v11
	v_cvt_pk_bf16_f32 v19, v12, v13
	global_store_dwordx2 v[16:17], v[18:19], off
	v_lshl_add_u64 v[16:17], v[16:17], 0, s[12:13]
	v_lshlrev_b32_e32 v20, 16, v82
	v_and_b32_e32 v21, 0xffff0000, v82
	v_lshlrev_b32_e32 v22, 16, v83
	v_and_b32_e32 v23, 0xffff0000, v83
	v_pk_add_f32 v[10:11], v[10:11], v[20:21]
	v_pk_add_f32 v[12:13], v[12:13], v[22:23]
	v_pk_mul_f32 v[10:11], v[0:1], v[10:11]
	v_pk_mul_f32 v[12:13], v[0:1], v[12:13]
	s_waitcnt vmcnt(15)
	v_cvt_pk_bf16_f32 v18, v10, v11
	v_cvt_pk_bf16_f32 v19, v12, v13
	global_store_dwordx2 v[16:17], v[18:19], off
	v_lshl_add_u64 v[16:17], v[16:17], 0, s[12:13]
	v_lshlrev_b32_e32 v20, 16, v84
	v_and_b32_e32 v21, 0xffff0000, v84
	v_lshlrev_b32_e32 v22, 16, v85
	v_and_b32_e32 v23, 0xffff0000, v85
	v_pk_add_f32 v[10:11], v[10:11], v[20:21]
	v_pk_add_f32 v[12:13], v[12:13], v[22:23]
	v_pk_mul_f32 v[10:11], v[0:1], v[10:11]
	v_pk_mul_f32 v[12:13], v[0:1], v[12:13]
	s_waitcnt vmcnt(15)
	v_cvt_pk_bf16_f32 v18, v10, v11
	v_cvt_pk_bf16_f32 v19, v12, v13
	global_store_dwordx2 v[16:17], v[18:19], off
	v_lshl_add_u64 v[16:17], v[16:17], 0, s[12:13]
	v_lshlrev_b32_e32 v20, 16, v86
	v_and_b32_e32 v21, 0xffff0000, v86
	v_lshlrev_b32_e32 v22, 16, v87
	v_and_b32_e32 v23, 0xffff0000, v87
	v_pk_add_f32 v[10:11], v[10:11], v[20:21]
	v_pk_add_f32 v[12:13], v[12:13], v[22:23]
	v_pk_mul_f32 v[10:11], v[0:1], v[10:11]
	v_pk_mul_f32 v[12:13], v[0:1], v[12:13]
	s_waitcnt vmcnt(15)
	v_cvt_pk_bf16_f32 v18, v10, v11
	v_cvt_pk_bf16_f32 v19, v12, v13
	global_store_dwordx2 v[16:17], v[18:19], off
	v_lshl_add_u64 v[16:17], v[16:17], 0, s[12:13]
	v_lshlrev_b32_e32 v20, 16, v88
	v_and_b32_e32 v21, 0xffff0000, v88
	v_lshlrev_b32_e32 v22, 16, v89
	v_and_b32_e32 v23, 0xffff0000, v89
	v_pk_add_f32 v[10:11], v[10:11], v[20:21]
	v_pk_add_f32 v[12:13], v[12:13], v[22:23]
	v_pk_mul_f32 v[10:11], v[0:1], v[10:11]
	v_pk_mul_f32 v[12:13], v[0:1], v[12:13]
	s_waitcnt vmcnt(15)
	v_cvt_pk_bf16_f32 v18, v10, v11
	v_cvt_pk_bf16_f32 v19, v12, v13
	global_store_dwordx2 v[16:17], v[18:19], off
	v_lshl_add_u64 v[16:17], v[16:17], 0, s[12:13]
	v_lshlrev_b32_e32 v20, 16, v90
	v_and_b32_e32 v21, 0xffff0000, v90
	v_lshlrev_b32_e32 v22, 16, v91
	v_and_b32_e32 v23, 0xffff0000, v91
	v_pk_add_f32 v[10:11], v[10:11], v[20:21]
	v_pk_add_f32 v[12:13], v[12:13], v[22:23]
	v_pk_mul_f32 v[10:11], v[0:1], v[10:11]
	v_pk_mul_f32 v[12:13], v[0:1], v[12:13]
	s_waitcnt vmcnt(15)
	v_cvt_pk_bf16_f32 v18, v10, v11
	v_cvt_pk_bf16_f32 v19, v12, v13
	global_store_dwordx2 v[16:17], v[18:19], off
	v_lshl_add_u64 v[16:17], v[16:17], 0, s[12:13]
	v_lshlrev_b32_e32 v20, 16, v92
	v_and_b32_e32 v21, 0xffff0000, v92
	v_lshlrev_b32_e32 v22, 16, v93
	v_and_b32_e32 v23, 0xffff0000, v93
	v_pk_add_f32 v[10:11], v[10:11], v[20:21]
	v_pk_add_f32 v[12:13], v[12:13], v[22:23]
	v_pk_mul_f32 v[10:11], v[0:1], v[10:11]
	v_pk_mul_f32 v[12:13], v[0:1], v[12:13]
	s_waitcnt vmcnt(15)
	v_cvt_pk_bf16_f32 v18, v10, v11
	v_cvt_pk_bf16_f32 v19, v12, v13
	global_store_dwordx2 v[16:17], v[18:19], off
	v_lshl_add_u64 v[16:17], v[16:17], 0, s[12:13]
	v_lshlrev_b32_e32 v20, 16, v94
	v_and_b32_e32 v21, 0xffff0000, v94
	v_lshlrev_b32_e32 v22, 16, v95
	v_and_b32_e32 v23, 0xffff0000, v95
	v_pk_add_f32 v[10:11], v[10:11], v[20:21]
	v_pk_add_f32 v[12:13], v[12:13], v[22:23]
	v_pk_mul_f32 v[10:11], v[0:1], v[10:11]
	v_pk_mul_f32 v[12:13], v[0:1], v[12:13]
	s_waitcnt vmcnt(15)
	v_cvt_pk_bf16_f32 v18, v10, v11
	v_cvt_pk_bf16_f32 v19, v12, v13
	global_store_dwordx2 v[16:17], v[18:19], off
	v_lshl_add_u64 v[16:17], v[16:17], 0, s[12:13]
	v_lshlrev_b32_e32 v20, 16, v96
	v_and_b32_e32 v21, 0xffff0000, v96
	v_lshlrev_b32_e32 v22, 16, v97
	v_and_b32_e32 v23, 0xffff0000, v97
	v_pk_add_f32 v[10:11], v[10:11], v[20:21]
	v_pk_add_f32 v[12:13], v[12:13], v[22:23]
	v_pk_mul_f32 v[10:11], v[0:1], v[10:11]
	v_pk_mul_f32 v[12:13], v[0:1], v[12:13]
	s_waitcnt vmcnt(15)
	v_cvt_pk_bf16_f32 v18, v10, v11
	v_cvt_pk_bf16_f32 v19, v12, v13
	global_store_dwordx2 v[16:17], v[18:19], off
	v_lshl_add_u64 v[16:17], v[16:17], 0, s[12:13]
	v_lshlrev_b32_e32 v20, 16, v98
	v_and_b32_e32 v21, 0xffff0000, v98
	v_lshlrev_b32_e32 v22, 16, v99
	v_and_b32_e32 v23, 0xffff0000, v99
	v_pk_add_f32 v[10:11], v[10:11], v[20:21]
	v_pk_add_f32 v[12:13], v[12:13], v[22:23]
	v_pk_mul_f32 v[10:11], v[0:1], v[10:11]
	v_pk_mul_f32 v[12:13], v[0:1], v[12:13]
	s_waitcnt vmcnt(15)
	v_cvt_pk_bf16_f32 v18, v10, v11
	v_cvt_pk_bf16_f32 v19, v12, v13
	global_store_dwordx2 v[16:17], v[18:19], off
	v_lshl_add_u64 v[16:17], v[16:17], 0, s[12:13]
	v_lshlrev_b32_e32 v20, 16, v100
	v_and_b32_e32 v21, 0xffff0000, v100
	v_lshlrev_b32_e32 v22, 16, v101
	v_and_b32_e32 v23, 0xffff0000, v101
	v_pk_add_f32 v[10:11], v[10:11], v[20:21]
	v_pk_add_f32 v[12:13], v[12:13], v[22:23]
	v_pk_mul_f32 v[10:11], v[0:1], v[10:11]
	v_pk_mul_f32 v[12:13], v[0:1], v[12:13]
	s_add_i32 s0, s0, -1
	s_cmp_lg_u32 s0, 0
	s_cbranch_scc1 .LBB0_557
	v_readlane_b32 s0, v254, 11
	s_nop 1
	v_add_u32_e32 v8, s0, v8
	s_mov_b32 s0, 0x1ffff
	v_cmp_lt_i32_e32 vcc, s0, v8
	v_readlane_b32 s0, v254, 20
	s_or_b64 s[10:11], vcc, s[10:11]
	s_nop 0
	v_add_u32_e32 v9, s0, v9
	s_andn2_b64 exec, exec, s[10:11]
	s_cbranch_execnz .LBB0_556

.LBB0_698:
	s_andn2_b64 vcc, exec, s[0:1]
	s_cbranch_vccnz .LBB0_992
	v_readlane_b32 s0, v254, 5
	v_readlane_b32 s1, v254, 6
	s_load_dwordx4 s[40:43], s[0:1], 0xa0
	s_load_dword s2, s[0:1], 0xb0
	v_mov_b32_e32 v0, v208
	s_waitcnt lgkmcnt(0)
	s_mov_b64 s[26:27], s[42:43]
	v_writelane_b32 v254, s2, 46
	v_ashrrev_i32_e32 v220, 6, v0
	v_readlane_b32 s2, v254, 0
	s_add_u32 s24, s26, 0x6d00000
	s_addc_u32 s25, s27, 0
	v_mov_b32_e32 v0, v208
	s_cmpk_gt_i32 s2, 0xff
	v_writelane_b32 v254, s2, 47
	s_cbranch_scc1 .LBB0_748
	s_cmpk_lg_i32 s46, 0x100
	s_cbranch_scc1 .Lintra_orig
	v_readlane_b32 s2, v254, 47
	v_readfirstlane_b32 s3, v220
	s_load_dwordx2 s[28:29], s[0:1], 0x48
	v_readlane_b32 s6, v254, 39
	v_readlane_b32 s7, v254, 40
	s_lshr_b32 s4, s2, 6
	s_and_b32 s5, s2, 63
	v_and_b32_e32 v221, 15, v208
	v_bfe_u32 v222, v208, 4, 2
	v_lshlrev_b32_e32 v200, 6, v221
	v_lshl_add_u32 v200, v222, 4, v200
	v_mul_u32_u24_e32 v204, 0x1800, v221
	v_lshl_add_u32 v204, v222, 3, v204
	v_lshlrev_b32_e32 v205, 12, v221
	v_lshl_add_u32 v205, v222, 3, v205
	v_lshlrev_b32_e32 v206, 4, v222
	v_lshlrev_b32_e32 v223, 2, v222
	v_sub_u32_e32 v201, v221, v223
	v_mov_b32_e32 v231, v201
	v_and_b32_e32 v207, 63, v208
	v_lshlrev_b32_e32 v207, 4, v207
	v_add_u32_e32 v230, 0x10000, v207
	s_lshl_b32 s11, s3, 13
	s_lshl_b32 s0, s4, 23
	s_add_i32 s1, s0, 0xcd00000
	s_add_u32 s12, s26, s1
	s_addc_u32 s13, s27, 0
	s_add_i32 s1, s0, 0xed00000
	s_add_u32 s14, s26, s1
	s_addc_u32 s15, s27, 0
	s_lshl_b32 s0, s5, 17
	s_add_u32 s14, s14, s0
	s_addc_u32 s15, s15, 0
	s_lshl_b32 s0, s4, 24
	s_lshl_b32 s1, s5, 18
	s_add_i32 s0, s0, s1
	s_add_i32 s0, s0, 0x12d00000
	s_add_u32 s16, s26, s0
	s_addc_u32 s17, s27, 0
	s_lshl_b32 s0, s4, 6
	s_add_i32 s0, s0, s5
	s_lshl_b32 s0, s0, 18
	s_add_i32 s0, s0, 0x2d00000
	s_add_u32 s18, s26, s0
	s_addc_u32 s19, s27, 0
	s_lshl_b32 s0, s4, 10
	s_add_u32 s20, s24, s0
	s_addc_u32 s21, s25, 0
	s_add_i32 s1, s0, 0x16d00000
	s_add_u32 s22, s26, s1
	s_addc_u32 s23, s27, 0
	s_waitcnt lgkmcnt(0)
	s_add_u32 s28, s28, s6
	s_addc_u32 s29, s29, s7
	s_lshl_b32 s0, s4, 11
	s_add_u32 s28, s28, s0
	s_addc_u32 s29, s29, 0
	s_mov_b32 s6, 0
.Lintra_unit:
	s_sub_i32 s0, 15, s3
	s_cmp_eq_u32 s6, 0
	s_cselect_b32 s7, s3, s0
	s_lshl_b32 s0, s5, 4
	s_add_i32 s0, s0, s7
	s_lshl_b32 s8, s0, 4
	s_lshr_b32 s9, s7, 1
	s_add_i32 s9, s9, 1
	s_lshl_b32 s1, s7, 4
	v_add_u32_e32 v201, s1, v231
	s_lshl_b32 s0, s0, 13
	s_add_u32 s30, s12, s0
	s_addc_u32 s31, s13, 0
	global_load_dwordx4 v[0:3], v200, s[30:31] offset:0
	global_load_dwordx4 v[4:7], v200, s[30:31] offset:1024
	global_load_dwordx4 v[8:11], v200, s[30:31] offset:2048
	global_load_dwordx4 v[12:15], v200, s[30:31] offset:3072
	s_add_u32 s30, s30, 0x1000
	s_addc_u32 s31, s31, 0
	global_load_dwordx4 v[16:19], v200, s[30:31] offset:0
	global_load_dwordx4 v[20:23], v200, s[30:31] offset:1024
	global_load_dwordx4 v[24:27], v200, s[30:31] offset:2048
	global_load_dwordx4 v[28:31], v200, s[30:31] offset:3072
	s_mov_b32 s0, 0
	s_mov_b32 s1, 0
	s_add_u32 s34, s18, s0
	s_addc_u32 s35, s19, 0
	s_add_u32 s34, s34, s11
	s_addc_u32 s35, s35, 0
	s_add_i32 s1, s1, s11
	s_add_i32 m0, s1, 0
	s_nop 0
	global_load_lds_dwordx4 v200, s[34:35]
	s_add_i32 m0, s1, 1024
	s_add_u32 s34, s34, 0x400
	s_addc_u32 s35, s35, 0
	global_load_lds_dwordx4 v200, s[34:35]
	s_add_i32 m0, s1, 2048
	s_add_u32 s34, s34, 0x400
	s_addc_u32 s35, s35, 0
	global_load_lds_dwordx4 v200, s[34:35]
	s_add_i32 m0, s1, 3072
	s_add_u32 s34, s34, 0x400
	s_addc_u32 s35, s35, 0
	global_load_lds_dwordx4 v200, s[34:35]
	s_add_i32 m0, s1, 4096
	s_add_u32 s34, s34, 0x400
	s_addc_u32 s35, s35, 0
	global_load_lds_dwordx4 v200, s[34:35]
	s_add_i32 m0, s1, 5120
	s_add_u32 s34, s34, 0x400
	s_addc_u32 s35, s35, 0
	global_load_lds_dwordx4 v200, s[34:35]
	s_add_i32 m0, s1, 6144
	s_add_u32 s34, s34, 0x400
	s_addc_u32 s35, s35, 0
	global_load_lds_dwordx4 v200, s[34:35]
	s_add_i32 m0, s1, 7168
	s_add_u32 s34, s34, 0x400
	s_addc_u32 s35, s35, 0
	global_load_lds_dwordx4 v200, s[34:35]
	s_add_u32 s34, s14, 0
	s_addc_u32 s35, s15, 0
	s_add_u32 s36, s34, 0x1000
	s_addc_u32 s37, s35, 0
	s_add_u32 s38, s34, 0x2000
	s_addc_u32 s39, s35, 0
	s_add_u32 s0, s34, 0x3000
	s_addc_u32 s1, s35, 0
	global_load_dwordx4 v[68:71], v200, s[34:35] offset:0
	global_load_dwordx4 v[72:75], v200, s[34:35] offset:1024
	global_load_dwordx4 v[76:79], v200, s[34:35] offset:2048
	global_load_dwordx4 v[80:83], v200, s[34:35] offset:3072
	global_load_dwordx4 v[84:87], v200, s[36:37] offset:0
	global_load_dwordx4 v[88:91], v200, s[36:37] offset:1024
	global_load_dwordx4 v[92:95], v200, s[36:37] offset:2048
	global_load_dwordx4 v[96:99], v200, s[36:37] offset:3072
	global_load_dwordx4 v[100:103], v200, s[38:39] offset:0
	global_load_dwordx4 v[104:107], v200, s[38:39] offset:1024
	global_load_dwordx4 v[108:111], v200, s[38:39] offset:2048
	global_load_dwordx4 v[112:115], v200, s[38:39] offset:3072
	global_load_dwordx4 v[116:119], v200, s[0:1] offset:0
	global_load_dwordx4 v[120:123], v200, s[0:1] offset:1024
	global_load_dwordx4 v[124:127], v200, s[0:1] offset:2048
	global_load_dwordx4 v[128:131], v200, s[0:1] offset:3072
.Lintra_a0:
	s_cmp_ge_i32 s9, 2
	s_cbranch_scc0 .Lintra_a0_last
	s_add_u32 s34, s14, 16384
	s_addc_u32 s35, s15, 0
	s_add_u32 s36, s34, 0x1000
	s_addc_u32 s37, s35, 0
	s_add_u32 s38, s34, 0x2000
	s_addc_u32 s39, s35, 0
	s_add_u32 s0, s34, 0x3000
	s_addc_u32 s1, s35, 0
	global_load_dwordx4 v[132:135], v200, s[34:35] offset:0
	global_load_dwordx4 v[136:139], v200, s[34:35] offset:1024
	global_load_dwordx4 v[144:147], v200, s[34:35] offset:2048
	global_load_dwordx4 v[148:151], v200, s[34:35] offset:3072
	global_load_dwordx4 v[152:155], v200, s[36:37] offset:0
	global_load_dwordx4 v[156:159], v200, s[36:37] offset:1024
	global_load_dwordx4 v[160:163], v200, s[36:37] offset:2048
	global_load_dwordx4 v[164:167], v200, s[36:37] offset:3072
	global_load_dwordx4 v[168:171], v200, s[38:39] offset:0
	global_load_dwordx4 v[172:175], v200, s[38:39] offset:1024
	global_load_dwordx4 v[176:179], v200, s[38:39] offset:2048
	global_load_dwordx4 v[180:183], v200, s[38:39] offset:3072
	global_load_dwordx4 v[184:187], v200, s[0:1] offset:0
	global_load_dwordx4 v[188:191], v200, s[0:1] offset:1024
	global_load_dwordx4 v[192:195], v200, s[0:1] offset:2048
	global_load_dwordx4 v[196:199], v200, s[0:1] offset:3072
	s_waitcnt vmcnt(16)
	s_branch .Lintra_a0_go

.Lintra_a0_go:
	v_mfma_f32_16x16x32_bf16 v[232:235], v[68:71], v[0:3], 0
	v_mfma_f32_16x16x32_bf16 v[236:239], v[100:103], v[0:3], 0
	v_mfma_f32_16x16x32_bf16 v[232:235], v[72:75], v[4:7], v[232:235]
	v_mfma_f32_16x16x32_bf16 v[236:239], v[104:107], v[4:7], v[236:239]
	v_mfma_f32_16x16x32_bf16 v[232:235], v[76:79], v[8:11], v[232:235]
	v_mfma_f32_16x16x32_bf16 v[236:239], v[108:111], v[8:11], v[236:239]
	v_mfma_f32_16x16x32_bf16 v[232:235], v[80:83], v[12:15], v[232:235]
	v_mfma_f32_16x16x32_bf16 v[236:239], v[112:115], v[12:15], v[236:239]
	v_mfma_f32_16x16x32_bf16 v[232:235], v[84:87], v[16:19], v[232:235]
	v_mfma_f32_16x16x32_bf16 v[236:239], v[116:119], v[16:19], v[236:239]
	v_mfma_f32_16x16x32_bf16 v[232:235], v[88:91], v[20:23], v[232:235]
	v_mfma_f32_16x16x32_bf16 v[236:239], v[120:123], v[20:23], v[236:239]
	v_mfma_f32_16x16x32_bf16 v[232:235], v[92:95], v[24:27], v[232:235]
	v_mfma_f32_16x16x32_bf16 v[236:239], v[124:127], v[24:27], v[236:239]
	v_mfma_f32_16x16x32_bf16 v[232:235], v[96:99], v[28:31], v[232:235]
	v_mfma_f32_16x16x32_bf16 v[236:239], v[128:131], v[28:31], v[236:239]
	s_nop 7
	s_nop 1
	v_cmp_le_i32_e32 vcc, 0, v201
	s_nop 1
	v_cndmask_b32_e32 v232, 0, v232, vcc
	v_cmp_le_i32_e32 vcc, 1, v201
	s_nop 1
	v_cndmask_b32_e32 v233, 0, v233, vcc
	v_cmp_le_i32_e32 vcc, 2, v201
	s_nop 1
	v_cndmask_b32_e32 v234, 0, v234, vcc
	v_cmp_le_i32_e32 vcc, 3, v201
	s_nop 1
	v_cndmask_b32_e32 v235, 0, v235, vcc
	v_cmp_le_i32_e32 vcc, 16, v201
	s_nop 1
	v_cndmask_b32_e32 v236, 0, v236, vcc
	v_cmp_le_i32_e32 vcc, 17, v201
	s_nop 1
	v_cndmask_b32_e32 v237, 0, v237, vcc
	v_cmp_le_i32_e32 vcc, 18, v201
	s_nop 1
	v_cndmask_b32_e32 v238, 0, v238, vcc
	v_cmp_le_i32_e32 vcc, 19, v201
	s_nop 1
	v_cndmask_b32_e32 v239, 0, v239, vcc
	v_cvt_pk_bf16_f32 v32, v232, v233
	v_cvt_pk_bf16_f32 v33, v234, v235
	v_cvt_pk_bf16_f32 v34, v236, v237
	v_cvt_pk_bf16_f32 v35, v238, v239
	s_cmp_ge_i32 s9, 2
	s_cbranch_scc0 .Lintra_b
.Lintra_a1:
	s_cmp_ge_i32 s9, 3
	s_cbranch_scc0 .Lintra_a1_last
	s_add_u32 s34, s14, 32768
	s_addc_u32 s35, s15, 0
	s_add_u32 s36, s34, 0x1000
	s_addc_u32 s37, s35, 0
	s_add_u32 s38, s34, 0x2000
	s_addc_u32 s39, s35, 0
	s_add_u32 s0, s34, 0x3000
	s_addc_u32 s1, s35, 0
	global_load_dwordx4 v[68:71], v200, s[34:35] offset:0
	global_load_dwordx4 v[72:75], v200, s[34:35] offset:1024
	global_load_dwordx4 v[76:79], v200, s[34:35] offset:2048
	global_load_dwordx4 v[80:83], v200, s[34:35] offset:3072
	global_load_dwordx4 v[84:87], v200, s[36:37] offset:0
	global_load_dwordx4 v[88:91], v200, s[36:37] offset:1024
	global_load_dwordx4 v[92:95], v200, s[36:37] offset:2048
	global_load_dwordx4 v[96:99], v200, s[36:37] offset:3072
	global_load_dwordx4 v[100:103], v200, s[38:39] offset:0
	global_load_dwordx4 v[104:107], v200, s[38:39] offset:1024
	global_load_dwordx4 v[108:111], v200, s[38:39] offset:2048
	global_load_dwordx4 v[112:115], v200, s[38:39] offset:3072
	global_load_dwordx4 v[116:119], v200, s[0:1] offset:0
	global_load_dwordx4 v[120:123], v200, s[0:1] offset:1024
	global_load_dwordx4 v[124:127], v200, s[0:1] offset:2048
	global_load_dwordx4 v[128:131], v200, s[0:1] offset:3072
	s_waitcnt vmcnt(16)
	s_branch .Lintra_a1_go

.Lintra_a1_go:
	v_mfma_f32_16x16x32_bf16 v[232:235], v[132:135], v[0:3], 0
	v_mfma_f32_16x16x32_bf16 v[236:239], v[168:171], v[0:3], 0
	v_mfma_f32_16x16x32_bf16 v[232:235], v[136:139], v[4:7], v[232:235]
	v_mfma_f32_16x16x32_bf16 v[236:239], v[172:175], v[4:7], v[236:239]
	v_mfma_f32_16x16x32_bf16 v[232:235], v[144:147], v[8:11], v[232:235]
	v_mfma_f32_16x16x32_bf16 v[236:239], v[176:179], v[8:11], v[236:239]
	v_mfma_f32_16x16x32_bf16 v[232:235], v[148:151], v[12:15], v[232:235]
	v_mfma_f32_16x16x32_bf16 v[236:239], v[180:183], v[12:15], v[236:239]
	v_mfma_f32_16x16x32_bf16 v[232:235], v[152:155], v[16:19], v[232:235]
	v_mfma_f32_16x16x32_bf16 v[236:239], v[184:187], v[16:19], v[236:239]
	v_mfma_f32_16x16x32_bf16 v[232:235], v[156:159], v[20:23], v[232:235]
	v_mfma_f32_16x16x32_bf16 v[236:239], v[188:191], v[20:23], v[236:239]
	v_mfma_f32_16x16x32_bf16 v[232:235], v[160:163], v[24:27], v[232:235]
	v_mfma_f32_16x16x32_bf16 v[236:239], v[192:195], v[24:27], v[236:239]
	v_mfma_f32_16x16x32_bf16 v[232:235], v[164:167], v[28:31], v[232:235]
	v_mfma_f32_16x16x32_bf16 v[236:239], v[196:199], v[28:31], v[236:239]
	s_nop 7
	s_nop 1
	v_cmp_le_i32_e32 vcc, 32, v201
	s_nop 1
	v_cndmask_b32_e32 v232, 0, v232, vcc
	v_cmp_le_i32_e32 vcc, 33, v201
	s_nop 1
	v_cndmask_b32_e32 v233, 0, v233, vcc
	v_cmp_le_i32_e32 vcc, 34, v201
	s_nop 1
	v_cndmask_b32_e32 v234, 0, v234, vcc
	v_cmp_le_i32_e32 vcc, 35, v201
	s_nop 1
	v_cndmask_b32_e32 v235, 0, v235, vcc
	v_cmp_le_i32_e32 vcc, 48, v201
	s_nop 1
	v_cndmask_b32_e32 v236, 0, v236, vcc
	v_cmp_le_i32_e32 vcc, 49, v201
	s_nop 1
	v_cndmask_b32_e32 v237, 0, v237, vcc
	v_cmp_le_i32_e32 vcc, 50, v201
	s_nop 1
	v_cndmask_b32_e32 v238, 0, v238, vcc
	v_cmp_le_i32_e32 vcc, 51, v201
	s_nop 1
	v_cndmask_b32_e32 v239, 0, v239, vcc
	v_cvt_pk_bf16_f32 v36, v232, v233
	v_cvt_pk_bf16_f32 v37, v234, v235
	v_cvt_pk_bf16_f32 v38, v236, v237
	v_cvt_pk_bf16_f32 v39, v238, v239
	s_cmp_ge_i32 s9, 3
	s_cbranch_scc0 .Lintra_b
.Lintra_a2:
	s_cmp_ge_i32 s9, 4
	s_cbranch_scc0 .Lintra_a2_last
	s_add_u32 s34, s14, 49152
	s_addc_u32 s35, s15, 0
	s_add_u32 s36, s34, 0x1000
	s_addc_u32 s37, s35, 0
	s_add_u32 s38, s34, 0x2000
	s_addc_u32 s39, s35, 0
	s_add_u32 s0, s34, 0x3000
	s_addc_u32 s1, s35, 0
	global_load_dwordx4 v[132:135], v200, s[34:35] offset:0
	global_load_dwordx4 v[136:139], v200, s[34:35] offset:1024
	global_load_dwordx4 v[144:147], v200, s[34:35] offset:2048
	global_load_dwordx4 v[148:151], v200, s[34:35] offset:3072
	global_load_dwordx4 v[152:155], v200, s[36:37] offset:0
	global_load_dwordx4 v[156:159], v200, s[36:37] offset:1024
	global_load_dwordx4 v[160:163], v200, s[36:37] offset:2048
	global_load_dwordx4 v[164:167], v200, s[36:37] offset:3072
	global_load_dwordx4 v[168:171], v200, s[38:39] offset:0
	global_load_dwordx4 v[172:175], v200, s[38:39] offset:1024
	global_load_dwordx4 v[176:179], v200, s[38:39] offset:2048
	global_load_dwordx4 v[180:183], v200, s[38:39] offset:3072
	global_load_dwordx4 v[184:187], v200, s[0:1] offset:0
	global_load_dwordx4 v[188:191], v200, s[0:1] offset:1024
	global_load_dwordx4 v[192:195], v200, s[0:1] offset:2048
	global_load_dwordx4 v[196:199], v200, s[0:1] offset:3072
	s_waitcnt vmcnt(16)
	s_branch .Lintra_a2_go

.Lintra_a2_go:
	v_mfma_f32_16x16x32_bf16 v[232:235], v[68:71], v[0:3], 0
	v_mfma_f32_16x16x32_bf16 v[236:239], v[100:103], v[0:3], 0
	v_mfma_f32_16x16x32_bf16 v[232:235], v[72:75], v[4:7], v[232:235]
	v_mfma_f32_16x16x32_bf16 v[236:239], v[104:107], v[4:7], v[236:239]
	v_mfma_f32_16x16x32_bf16 v[232:235], v[76:79], v[8:11], v[232:235]
	v_mfma_f32_16x16x32_bf16 v[236:239], v[108:111], v[8:11], v[236:239]
	v_mfma_f32_16x16x32_bf16 v[232:235], v[80:83], v[12:15], v[232:235]
	v_mfma_f32_16x16x32_bf16 v[236:239], v[112:115], v[12:15], v[236:239]
	v_mfma_f32_16x16x32_bf16 v[232:235], v[84:87], v[16:19], v[232:235]
	v_mfma_f32_16x16x32_bf16 v[236:239], v[116:119], v[16:19], v[236:239]
	v_mfma_f32_16x16x32_bf16 v[232:235], v[88:91], v[20:23], v[232:235]
	v_mfma_f32_16x16x32_bf16 v[236:239], v[120:123], v[20:23], v[236:239]
	v_mfma_f32_16x16x32_bf16 v[232:235], v[92:95], v[24:27], v[232:235]
	v_mfma_f32_16x16x32_bf16 v[236:239], v[124:127], v[24:27], v[236:239]
	v_mfma_f32_16x16x32_bf16 v[232:235], v[96:99], v[28:31], v[232:235]
	v_mfma_f32_16x16x32_bf16 v[236:239], v[128:131], v[28:31], v[236:239]
	s_nop 7
	s_nop 1
	v_cmp_le_i32_e32 vcc, 64, v201
	s_nop 1
	v_cndmask_b32_e32 v232, 0, v232, vcc
	v_cmp_le_i32_e32 vcc, 65, v201
	s_nop 1
	v_cndmask_b32_e32 v233, 0, v233, vcc
	v_cmp_le_i32_e32 vcc, 66, v201
	s_nop 1
	v_cndmask_b32_e32 v234, 0, v234, vcc
	v_cmp_le_i32_e32 vcc, 67, v201
	s_nop 1
	v_cndmask_b32_e32 v235, 0, v235, vcc
	v_cmp_le_i32_e32 vcc, 80, v201
	s_nop 1
	v_cndmask_b32_e32 v236, 0, v236, vcc
	v_cmp_le_i32_e32 vcc, 81, v201
	s_nop 1
	v_cndmask_b32_e32 v237, 0, v237, vcc
	v_cmp_le_i32_e32 vcc, 82, v201
	s_nop 1
	v_cndmask_b32_e32 v238, 0, v238, vcc
	v_cmp_le_i32_e32 vcc, 83, v201
	s_nop 1
	v_cndmask_b32_e32 v239, 0, v239, vcc
	v_cvt_pk_bf16_f32 v40, v232, v233
	v_cvt_pk_bf16_f32 v41, v234, v235
	v_cvt_pk_bf16_f32 v42, v236, v237
	v_cvt_pk_bf16_f32 v43, v238, v239
	s_cmp_ge_i32 s9, 4
	s_cbranch_scc0 .Lintra_b
.Lintra_a3:
	s_cmp_ge_i32 s9, 5
	s_cbranch_scc0 .Lintra_a3_last
	s_add_u32 s34, s14, 65536
	s_addc_u32 s35, s15, 0
	s_add_u32 s36, s34, 0x1000
	s_addc_u32 s37, s35, 0
	s_add_u32 s38, s34, 0x2000
	s_addc_u32 s39, s35, 0
	s_add_u32 s0, s34, 0x3000
	s_addc_u32 s1, s35, 0
	global_load_dwordx4 v[68:71], v200, s[34:35] offset:0
	global_load_dwordx4 v[72:75], v200, s[34:35] offset:1024
	global_load_dwordx4 v[76:79], v200, s[34:35] offset:2048
	global_load_dwordx4 v[80:83], v200, s[34:35] offset:3072
	global_load_dwordx4 v[84:87], v200, s[36:37] offset:0
	global_load_dwordx4 v[88:91], v200, s[36:37] offset:1024
	global_load_dwordx4 v[92:95], v200, s[36:37] offset:2048
	global_load_dwordx4 v[96:99], v200, s[36:37] offset:3072
	global_load_dwordx4 v[100:103], v200, s[38:39] offset:0
	global_load_dwordx4 v[104:107], v200, s[38:39] offset:1024
	global_load_dwordx4 v[108:111], v200, s[38:39] offset:2048
	global_load_dwordx4 v[112:115], v200, s[38:39] offset:3072
	global_load_dwordx4 v[116:119], v200, s[0:1] offset:0
	global_load_dwordx4 v[120:123], v200, s[0:1] offset:1024
	global_load_dwordx4 v[124:127], v200, s[0:1] offset:2048
	global_load_dwordx4 v[128:131], v200, s[0:1] offset:3072
	s_waitcnt vmcnt(16)
	s_branch .Lintra_a3_go

.Lintra_a3_go:
	v_mfma_f32_16x16x32_bf16 v[232:235], v[132:135], v[0:3], 0
	v_mfma_f32_16x16x32_bf16 v[236:239], v[168:171], v[0:3], 0
	v_mfma_f32_16x16x32_bf16 v[232:235], v[136:139], v[4:7], v[232:235]
	v_mfma_f32_16x16x32_bf16 v[236:239], v[172:175], v[4:7], v[236:239]
	v_mfma_f32_16x16x32_bf16 v[232:235], v[144:147], v[8:11], v[232:235]
	v_mfma_f32_16x16x32_bf16 v[236:239], v[176:179], v[8:11], v[236:239]
	v_mfma_f32_16x16x32_bf16 v[232:235], v[148:151], v[12:15], v[232:235]
	v_mfma_f32_16x16x32_bf16 v[236:239], v[180:183], v[12:15], v[236:239]
	v_mfma_f32_16x16x32_bf16 v[232:235], v[152:155], v[16:19], v[232:235]
	v_mfma_f32_16x16x32_bf16 v[236:239], v[184:187], v[16:19], v[236:239]
	v_mfma_f32_16x16x32_bf16 v[232:235], v[156:159], v[20:23], v[232:235]
	v_mfma_f32_16x16x32_bf16 v[236:239], v[188:191], v[20:23], v[236:239]
	v_mfma_f32_16x16x32_bf16 v[232:235], v[160:163], v[24:27], v[232:235]
	v_mfma_f32_16x16x32_bf16 v[236:239], v[192:195], v[24:27], v[236:239]
	v_mfma_f32_16x16x32_bf16 v[232:235], v[164:167], v[28:31], v[232:235]
	v_mfma_f32_16x16x32_bf16 v[236:239], v[196:199], v[28:31], v[236:239]
	s_nop 7
	s_nop 1
	v_cmp_le_i32_e32 vcc, 96, v201
	s_nop 1
	v_cndmask_b32_e32 v232, 0, v232, vcc
	v_cmp_le_i32_e32 vcc, 97, v201
	s_nop 1
	v_cndmask_b32_e32 v233, 0, v233, vcc
	v_cmp_le_i32_e32 vcc, 98, v201
	s_nop 1
	v_cndmask_b32_e32 v234, 0, v234, vcc
	v_cmp_le_i32_e32 vcc, 99, v201
	s_nop 1
	v_cndmask_b32_e32 v235, 0, v235, vcc
	v_cmp_le_i32_e32 vcc, 112, v201
	s_nop 1
	v_cndmask_b32_e32 v236, 0, v236, vcc
	v_cmp_le_i32_e32 vcc, 113, v201
	s_nop 1
	v_cndmask_b32_e32 v237, 0, v237, vcc
	v_cmp_le_i32_e32 vcc, 114, v201
	s_nop 1
	v_cndmask_b32_e32 v238, 0, v238, vcc
	v_cmp_le_i32_e32 vcc, 115, v201
	s_nop 1
	v_cndmask_b32_e32 v239, 0, v239, vcc
	v_cvt_pk_bf16_f32 v44, v232, v233
	v_cvt_pk_bf16_f32 v45, v234, v235
	v_cvt_pk_bf16_f32 v46, v236, v237
	v_cvt_pk_bf16_f32 v47, v238, v239
	s_cmp_ge_i32 s9, 5
	s_cbranch_scc0 .Lintra_b
.Lintra_a4:
	s_cmp_ge_i32 s9, 6
	s_cbranch_scc0 .Lintra_a4_last
	s_add_u32 s34, s14, 81920
	s_addc_u32 s35, s15, 0
	s_add_u32 s36, s34, 0x1000
	s_addc_u32 s37, s35, 0
	s_add_u32 s38, s34, 0x2000
	s_addc_u32 s39, s35, 0
	s_add_u32 s0, s34, 0x3000
	s_addc_u32 s1, s35, 0
	global_load_dwordx4 v[132:135], v200, s[34:35] offset:0
	global_load_dwordx4 v[136:139], v200, s[34:35] offset:1024
	global_load_dwordx4 v[144:147], v200, s[34:35] offset:2048
	global_load_dwordx4 v[148:151], v200, s[34:35] offset:3072
	global_load_dwordx4 v[152:155], v200, s[36:37] offset:0
	global_load_dwordx4 v[156:159], v200, s[36:37] offset:1024
	global_load_dwordx4 v[160:163], v200, s[36:37] offset:2048
	global_load_dwordx4 v[164:167], v200, s[36:37] offset:3072
	global_load_dwordx4 v[168:171], v200, s[38:39] offset:0
	global_load_dwordx4 v[172:175], v200, s[38:39] offset:1024
	global_load_dwordx4 v[176:179], v200, s[38:39] offset:2048
	global_load_dwordx4 v[180:183], v200, s[38:39] offset:3072
	global_load_dwordx4 v[184:187], v200, s[0:1] offset:0
	global_load_dwordx4 v[188:191], v200, s[0:1] offset:1024
	global_load_dwordx4 v[192:195], v200, s[0:1] offset:2048
	global_load_dwordx4 v[196:199], v200, s[0:1] offset:3072
	s_waitcnt vmcnt(16)
	s_branch .Lintra_a4_go

.Lintra_a4_go:
	v_mfma_f32_16x16x32_bf16 v[232:235], v[68:71], v[0:3], 0
	v_mfma_f32_16x16x32_bf16 v[236:239], v[100:103], v[0:3], 0
	v_mfma_f32_16x16x32_bf16 v[232:235], v[72:75], v[4:7], v[232:235]
	v_mfma_f32_16x16x32_bf16 v[236:239], v[104:107], v[4:7], v[236:239]
	v_mfma_f32_16x16x32_bf16 v[232:235], v[76:79], v[8:11], v[232:235]
	v_mfma_f32_16x16x32_bf16 v[236:239], v[108:111], v[8:11], v[236:239]
	v_mfma_f32_16x16x32_bf16 v[232:235], v[80:83], v[12:15], v[232:235]
	v_mfma_f32_16x16x32_bf16 v[236:239], v[112:115], v[12:15], v[236:239]
	v_mfma_f32_16x16x32_bf16 v[232:235], v[84:87], v[16:19], v[232:235]
	v_mfma_f32_16x16x32_bf16 v[236:239], v[116:119], v[16:19], v[236:239]
	v_mfma_f32_16x16x32_bf16 v[232:235], v[88:91], v[20:23], v[232:235]
	v_mfma_f32_16x16x32_bf16 v[236:239], v[120:123], v[20:23], v[236:239]
	v_mfma_f32_16x16x32_bf16 v[232:235], v[92:95], v[24:27], v[232:235]
	v_mfma_f32_16x16x32_bf16 v[236:239], v[124:127], v[24:27], v[236:239]
	v_mfma_f32_16x16x32_bf16 v[232:235], v[96:99], v[28:31], v[232:235]
	v_mfma_f32_16x16x32_bf16 v[236:239], v[128:131], v[28:31], v[236:239]
	s_nop 7
	s_nop 1
	v_cmp_le_i32_e32 vcc, 128, v201
	s_nop 1
	v_cndmask_b32_e32 v232, 0, v232, vcc
	v_cmp_le_i32_e32 vcc, 129, v201
	s_nop 1
	v_cndmask_b32_e32 v233, 0, v233, vcc
	v_cmp_le_i32_e32 vcc, 130, v201
	s_nop 1
	v_cndmask_b32_e32 v234, 0, v234, vcc
	v_cmp_le_i32_e32 vcc, 131, v201
	s_nop 1
	v_cndmask_b32_e32 v235, 0, v235, vcc
	v_cmp_le_i32_e32 vcc, 144, v201
	s_nop 1
	v_cndmask_b32_e32 v236, 0, v236, vcc
	v_cmp_le_i32_e32 vcc, 145, v201
	s_nop 1
	v_cndmask_b32_e32 v237, 0, v237, vcc
	v_cmp_le_i32_e32 vcc, 146, v201
	s_nop 1
	v_cndmask_b32_e32 v238, 0, v238, vcc
	v_cmp_le_i32_e32 vcc, 147, v201
	s_nop 1
	v_cndmask_b32_e32 v239, 0, v239, vcc
	v_cvt_pk_bf16_f32 v48, v232, v233
	v_cvt_pk_bf16_f32 v49, v234, v235
	v_cvt_pk_bf16_f32 v50, v236, v237
	v_cvt_pk_bf16_f32 v51, v238, v239
	s_cmp_ge_i32 s9, 6
	s_cbranch_scc0 .Lintra_b
.Lintra_a5:
	s_cmp_ge_i32 s9, 7
	s_cbranch_scc0 .Lintra_a5_last
	s_add_u32 s34, s14, 98304
	s_addc_u32 s35, s15, 0
	s_add_u32 s36, s34, 0x1000
	s_addc_u32 s37, s35, 0
	s_add_u32 s38, s34, 0x2000
	s_addc_u32 s39, s35, 0
	s_add_u32 s0, s34, 0x3000
	s_addc_u32 s1, s35, 0
	global_load_dwordx4 v[68:71], v200, s[34:35] offset:0
	global_load_dwordx4 v[72:75], v200, s[34:35] offset:1024
	global_load_dwordx4 v[76:79], v200, s[34:35] offset:2048
	global_load_dwordx4 v[80:83], v200, s[34:35] offset:3072
	global_load_dwordx4 v[84:87], v200, s[36:37] offset:0
	global_load_dwordx4 v[88:91], v200, s[36:37] offset:1024
	global_load_dwordx4 v[92:95], v200, s[36:37] offset:2048
	global_load_dwordx4 v[96:99], v200, s[36:37] offset:3072
	global_load_dwordx4 v[100:103], v200, s[38:39] offset:0
	global_load_dwordx4 v[104:107], v200, s[38:39] offset:1024
	global_load_dwordx4 v[108:111], v200, s[38:39] offset:2048
	global_load_dwordx4 v[112:115], v200, s[38:39] offset:3072
	global_load_dwordx4 v[116:119], v200, s[0:1] offset:0
	global_load_dwordx4 v[120:123], v200, s[0:1] offset:1024
	global_load_dwordx4 v[124:127], v200, s[0:1] offset:2048
	global_load_dwordx4 v[128:131], v200, s[0:1] offset:3072
	s_waitcnt vmcnt(16)
	s_branch .Lintra_a5_go

.Lintra_a5_go:
	v_mfma_f32_16x16x32_bf16 v[232:235], v[132:135], v[0:3], 0
	v_mfma_f32_16x16x32_bf16 v[236:239], v[168:171], v[0:3], 0
	v_mfma_f32_16x16x32_bf16 v[232:235], v[136:139], v[4:7], v[232:235]
	v_mfma_f32_16x16x32_bf16 v[236:239], v[172:175], v[4:7], v[236:239]
	v_mfma_f32_16x16x32_bf16 v[232:235], v[144:147], v[8:11], v[232:235]
	v_mfma_f32_16x16x32_bf16 v[236:239], v[176:179], v[8:11], v[236:239]
	v_mfma_f32_16x16x32_bf16 v[232:235], v[148:151], v[12:15], v[232:235]
	v_mfma_f32_16x16x32_bf16 v[236:239], v[180:183], v[12:15], v[236:239]
	v_mfma_f32_16x16x32_bf16 v[232:235], v[152:155], v[16:19], v[232:235]
	v_mfma_f32_16x16x32_bf16 v[236:239], v[184:187], v[16:19], v[236:239]
	v_mfma_f32_16x16x32_bf16 v[232:235], v[156:159], v[20:23], v[232:235]
	v_mfma_f32_16x16x32_bf16 v[236:239], v[188:191], v[20:23], v[236:239]
	v_mfma_f32_16x16x32_bf16 v[232:235], v[160:163], v[24:27], v[232:235]
	v_mfma_f32_16x16x32_bf16 v[236:239], v[192:195], v[24:27], v[236:239]
	v_mfma_f32_16x16x32_bf16 v[232:235], v[164:167], v[28:31], v[232:235]
	v_mfma_f32_16x16x32_bf16 v[236:239], v[196:199], v[28:31], v[236:239]
	s_nop 7
	s_nop 1
	v_cmp_le_i32_e32 vcc, 160, v201
	s_nop 1
	v_cndmask_b32_e32 v232, 0, v232, vcc
	v_cmp_le_i32_e32 vcc, 161, v201
	s_nop 1
	v_cndmask_b32_e32 v233, 0, v233, vcc
	v_cmp_le_i32_e32 vcc, 162, v201
	s_nop 1
	v_cndmask_b32_e32 v234, 0, v234, vcc
	v_cmp_le_i32_e32 vcc, 163, v201
	s_nop 1
	v_cndmask_b32_e32 v235, 0, v235, vcc
	v_cmp_le_i32_e32 vcc, 176, v201
	s_nop 1
	v_cndmask_b32_e32 v236, 0, v236, vcc
	v_cmp_le_i32_e32 vcc, 177, v201
	s_nop 1
	v_cndmask_b32_e32 v237, 0, v237, vcc
	v_cmp_le_i32_e32 vcc, 178, v201
	s_nop 1
	v_cndmask_b32_e32 v238, 0, v238, vcc
	v_cmp_le_i32_e32 vcc, 179, v201
	s_nop 1
	v_cndmask_b32_e32 v239, 0, v239, vcc
	v_cvt_pk_bf16_f32 v52, v232, v233
	v_cvt_pk_bf16_f32 v53, v234, v235
	v_cvt_pk_bf16_f32 v54, v236, v237
	v_cvt_pk_bf16_f32 v55, v238, v239
	s_cmp_ge_i32 s9, 7
	s_cbranch_scc0 .Lintra_b
.Lintra_a6:
	s_cmp_ge_i32 s9, 8
	s_cbranch_scc0 .Lintra_a6_last
	s_add_u32 s34, s14, 114688
	s_addc_u32 s35, s15, 0
	s_add_u32 s36, s34, 0x1000
	s_addc_u32 s37, s35, 0
	s_add_u32 s38, s34, 0x2000
	s_addc_u32 s39, s35, 0
	s_add_u32 s0, s34, 0x3000
	s_addc_u32 s1, s35, 0
	global_load_dwordx4 v[132:135], v200, s[34:35] offset:0
	global_load_dwordx4 v[136:139], v200, s[34:35] offset:1024
	global_load_dwordx4 v[144:147], v200, s[34:35] offset:2048
	global_load_dwordx4 v[148:151], v200, s[34:35] offset:3072
	global_load_dwordx4 v[152:155], v200, s[36:37] offset:0
	global_load_dwordx4 v[156:159], v200, s[36:37] offset:1024
	global_load_dwordx4 v[160:163], v200, s[36:37] offset:2048
	global_load_dwordx4 v[164:167], v200, s[36:37] offset:3072
	global_load_dwordx4 v[168:171], v200, s[38:39] offset:0
	global_load_dwordx4 v[172:175], v200, s[38:39] offset:1024
	global_load_dwordx4 v[176:179], v200, s[38:39] offset:2048
	global_load_dwordx4 v[180:183], v200, s[38:39] offset:3072
	global_load_dwordx4 v[184:187], v200, s[0:1] offset:0
	global_load_dwordx4 v[188:191], v200, s[0:1] offset:1024
	global_load_dwordx4 v[192:195], v200, s[0:1] offset:2048
	global_load_dwordx4 v[196:199], v200, s[0:1] offset:3072
	s_waitcnt vmcnt(16)
	s_branch .Lintra_a6_go

.Lintra_a6_go:
	v_mfma_f32_16x16x32_bf16 v[232:235], v[68:71], v[0:3], 0
	v_mfma_f32_16x16x32_bf16 v[236:239], v[100:103], v[0:3], 0
	v_mfma_f32_16x16x32_bf16 v[232:235], v[72:75], v[4:7], v[232:235]
	v_mfma_f32_16x16x32_bf16 v[236:239], v[104:107], v[4:7], v[236:239]
	v_mfma_f32_16x16x32_bf16 v[232:235], v[76:79], v[8:11], v[232:235]
	v_mfma_f32_16x16x32_bf16 v[236:239], v[108:111], v[8:11], v[236:239]
	v_mfma_f32_16x16x32_bf16 v[232:235], v[80:83], v[12:15], v[232:235]
	v_mfma_f32_16x16x32_bf16 v[236:239], v[112:115], v[12:15], v[236:239]
	v_mfma_f32_16x16x32_bf16 v[232:235], v[84:87], v[16:19], v[232:235]
	v_mfma_f32_16x16x32_bf16 v[236:239], v[116:119], v[16:19], v[236:239]
	v_mfma_f32_16x16x32_bf16 v[232:235], v[88:91], v[20:23], v[232:235]
	v_mfma_f32_16x16x32_bf16 v[236:239], v[120:123], v[20:23], v[236:239]
	v_mfma_f32_16x16x32_bf16 v[232:235], v[92:95], v[24:27], v[232:235]
	v_mfma_f32_16x16x32_bf16 v[236:239], v[124:127], v[24:27], v[236:239]
	v_mfma_f32_16x16x32_bf16 v[232:235], v[96:99], v[28:31], v[232:235]
	v_mfma_f32_16x16x32_bf16 v[236:239], v[128:131], v[28:31], v[236:239]
	s_nop 7
	s_nop 1
	v_cmp_le_i32_e32 vcc, 192, v201
	s_nop 1
	v_cndmask_b32_e32 v232, 0, v232, vcc
	v_cmp_le_i32_e32 vcc, 193, v201
	s_nop 1
	v_cndmask_b32_e32 v233, 0, v233, vcc
	v_cmp_le_i32_e32 vcc, 194, v201
	s_nop 1
	v_cndmask_b32_e32 v234, 0, v234, vcc
	v_cmp_le_i32_e32 vcc, 195, v201
	s_nop 1
	v_cndmask_b32_e32 v235, 0, v235, vcc
	v_cmp_le_i32_e32 vcc, 208, v201
	s_nop 1
	v_cndmask_b32_e32 v236, 0, v236, vcc
	v_cmp_le_i32_e32 vcc, 209, v201
	s_nop 1
	v_cndmask_b32_e32 v237, 0, v237, vcc
	v_cmp_le_i32_e32 vcc, 210, v201
	s_nop 1
	v_cndmask_b32_e32 v238, 0, v238, vcc
	v_cmp_le_i32_e32 vcc, 211, v201
	s_nop 1
	v_cndmask_b32_e32 v239, 0, v239, vcc
	v_cvt_pk_bf16_f32 v56, v232, v233
	v_cvt_pk_bf16_f32 v57, v234, v235
	v_cvt_pk_bf16_f32 v58, v236, v237
	v_cvt_pk_bf16_f32 v59, v238, v239
	s_cmp_ge_i32 s9, 8
	s_cbranch_scc0 .Lintra_b

.Lintra_a7_go:
	v_mfma_f32_16x16x32_bf16 v[232:235], v[132:135], v[0:3], 0
	v_mfma_f32_16x16x32_bf16 v[236:239], v[168:171], v[0:3], 0
	v_mfma_f32_16x16x32_bf16 v[232:235], v[136:139], v[4:7], v[232:235]
	v_mfma_f32_16x16x32_bf16 v[236:239], v[172:175], v[4:7], v[236:239]
	v_mfma_f32_16x16x32_bf16 v[232:235], v[144:147], v[8:11], v[232:235]
	v_mfma_f32_16x16x32_bf16 v[236:239], v[176:179], v[8:11], v[236:239]
	v_mfma_f32_16x16x32_bf16 v[232:235], v[148:151], v[12:15], v[232:235]
	v_mfma_f32_16x16x32_bf16 v[236:239], v[180:183], v[12:15], v[236:239]
	v_mfma_f32_16x16x32_bf16 v[232:235], v[152:155], v[16:19], v[232:235]
	v_mfma_f32_16x16x32_bf16 v[236:239], v[184:187], v[16:19], v[236:239]
	v_mfma_f32_16x16x32_bf16 v[232:235], v[156:159], v[20:23], v[232:235]
	v_mfma_f32_16x16x32_bf16 v[236:239], v[188:191], v[20:23], v[236:239]
	v_mfma_f32_16x16x32_bf16 v[232:235], v[160:163], v[24:27], v[232:235]
	v_mfma_f32_16x16x32_bf16 v[236:239], v[192:195], v[24:27], v[236:239]
	v_mfma_f32_16x16x32_bf16 v[232:235], v[164:167], v[28:31], v[232:235]
	v_mfma_f32_16x16x32_bf16 v[236:239], v[196:199], v[28:31], v[236:239]
	s_nop 7
	s_nop 1
	v_cmp_le_i32_e32 vcc, 224, v201
	s_nop 1
	v_cndmask_b32_e32 v232, 0, v232, vcc
	v_cmp_le_i32_e32 vcc, 225, v201
	s_nop 1
	v_cndmask_b32_e32 v233, 0, v233, vcc
	v_cmp_le_i32_e32 vcc, 226, v201
	s_nop 1
	v_cndmask_b32_e32 v234, 0, v234, vcc
	v_cmp_le_i32_e32 vcc, 227, v201
	s_nop 1
	v_cndmask_b32_e32 v235, 0, v235, vcc
	v_cmp_le_i32_e32 vcc, 240, v201
	s_nop 1
	v_cndmask_b32_e32 v236, 0, v236, vcc
	v_cmp_le_i32_e32 vcc, 241, v201
	s_nop 1
	v_cndmask_b32_e32 v237, 0, v237, vcc
	v_cmp_le_i32_e32 vcc, 242, v201
	s_nop 1
	v_cndmask_b32_e32 v238, 0, v238, vcc
	v_cmp_le_i32_e32 vcc, 243, v201
	s_nop 1
	v_cndmask_b32_e32 v239, 0, v239, vcc
	v_cvt_pk_bf16_f32 v60, v232, v233
	v_cvt_pk_bf16_f32 v61, v234, v235
	v_cvt_pk_bf16_f32 v62, v236, v237
	v_cvt_pk_bf16_f32 v63, v238, v239
.Lintra_b:
	v_mov_b32_e32 v202, 0
	v_mov_b32_e32 v203, 0
	s_mov_b32 s10, 0
.Lintra_hf:
	s_waitcnt vmcnt(0) lgkmcnt(0)
	s_barrier
	s_lshl_b32 s0, s3, 15
	s_lshl_b32 s1, s10, 13
	s_add_i32 s0, s0, s1
	s_add_u32 s34, s16, s0
	s_addc_u32 s35, s17, 0
	s_add_i32 s1, s11, 0x10000
	s_add_i32 m0, s1, 0
	s_nop 0
	global_load_lds_dwordx4 v200, s[34:35]
	s_add_i32 m0, s1, 1024
	s_add_u32 s34, s34, 0x400
	s_addc_u32 s35, s35, 0
	global_load_lds_dwordx4 v200, s[34:35]
	s_add_i32 m0, s1, 2048
	s_add_u32 s34, s34, 0x400
	s_addc_u32 s35, s35, 0
	global_load_lds_dwordx4 v200, s[34:35]
	s_add_i32 m0, s1, 3072
	s_add_u32 s34, s34, 0x400
	s_addc_u32 s35, s35, 0
	global_load_lds_dwordx4 v200, s[34:35]
	s_add_i32 m0, s1, 4096
	s_add_u32 s34, s34, 0x400
	s_addc_u32 s35, s35, 0
	global_load_lds_dwordx4 v200, s[34:35]
	s_add_i32 m0, s1, 5120
	s_add_u32 s34, s34, 0x400
	s_addc_u32 s35, s35, 0
	global_load_lds_dwordx4 v200, s[34:35]
	s_add_i32 m0, s1, 6144
	s_add_u32 s34, s34, 0x400
	s_addc_u32 s35, s35, 0
	global_load_lds_dwordx4 v200, s[34:35]
	s_add_i32 m0, s1, 7168
	s_add_u32 s34, s34, 0x400
	s_addc_u32 s35, s35, 0
	global_load_lds_dwordx4 v200, s[34:35]
	ds_read_b128 v[100:103], v207 offset:0
	ds_read_b128 v[104:107], v207 offset:8192
	ds_read_b128 v[108:111], v207 offset:16384
	ds_read_b128 v[112:115], v207 offset:24576
	ds_read_b128 v[116:119], v207 offset:32768
	ds_read_b128 v[120:123], v207 offset:40960
	ds_read_b128 v[124:127], v207 offset:49152
	ds_read_b128 v[128:131], v207 offset:57344
	ds_read_b128 v[132:135], v207 offset:1024
	ds_read_b128 v[136:139], v207 offset:9216
	ds_read_b128 v[144:147], v207 offset:17408
	ds_read_b128 v[148:151], v207 offset:25600
	ds_read_b128 v[152:155], v207 offset:33792
	ds_read_b128 v[156:159], v207 offset:41984
	ds_read_b128 v[160:163], v207 offset:50176
	ds_read_b128 v[164:167], v207 offset:58368
	s_waitcnt lgkmcnt(8)
	v_mfma_f32_16x16x32_bf16 v[68:71], v[100:103], v[0:3], 0
	v_mfma_f32_16x16x32_bf16 v[72:75], v[104:107], v[0:3], 0
	v_mfma_f32_16x16x32_bf16 v[76:79], v[108:111], v[0:3], 0
	v_mfma_f32_16x16x32_bf16 v[80:83], v[112:115], v[0:3], 0
	v_mfma_f32_16x16x32_bf16 v[84:87], v[116:119], v[0:3], 0
	v_mfma_f32_16x16x32_bf16 v[88:91], v[120:123], v[0:3], 0
	v_mfma_f32_16x16x32_bf16 v[92:95], v[124:127], v[0:3], 0
	v_mfma_f32_16x16x32_bf16 v[96:99], v[128:131], v[0:3], 0
	ds_read_b128 v[100:103], v207 offset:2048
	ds_read_b128 v[104:107], v207 offset:10240
	ds_read_b128 v[108:111], v207 offset:18432
	ds_read_b128 v[112:115], v207 offset:26624
	ds_read_b128 v[116:119], v207 offset:34816
	ds_read_b128 v[120:123], v207 offset:43008
	ds_read_b128 v[124:127], v207 offset:51200
	ds_read_b128 v[128:131], v207 offset:59392
	s_waitcnt lgkmcnt(8)
	v_mfma_f32_16x16x32_bf16 v[68:71], v[132:135], v[4:7], v[68:71]
	v_mfma_f32_16x16x32_bf16 v[72:75], v[136:139], v[4:7], v[72:75]
	v_mfma_f32_16x16x32_bf16 v[76:79], v[144:147], v[4:7], v[76:79]
	v_mfma_f32_16x16x32_bf16 v[80:83], v[148:151], v[4:7], v[80:83]
	v_mfma_f32_16x16x32_bf16 v[84:87], v[152:155], v[4:7], v[84:87]
	v_mfma_f32_16x16x32_bf16 v[88:91], v[156:159], v[4:7], v[88:91]
	v_mfma_f32_16x16x32_bf16 v[92:95], v[160:163], v[4:7], v[92:95]
	v_mfma_f32_16x16x32_bf16 v[96:99], v[164:167], v[4:7], v[96:99]
	ds_read_b128 v[132:135], v207 offset:3072
	ds_read_b128 v[136:139], v207 offset:11264
	ds_read_b128 v[144:147], v207 offset:19456
	ds_read_b128 v[148:151], v207 offset:27648
	ds_read_b128 v[152:155], v207 offset:35840
	ds_read_b128 v[156:159], v207 offset:44032
	ds_read_b128 v[160:163], v207 offset:52224
	ds_read_b128 v[164:167], v207 offset:60416
	s_waitcnt lgkmcnt(8)
	v_mfma_f32_16x16x32_bf16 v[68:71], v[100:103], v[8:11], v[68:71]
	v_mfma_f32_16x16x32_bf16 v[72:75], v[104:107], v[8:11], v[72:75]
	v_mfma_f32_16x16x32_bf16 v[76:79], v[108:111], v[8:11], v[76:79]
	v_mfma_f32_16x16x32_bf16 v[80:83], v[112:115], v[8:11], v[80:83]
	v_mfma_f32_16x16x32_bf16 v[84:87], v[116:119], v[8:11], v[84:87]
	v_mfma_f32_16x16x32_bf16 v[88:91], v[120:123], v[8:11], v[88:91]
	v_mfma_f32_16x16x32_bf16 v[92:95], v[124:127], v[8:11], v[92:95]
	v_mfma_f32_16x16x32_bf16 v[96:99], v[128:131], v[8:11], v[96:99]
	ds_read_b128 v[100:103], v207 offset:4096
	ds_read_b128 v[104:107], v207 offset:12288
	ds_read_b128 v[108:111], v207 offset:20480
	ds_read_b128 v[112:115], v207 offset:28672
	ds_read_b128 v[116:119], v207 offset:36864
	ds_read_b128 v[120:123], v207 offset:45056
	ds_read_b128 v[124:127], v207 offset:53248
	ds_read_b128 v[128:131], v207 offset:61440
	s_waitcnt lgkmcnt(8)
	v_mfma_f32_16x16x32_bf16 v[68:71], v[132:135], v[12:15], v[68:71]
	v_mfma_f32_16x16x32_bf16 v[72:75], v[136:139], v[12:15], v[72:75]
	v_mfma_f32_16x16x32_bf16 v[76:79], v[144:147], v[12:15], v[76:79]
	v_mfma_f32_16x16x32_bf16 v[80:83], v[148:151], v[12:15], v[80:83]
	v_mfma_f32_16x16x32_bf16 v[84:87], v[152:155], v[12:15], v[84:87]
	v_mfma_f32_16x16x32_bf16 v[88:91], v[156:159], v[12:15], v[88:91]
	v_mfma_f32_16x16x32_bf16 v[92:95], v[160:163], v[12:15], v[92:95]
	v_mfma_f32_16x16x32_bf16 v[96:99], v[164:167], v[12:15], v[96:99]
	ds_read_b128 v[132:135], v207 offset:5120
	ds_read_b128 v[136:139], v207 offset:13312
	ds_read_b128 v[144:147], v207 offset:21504
	ds_read_b128 v[148:151], v207 offset:29696
	ds_read_b128 v[152:155], v207 offset:37888
	ds_read_b128 v[156:159], v207 offset:46080
	ds_read_b128 v[160:163], v207 offset:54272
	ds_read_b128 v[164:167], v207 offset:62464
	s_waitcnt lgkmcnt(8)
	v_mfma_f32_16x16x32_bf16 v[68:71], v[100:103], v[16:19], v[68:71]
	v_mfma_f32_16x16x32_bf16 v[72:75], v[104:107], v[16:19], v[72:75]
	v_mfma_f32_16x16x32_bf16 v[76:79], v[108:111], v[16:19], v[76:79]
	v_mfma_f32_16x16x32_bf16 v[80:83], v[112:115], v[16:19], v[80:83]
	v_mfma_f32_16x16x32_bf16 v[84:87], v[116:119], v[16:19], v[84:87]
	v_mfma_f32_16x16x32_bf16 v[88:91], v[120:123], v[16:19], v[88:91]
	v_mfma_f32_16x16x32_bf16 v[92:95], v[124:127], v[16:19], v[92:95]
	v_mfma_f32_16x16x32_bf16 v[96:99], v[128:131], v[16:19], v[96:99]
	ds_read_b128 v[100:103], v207 offset:6144
	ds_read_b128 v[104:107], v207 offset:14336
	ds_read_b128 v[108:111], v207 offset:22528
	ds_read_b128 v[112:115], v207 offset:30720
	ds_read_b128 v[116:119], v207 offset:38912
	ds_read_b128 v[120:123], v207 offset:47104
	ds_read_b128 v[124:127], v207 offset:55296
	ds_read_b128 v[128:131], v207 offset:63488
	s_waitcnt lgkmcnt(8)
	v_mfma_f32_16x16x32_bf16 v[68:71], v[132:135], v[20:23], v[68:71]
	v_mfma_f32_16x16x32_bf16 v[72:75], v[136:139], v[20:23], v[72:75]
	v_mfma_f32_16x16x32_bf16 v[76:79], v[144:147], v[20:23], v[76:79]
	v_mfma_f32_16x16x32_bf16 v[80:83], v[148:151], v[20:23], v[80:83]
	v_mfma_f32_16x16x32_bf16 v[84:87], v[152:155], v[20:23], v[84:87]
	v_mfma_f32_16x16x32_bf16 v[88:91], v[156:159], v[20:23], v[88:91]
	v_mfma_f32_16x16x32_bf16 v[92:95], v[160:163], v[20:23], v[92:95]
	v_mfma_f32_16x16x32_bf16 v[96:99], v[164:167], v[20:23], v[96:99]
	ds_read_b128 v[132:135], v207 offset:7168
	ds_read_b128 v[136:139], v207 offset:15360
	ds_read_b128 v[144:147], v207 offset:23552
	ds_read_b128 v[148:151], v207 offset:31744
	ds_read_b128 v[152:155], v207 offset:39936
	ds_read_b128 v[156:159], v207 offset:48128
	ds_read_b128 v[160:163], v207 offset:56320
	ds_read_b128 v[164:167], v207 offset:64512
	s_waitcnt lgkmcnt(8)
	v_mfma_f32_16x16x32_bf16 v[68:71], v[100:103], v[24:27], v[68:71]
	v_mfma_f32_16x16x32_bf16 v[72:75], v[104:107], v[24:27], v[72:75]
	v_mfma_f32_16x16x32_bf16 v[76:79], v[108:111], v[24:27], v[76:79]
	v_mfma_f32_16x16x32_bf16 v[80:83], v[112:115], v[24:27], v[80:83]
	v_mfma_f32_16x16x32_bf16 v[84:87], v[116:119], v[24:27], v[84:87]
	v_mfma_f32_16x16x32_bf16 v[88:91], v[120:123], v[24:27], v[88:91]
	v_mfma_f32_16x16x32_bf16 v[92:95], v[124:127], v[24:27], v[92:95]
	v_mfma_f32_16x16x32_bf16 v[96:99], v[128:131], v[24:27], v[96:99]
	s_waitcnt lgkmcnt(0)
	v_mfma_f32_16x16x32_bf16 v[68:71], v[132:135], v[28:31], v[68:71]
	v_mfma_f32_16x16x32_bf16 v[72:75], v[136:139], v[28:31], v[72:75]
	v_mfma_f32_16x16x32_bf16 v[76:79], v[144:147], v[28:31], v[76:79]
	v_mfma_f32_16x16x32_bf16 v[80:83], v[148:151], v[28:31], v[80:83]
	v_mfma_f32_16x16x32_bf16 v[84:87], v[152:155], v[28:31], v[84:87]
	v_mfma_f32_16x16x32_bf16 v[88:91], v[156:159], v[28:31], v[88:91]
	v_mfma_f32_16x16x32_bf16 v[92:95], v[160:163], v[28:31], v[92:95]
	v_mfma_f32_16x16x32_bf16 v[96:99], v[164:167], v[28:31], v[96:99]
	s_waitcnt vmcnt(0)
	s_barrier
	s_cmp_lt_i32 s10, 3
	s_cbranch_scc0 .Lintra_nodma
	s_add_i32 s0, s10, 1
	s_lshl_b32 s0, s0, 16
	s_mov_b32 s1, 0
	s_add_u32 s34, s18, s0
	s_addc_u32 s35, s19, 0
	s_add_u32 s34, s34, s11
	s_addc_u32 s35, s35, 0
	s_add_i32 s1, s1, s11
	s_add_i32 m0, s1, 0
	s_nop 0
	global_load_lds_dwordx4 v200, s[34:35]
	s_add_i32 m0, s1, 1024
	s_add_u32 s34, s34, 0x400
	s_addc_u32 s35, s35, 0
	global_load_lds_dwordx4 v200, s[34:35]
	s_add_i32 m0, s1, 2048
	s_add_u32 s34, s34, 0x400
	s_addc_u32 s35, s35, 0
	global_load_lds_dwordx4 v200, s[34:35]
	s_add_i32 m0, s1, 3072
	s_add_u32 s34, s34, 0x400
	s_addc_u32 s35, s35, 0
	global_load_lds_dwordx4 v200, s[34:35]
	s_add_i32 m0, s1, 4096
	s_add_u32 s34, s34, 0x400
	s_addc_u32 s35, s35, 0
	global_load_lds_dwordx4 v200, s[34:35]
	s_add_i32 m0, s1, 5120
	s_add_u32 s34, s34, 0x400
	s_addc_u32 s35, s35, 0
	global_load_lds_dwordx4 v200, s[34:35]
	s_add_i32 m0, s1, 6144
	s_add_u32 s34, s34, 0x400
	s_addc_u32 s35, s35, 0
	global_load_lds_dwordx4 v200, s[34:35]
	s_add_i32 m0, s1, 7168
	s_add_u32 s34, s34, 0x400
	s_addc_u32 s35, s35, 0
	global_load_lds_dwordx4 v200, s[34:35]
.Lintra_nodma:
	ds_read_b128 v[100:103], v230 offset:0
	ds_read_b128 v[104:107], v230 offset:1024
	ds_read_b128 v[108:111], v230 offset:2048
	ds_read_b128 v[112:115], v230 offset:3072
	ds_read_b128 v[116:119], v230 offset:4096
	ds_read_b128 v[120:123], v230 offset:5120
	ds_read_b128 v[124:127], v230 offset:6144
	ds_read_b128 v[128:131], v230 offset:7168
	s_cmp_ge_i32 s9, 2
	s_cbranch_scc0 .Lintra_v0_last
	ds_read_b128 v[132:135], v230 offset:8192
	ds_read_b128 v[136:139], v230 offset:9216
	ds_read_b128 v[144:147], v230 offset:10240
	ds_read_b128 v[148:151], v230 offset:11264
	ds_read_b128 v[152:155], v230 offset:12288
	ds_read_b128 v[156:159], v230 offset:13312
	ds_read_b128 v[160:163], v230 offset:14336
	ds_read_b128 v[164:167], v230 offset:15360
	s_waitcnt lgkmcnt(8)
	s_branch .Lintra_v0_go

.Lintra_v0_go:
	v_mfma_f32_16x16x32_bf16 v[68:71], v[100:103], v[32:35], v[68:71]
	v_mfma_f32_16x16x32_bf16 v[72:75], v[104:107], v[32:35], v[72:75]
	v_mfma_f32_16x16x32_bf16 v[76:79], v[108:111], v[32:35], v[76:79]
	v_mfma_f32_16x16x32_bf16 v[80:83], v[112:115], v[32:35], v[80:83]
	v_mfma_f32_16x16x32_bf16 v[84:87], v[116:119], v[32:35], v[84:87]
	v_mfma_f32_16x16x32_bf16 v[88:91], v[120:123], v[32:35], v[88:91]
	v_mfma_f32_16x16x32_bf16 v[92:95], v[124:127], v[32:35], v[92:95]
	v_mfma_f32_16x16x32_bf16 v[96:99], v[128:131], v[32:35], v[96:99]
	s_cmp_ge_i32 s9, 2
	s_cbranch_scc0 .Lintra_hfend
	s_cmp_ge_i32 s9, 3
	s_cbranch_scc0 .Lintra_v1_last
	ds_read_b128 v[100:103], v230 offset:16384
	ds_read_b128 v[104:107], v230 offset:17408
	ds_read_b128 v[108:111], v230 offset:18432
	ds_read_b128 v[112:115], v230 offset:19456
	ds_read_b128 v[116:119], v230 offset:20480
	ds_read_b128 v[120:123], v230 offset:21504
	ds_read_b128 v[124:127], v230 offset:22528
	ds_read_b128 v[128:131], v230 offset:23552
	s_waitcnt lgkmcnt(8)
	s_branch .Lintra_v1_go

.Lintra_v1_go:
	v_mfma_f32_16x16x32_bf16 v[68:71], v[132:135], v[36:39], v[68:71]
	v_mfma_f32_16x16x32_bf16 v[72:75], v[136:139], v[36:39], v[72:75]
	v_mfma_f32_16x16x32_bf16 v[76:79], v[144:147], v[36:39], v[76:79]
	v_mfma_f32_16x16x32_bf16 v[80:83], v[148:151], v[36:39], v[80:83]
	v_mfma_f32_16x16x32_bf16 v[84:87], v[152:155], v[36:39], v[84:87]
	v_mfma_f32_16x16x32_bf16 v[88:91], v[156:159], v[36:39], v[88:91]
	v_mfma_f32_16x16x32_bf16 v[92:95], v[160:163], v[36:39], v[92:95]
	v_mfma_f32_16x16x32_bf16 v[96:99], v[164:167], v[36:39], v[96:99]
	s_cmp_ge_i32 s9, 3
	s_cbranch_scc0 .Lintra_hfend
	s_cmp_ge_i32 s9, 4
	s_cbranch_scc0 .Lintra_v2_last
	ds_read_b128 v[132:135], v230 offset:24576
	ds_read_b128 v[136:139], v230 offset:25600
	ds_read_b128 v[144:147], v230 offset:26624
	ds_read_b128 v[148:151], v230 offset:27648
	ds_read_b128 v[152:155], v230 offset:28672
	ds_read_b128 v[156:159], v230 offset:29696
	ds_read_b128 v[160:163], v230 offset:30720
	ds_read_b128 v[164:167], v230 offset:31744
	s_waitcnt lgkmcnt(8)
	s_branch .Lintra_v2_go

.Lintra_v2_go:
	v_mfma_f32_16x16x32_bf16 v[68:71], v[100:103], v[40:43], v[68:71]
	v_mfma_f32_16x16x32_bf16 v[72:75], v[104:107], v[40:43], v[72:75]
	v_mfma_f32_16x16x32_bf16 v[76:79], v[108:111], v[40:43], v[76:79]
	v_mfma_f32_16x16x32_bf16 v[80:83], v[112:115], v[40:43], v[80:83]
	v_mfma_f32_16x16x32_bf16 v[84:87], v[116:119], v[40:43], v[84:87]
	v_mfma_f32_16x16x32_bf16 v[88:91], v[120:123], v[40:43], v[88:91]
	v_mfma_f32_16x16x32_bf16 v[92:95], v[124:127], v[40:43], v[92:95]
	v_mfma_f32_16x16x32_bf16 v[96:99], v[128:131], v[40:43], v[96:99]
	s_cmp_ge_i32 s9, 4
	s_cbranch_scc0 .Lintra_hfend
	s_cmp_ge_i32 s9, 5
	s_cbranch_scc0 .Lintra_v3_last
	ds_read_b128 v[100:103], v230 offset:32768
	ds_read_b128 v[104:107], v230 offset:33792
	ds_read_b128 v[108:111], v230 offset:34816
	ds_read_b128 v[112:115], v230 offset:35840
	ds_read_b128 v[116:119], v230 offset:36864
	ds_read_b128 v[120:123], v230 offset:37888
	ds_read_b128 v[124:127], v230 offset:38912
	ds_read_b128 v[128:131], v230 offset:39936
	s_waitcnt lgkmcnt(8)
	s_branch .Lintra_v3_go

.Lintra_v3_go:
	v_mfma_f32_16x16x32_bf16 v[68:71], v[132:135], v[44:47], v[68:71]
	v_mfma_f32_16x16x32_bf16 v[72:75], v[136:139], v[44:47], v[72:75]
	v_mfma_f32_16x16x32_bf16 v[76:79], v[144:147], v[44:47], v[76:79]
	v_mfma_f32_16x16x32_bf16 v[80:83], v[148:151], v[44:47], v[80:83]
	v_mfma_f32_16x16x32_bf16 v[84:87], v[152:155], v[44:47], v[84:87]
	v_mfma_f32_16x16x32_bf16 v[88:91], v[156:159], v[44:47], v[88:91]
	v_mfma_f32_16x16x32_bf16 v[92:95], v[160:163], v[44:47], v[92:95]
	v_mfma_f32_16x16x32_bf16 v[96:99], v[164:167], v[44:47], v[96:99]
	s_cmp_ge_i32 s9, 5
	s_cbranch_scc0 .Lintra_hfend
	s_cmp_ge_i32 s9, 6
	s_cbranch_scc0 .Lintra_v4_last
	ds_read_b128 v[132:135], v230 offset:40960
	ds_read_b128 v[136:139], v230 offset:41984
	ds_read_b128 v[144:147], v230 offset:43008
	ds_read_b128 v[148:151], v230 offset:44032
	ds_read_b128 v[152:155], v230 offset:45056
	ds_read_b128 v[156:159], v230 offset:46080
	ds_read_b128 v[160:163], v230 offset:47104
	ds_read_b128 v[164:167], v230 offset:48128
	s_waitcnt lgkmcnt(8)
	s_branch .Lintra_v4_go

.Lintra_v4_go:
	v_mfma_f32_16x16x32_bf16 v[68:71], v[100:103], v[48:51], v[68:71]
	v_mfma_f32_16x16x32_bf16 v[72:75], v[104:107], v[48:51], v[72:75]
	v_mfma_f32_16x16x32_bf16 v[76:79], v[108:111], v[48:51], v[76:79]
	v_mfma_f32_16x16x32_bf16 v[80:83], v[112:115], v[48:51], v[80:83]
	v_mfma_f32_16x16x32_bf16 v[84:87], v[116:119], v[48:51], v[84:87]
	v_mfma_f32_16x16x32_bf16 v[88:91], v[120:123], v[48:51], v[88:91]
	v_mfma_f32_16x16x32_bf16 v[92:95], v[124:127], v[48:51], v[92:95]
	v_mfma_f32_16x16x32_bf16 v[96:99], v[128:131], v[48:51], v[96:99]
	s_cmp_ge_i32 s9, 6
	s_cbranch_scc0 .Lintra_hfend
	s_cmp_ge_i32 s9, 7
	s_cbranch_scc0 .Lintra_v5_last
	ds_read_b128 v[100:103], v230 offset:49152
	ds_read_b128 v[104:107], v230 offset:50176
	ds_read_b128 v[108:111], v230 offset:51200
	ds_read_b128 v[112:115], v230 offset:52224
	ds_read_b128 v[116:119], v230 offset:53248
	ds_read_b128 v[120:123], v230 offset:54272
	ds_read_b128 v[124:127], v230 offset:55296
	ds_read_b128 v[128:131], v230 offset:56320
	s_waitcnt lgkmcnt(8)
	s_branch .Lintra_v5_go

.Lintra_v5_go:
	v_mfma_f32_16x16x32_bf16 v[68:71], v[132:135], v[52:55], v[68:71]
	v_mfma_f32_16x16x32_bf16 v[72:75], v[136:139], v[52:55], v[72:75]
	v_mfma_f32_16x16x32_bf16 v[76:79], v[144:147], v[52:55], v[76:79]
	v_mfma_f32_16x16x32_bf16 v[80:83], v[148:151], v[52:55], v[80:83]
	v_mfma_f32_16x16x32_bf16 v[84:87], v[152:155], v[52:55], v[84:87]
	v_mfma_f32_16x16x32_bf16 v[88:91], v[156:159], v[52:55], v[88:91]
	v_mfma_f32_16x16x32_bf16 v[92:95], v[160:163], v[52:55], v[92:95]
	v_mfma_f32_16x16x32_bf16 v[96:99], v[164:167], v[52:55], v[96:99]
	s_cmp_ge_i32 s9, 7
	s_cbranch_scc0 .Lintra_hfend
	s_cmp_ge_i32 s9, 8
	s_cbranch_scc0 .Lintra_v6_last
	ds_read_b128 v[132:135], v230 offset:57344
	ds_read_b128 v[136:139], v230 offset:58368
	ds_read_b128 v[144:147], v230 offset:59392
	ds_read_b128 v[148:151], v230 offset:60416
	ds_read_b128 v[152:155], v230 offset:61440
	ds_read_b128 v[156:159], v230 offset:62464
	ds_read_b128 v[160:163], v230 offset:63488
	ds_read_b128 v[164:167], v230 offset:64512
	s_waitcnt lgkmcnt(8)
	s_branch .Lintra_v6_go

.Lintra_v6_go:
	v_mfma_f32_16x16x32_bf16 v[68:71], v[100:103], v[56:59], v[68:71]
	v_mfma_f32_16x16x32_bf16 v[72:75], v[104:107], v[56:59], v[72:75]
	v_mfma_f32_16x16x32_bf16 v[76:79], v[108:111], v[56:59], v[76:79]
	v_mfma_f32_16x16x32_bf16 v[80:83], v[112:115], v[56:59], v[80:83]
	v_mfma_f32_16x16x32_bf16 v[84:87], v[116:119], v[56:59], v[84:87]
	v_mfma_f32_16x16x32_bf16 v[88:91], v[120:123], v[56:59], v[88:91]
	v_mfma_f32_16x16x32_bf16 v[92:95], v[124:127], v[56:59], v[92:95]
	v_mfma_f32_16x16x32_bf16 v[96:99], v[128:131], v[56:59], v[96:99]
	s_cmp_ge_i32 s9, 8
	s_cbranch_scc0 .Lintra_hfend
	s_waitcnt lgkmcnt(0)
.Lintra_v7_go:
	v_mfma_f32_16x16x32_bf16 v[68:71], v[132:135], v[60:63], v[68:71]
	v_mfma_f32_16x16x32_bf16 v[72:75], v[136:139], v[60:63], v[72:75]
	v_mfma_f32_16x16x32_bf16 v[76:79], v[144:147], v[60:63], v[76:79]
	v_mfma_f32_16x16x32_bf16 v[80:83], v[148:151], v[60:63], v[80:83]
	v_mfma_f32_16x16x32_bf16 v[84:87], v[152:155], v[60:63], v[84:87]
	v_mfma_f32_16x16x32_bf16 v[88:91], v[156:159], v[60:63], v[88:91]
	v_mfma_f32_16x16x32_bf16 v[92:95], v[160:163], v[60:63], v[92:95]
	v_mfma_f32_16x16x32_bf16 v[96:99], v[164:167], v[60:63], v[96:99]
.Lintra_hfend:
	s_mul_i32 s0, s8, 0x1800
	s_lshl_b32 s1, s10, 8
	s_add_i32 s0, s0, s1
	s_add_u32 s30, s20, s0
	s_addc_u32 s31, s21, 0
	s_nop 7
	s_nop 1
	v_add_f32_e32 v221, v68, v69
	v_add_f32_e32 v222, v70, v71
	v_add_f32_e32 v221, v221, v222
	v_add_f32_e32 v202, v202, v221
	v_mul_f32_e32 v221, v68, v68
	v_fmac_f32_e32 v221, v69, v69
	v_mul_f32_e32 v222, v70, v70
	v_fmac_f32_e32 v222, v71, v71
	v_add_f32_e32 v221, v221, v222
	v_add_f32_e32 v203, v203, v221
	v_cvt_pk_bf16_f32 v224, v68, v69
	v_cvt_pk_bf16_f32 v225, v70, v71
	global_store_dwordx2 v204, v[224:225], s[30:31] offset:0
	v_add_f32_e32 v221, v72, v73
	v_add_f32_e32 v222, v74, v75
	v_add_f32_e32 v221, v221, v222
	v_add_f32_e32 v202, v202, v221
	v_mul_f32_e32 v221, v72, v72
	v_fmac_f32_e32 v221, v73, v73
	v_mul_f32_e32 v222, v74, v74
	v_fmac_f32_e32 v222, v75, v75
	v_add_f32_e32 v221, v221, v222
	v_add_f32_e32 v203, v203, v221
	v_cvt_pk_bf16_f32 v224, v72, v73
	v_cvt_pk_bf16_f32 v225, v74, v75
	global_store_dwordx2 v204, v[224:225], s[30:31] offset:32
	v_add_f32_e32 v221, v76, v77
	v_add_f32_e32 v222, v78, v79
	v_add_f32_e32 v221, v221, v222
	v_add_f32_e32 v202, v202, v221
	v_mul_f32_e32 v221, v76, v76
	v_fmac_f32_e32 v221, v77, v77
	v_mul_f32_e32 v222, v78, v78
	v_fmac_f32_e32 v222, v79, v79
	v_add_f32_e32 v221, v221, v222
	v_add_f32_e32 v203, v203, v221
	v_cvt_pk_bf16_f32 v224, v76, v77
	v_cvt_pk_bf16_f32 v225, v78, v79
	global_store_dwordx2 v204, v[224:225], s[30:31] offset:64
	v_add_f32_e32 v221, v80, v81
	v_add_f32_e32 v222, v82, v83
	v_add_f32_e32 v221, v221, v222
	v_add_f32_e32 v202, v202, v221
	v_mul_f32_e32 v221, v80, v80
	v_fmac_f32_e32 v221, v81, v81
	v_mul_f32_e32 v222, v82, v82
	v_fmac_f32_e32 v222, v83, v83
	v_add_f32_e32 v221, v221, v222
	v_add_f32_e32 v203, v203, v221
	v_cvt_pk_bf16_f32 v224, v80, v81
	v_cvt_pk_bf16_f32 v225, v82, v83
	global_store_dwordx2 v204, v[224:225], s[30:31] offset:96
	v_add_f32_e32 v221, v84, v85
	v_add_f32_e32 v222, v86, v87
	v_add_f32_e32 v221, v221, v222
	v_add_f32_e32 v202, v202, v221
	v_mul_f32_e32 v221, v84, v84
	v_fmac_f32_e32 v221, v85, v85
	v_mul_f32_e32 v222, v86, v86
	v_fmac_f32_e32 v222, v87, v87
	v_add_f32_e32 v221, v221, v222
	v_add_f32_e32 v203, v203, v221
	v_cvt_pk_bf16_f32 v224, v84, v85
	v_cvt_pk_bf16_f32 v225, v86, v87
	global_store_dwordx2 v204, v[224:225], s[30:31] offset:128
	v_add_f32_e32 v221, v88, v89
	v_add_f32_e32 v222, v90, v91
	v_add_f32_e32 v221, v221, v222
	v_add_f32_e32 v202, v202, v221
	v_mul_f32_e32 v221, v88, v88
	v_fmac_f32_e32 v221, v89, v89
	v_mul_f32_e32 v222, v90, v90
	v_fmac_f32_e32 v222, v91, v91
	v_add_f32_e32 v221, v221, v222
	v_add_f32_e32 v203, v203, v221
	v_cvt_pk_bf16_f32 v224, v88, v89
	v_cvt_pk_bf16_f32 v225, v90, v91
	global_store_dwordx2 v204, v[224:225], s[30:31] offset:160
	v_add_f32_e32 v221, v92, v93
	v_add_f32_e32 v222, v94, v95
	v_add_f32_e32 v221, v221, v222
	v_add_f32_e32 v202, v202, v221
	v_mul_f32_e32 v221, v92, v92
	v_fmac_f32_e32 v221, v93, v93
	v_mul_f32_e32 v222, v94, v94
	v_fmac_f32_e32 v222, v95, v95
	v_add_f32_e32 v221, v221, v222
	v_add_f32_e32 v203, v203, v221
	v_cvt_pk_bf16_f32 v224, v92, v93
	v_cvt_pk_bf16_f32 v225, v94, v95
	global_store_dwordx2 v204, v[224:225], s[30:31] offset:192
	v_add_f32_e32 v221, v96, v97
	v_add_f32_e32 v222, v98, v99
	v_add_f32_e32 v221, v221, v222
	v_add_f32_e32 v202, v202, v221
	v_mul_f32_e32 v221, v96, v96
	v_fmac_f32_e32 v221, v97, v97
	v_mul_f32_e32 v222, v98, v98
	v_fmac_f32_e32 v222, v99, v99
	v_add_f32_e32 v221, v221, v222
	v_add_f32_e32 v203, v203, v221
	v_cvt_pk_bf16_f32 v224, v96, v97
	v_cvt_pk_bf16_f32 v225, v98, v99
	global_store_dwordx2 v204, v[224:225], s[30:31] offset:224
	s_add_i32 s10, s10, 1
	s_cmp_lt_i32 s10, 4
	s_cbranch_scc1 .Lintra_hf
	v_mov_b32_e32 v221, v208
	v_and_b32_e32 v221, 63, v221
	v_lshlrev_b32_e32 v221, 2, v221
	v_xor_b32_e32 v222, 64, v221
	v_xor_b32_e32 v221, 0x80, v221
	ds_bpermute_b32 v223, v222, v202
	ds_bpermute_b32 v224, v222, v203
	s_waitcnt lgkmcnt(0)
	v_add_f32_e32 v202, v202, v223
	v_add_f32_e32 v203, v203, v224
	ds_bpermute_b32 v223, v221, v202
	ds_bpermute_b32 v224, v221, v203
	s_waitcnt lgkmcnt(0)
	v_add_f32_e32 v202, v202, v223
	v_add_f32_e32 v203, v203, v224
	v_mul_f32_e32 v227, 0x3b000000, v202
	v_mul_f32_e32 v228, 0x3b000000, v203
	v_fma_f32 v228, -v227, v227, v228
	v_max_f32_e32 v228, 0, v228
	v_add_f32_e32 v228, 0x3727c5ac, v228
	v_rsq_f32_e32 v228, v228
	s_mul_i32 s0, s8, 0x1800
	s_add_u32 s30, s20, s0
	s_addc_u32 s31, s21, 0
	s_lshl_b32 s0, s8, 12
	s_add_u32 s34, s22, s0
	s_addc_u32 s35, s23, 0
	s_waitcnt vmcnt(0)
	global_load_dwordx2 v[24:25], v205, s[34:35] offset:0
	global_load_dwordx2 v[100:101], v204, s[30:31] offset:0
	global_load_dwordx4 v[68:71], v206, s[28:29] offset:0
	global_load_dwordx2 v[26:27], v205, s[34:35] offset:32
	global_load_dwordx2 v[102:103], v204, s[30:31] offset:32
	global_load_dwordx4 v[72:75], v206, s[28:29] offset:64
	global_load_dwordx2 v[28:29], v205, s[34:35] offset:64
	global_load_dwordx2 v[104:105], v204, s[30:31] offset:64
	global_load_dwordx4 v[76:79], v206, s[28:29] offset:128
	global_load_dwordx2 v[30:31], v205, s[34:35] offset:96
	global_load_dwordx2 v[106:107], v204, s[30:31] offset:96
	global_load_dwordx4 v[80:83], v206, s[28:29] offset:192
	global_load_dwordx2 v[32:33], v205, s[34:35] offset:128
	global_load_dwordx2 v[108:109], v204, s[30:31] offset:128
	global_load_dwordx4 v[84:87], v206, s[28:29] offset:256
	global_load_dwordx2 v[34:35], v205, s[34:35] offset:160
	global_load_dwordx2 v[110:111], v204, s[30:31] offset:160
	global_load_dwordx4 v[88:91], v206, s[28:29] offset:320
	global_load_dwordx2 v[36:37], v205, s[34:35] offset:192
	global_load_dwordx2 v[112:113], v204, s[30:31] offset:192
	global_load_dwordx4 v[92:95], v206, s[28:29] offset:384
	global_load_dwordx2 v[38:39], v205, s[34:35] offset:224
	global_load_dwordx2 v[114:115], v204, s[30:31] offset:224
	global_load_dwordx4 v[96:99], v206, s[28:29] offset:448
	s_waitcnt vmcnt(21)
	v_lshlrev_b32_e32 v12, 16, v24
	v_and_b32_e32 v13, 0xffff0000, v24
	v_lshlrev_b32_e32 v14, 16, v25
	v_and_b32_e32 v15, 0xffff0000, v25
	v_mul_f32_e32 v16, 0xbfb8aa3b, v12
	v_mul_f32_e32 v17, 0xbfb8aa3b, v13
	v_mul_f32_e32 v18, 0xbfb8aa3b, v14
	v_mul_f32_e32 v19, 0xbfb8aa3b, v15
	v_exp_f32_e32 v16, v16
	v_exp_f32_e32 v17, v17
	v_exp_f32_e32 v18, v18
	v_exp_f32_e32 v19, v19
	v_lshlrev_b32_e32 v20, 16, v100
	v_and_b32_e32 v21, 0xffff0000, v100
	v_lshlrev_b32_e32 v22, 16, v101
	v_and_b32_e32 v23, 0xffff0000, v101
	v_add_f32_e32 v16, 1.0, v16
	v_add_f32_e32 v17, 1.0, v17
	v_add_f32_e32 v18, 1.0, v18
	v_add_f32_e32 v19, 1.0, v19
	v_rcp_f32_e32 v16, v16
	v_rcp_f32_e32 v17, v17
	v_rcp_f32_e32 v18, v18
	v_rcp_f32_e32 v19, v19
	v_sub_f32_e32 v20, v20, v227
	v_sub_f32_e32 v21, v21, v227
	v_sub_f32_e32 v22, v22, v227
	v_sub_f32_e32 v23, v23, v227
	v_mul_f32_e32 v20, v20, v228
	v_mul_f32_e32 v21, v21, v228
	v_mul_f32_e32 v22, v22, v228
	v_mul_f32_e32 v23, v23, v228
	v_mul_f32_e32 v12, v12, v16
	v_mul_f32_e32 v13, v13, v17
	v_mul_f32_e32 v14, v14, v18
	v_mul_f32_e32 v15, v15, v19
	v_mul_f32_e32 v20, v20, v68
	v_mul_f32_e32 v21, v21, v69
	v_mul_f32_e32 v22, v22, v70
	v_mul_f32_e32 v23, v23, v71
	v_mul_f32_e32 v20, v20, v12
	v_mul_f32_e32 v21, v21, v13
	v_mul_f32_e32 v22, v22, v14
	v_mul_f32_e32 v23, v23, v15
	v_cvt_pk_bf16_f32 v20, v20, v21
	v_cvt_pk_bf16_f32 v21, v22, v23
	global_store_dwordx2 v204, v[20:21], s[30:31] offset:0
	s_waitcnt vmcnt(19)
	v_lshlrev_b32_e32 v12, 16, v26
	v_and_b32_e32 v13, 0xffff0000, v26
	v_lshlrev_b32_e32 v14, 16, v27
	v_and_b32_e32 v15, 0xffff0000, v27
	v_mul_f32_e32 v16, 0xbfb8aa3b, v12
	v_mul_f32_e32 v17, 0xbfb8aa3b, v13
	v_mul_f32_e32 v18, 0xbfb8aa3b, v14
	v_mul_f32_e32 v19, 0xbfb8aa3b, v15
	v_exp_f32_e32 v16, v16
	v_exp_f32_e32 v17, v17
	v_exp_f32_e32 v18, v18
	v_exp_f32_e32 v19, v19
	v_lshlrev_b32_e32 v20, 16, v102
	v_and_b32_e32 v21, 0xffff0000, v102
	v_lshlrev_b32_e32 v22, 16, v103
	v_and_b32_e32 v23, 0xffff0000, v103
	v_add_f32_e32 v16, 1.0, v16
	v_add_f32_e32 v17, 1.0, v17
	v_add_f32_e32 v18, 1.0, v18
	v_add_f32_e32 v19, 1.0, v19
	v_rcp_f32_e32 v16, v16
	v_rcp_f32_e32 v17, v17
	v_rcp_f32_e32 v18, v18
	v_rcp_f32_e32 v19, v19
	v_sub_f32_e32 v20, v20, v227
	v_sub_f32_e32 v21, v21, v227
	v_sub_f32_e32 v22, v22, v227
	v_sub_f32_e32 v23, v23, v227
	v_mul_f32_e32 v20, v20, v228
	v_mul_f32_e32 v21, v21, v228
	v_mul_f32_e32 v22, v22, v228
	v_mul_f32_e32 v23, v23, v228
	v_mul_f32_e32 v12, v12, v16
	v_mul_f32_e32 v13, v13, v17
	v_mul_f32_e32 v14, v14, v18
	v_mul_f32_e32 v15, v15, v19
	v_mul_f32_e32 v20, v20, v72
	v_mul_f32_e32 v21, v21, v73
	v_mul_f32_e32 v22, v22, v74
	v_mul_f32_e32 v23, v23, v75
	v_mul_f32_e32 v20, v20, v12
	v_mul_f32_e32 v21, v21, v13
	v_mul_f32_e32 v22, v22, v14
	v_mul_f32_e32 v23, v23, v15
	v_cvt_pk_bf16_f32 v20, v20, v21
	v_cvt_pk_bf16_f32 v21, v22, v23
	global_store_dwordx2 v204, v[20:21], s[30:31] offset:32
	s_waitcnt vmcnt(17)
	v_lshlrev_b32_e32 v12, 16, v28
	v_and_b32_e32 v13, 0xffff0000, v28
	v_lshlrev_b32_e32 v14, 16, v29
	v_and_b32_e32 v15, 0xffff0000, v29
	v_mul_f32_e32 v16, 0xbfb8aa3b, v12
	v_mul_f32_e32 v17, 0xbfb8aa3b, v13
	v_mul_f32_e32 v18, 0xbfb8aa3b, v14
	v_mul_f32_e32 v19, 0xbfb8aa3b, v15
	v_exp_f32_e32 v16, v16
	v_exp_f32_e32 v17, v17
	v_exp_f32_e32 v18, v18
	v_exp_f32_e32 v19, v19
	v_lshlrev_b32_e32 v20, 16, v104
	v_and_b32_e32 v21, 0xffff0000, v104
	v_lshlrev_b32_e32 v22, 16, v105
	v_and_b32_e32 v23, 0xffff0000, v105
	v_add_f32_e32 v16, 1.0, v16
	v_add_f32_e32 v17, 1.0, v17
	v_add_f32_e32 v18, 1.0, v18
	v_add_f32_e32 v19, 1.0, v19
	v_rcp_f32_e32 v16, v16
	v_rcp_f32_e32 v17, v17
	v_rcp_f32_e32 v18, v18
	v_rcp_f32_e32 v19, v19
	v_sub_f32_e32 v20, v20, v227
	v_sub_f32_e32 v21, v21, v227
	v_sub_f32_e32 v22, v22, v227
	v_sub_f32_e32 v23, v23, v227
	v_mul_f32_e32 v20, v20, v228
	v_mul_f32_e32 v21, v21, v228
	v_mul_f32_e32 v22, v22, v228
	v_mul_f32_e32 v23, v23, v228
	v_mul_f32_e32 v12, v12, v16
	v_mul_f32_e32 v13, v13, v17
	v_mul_f32_e32 v14, v14, v18
	v_mul_f32_e32 v15, v15, v19
	v_mul_f32_e32 v20, v20, v76
	v_mul_f32_e32 v21, v21, v77
	v_mul_f32_e32 v22, v22, v78
	v_mul_f32_e32 v23, v23, v79
	v_mul_f32_e32 v20, v20, v12
	v_mul_f32_e32 v21, v21, v13
	v_mul_f32_e32 v22, v22, v14
	v_mul_f32_e32 v23, v23, v15
	v_cvt_pk_bf16_f32 v20, v20, v21
	v_cvt_pk_bf16_f32 v21, v22, v23
	global_store_dwordx2 v204, v[20:21], s[30:31] offset:64
	s_waitcnt vmcnt(15)
	v_lshlrev_b32_e32 v12, 16, v30
	v_and_b32_e32 v13, 0xffff0000, v30
	v_lshlrev_b32_e32 v14, 16, v31
	v_and_b32_e32 v15, 0xffff0000, v31
	v_mul_f32_e32 v16, 0xbfb8aa3b, v12
	v_mul_f32_e32 v17, 0xbfb8aa3b, v13
	v_mul_f32_e32 v18, 0xbfb8aa3b, v14
	v_mul_f32_e32 v19, 0xbfb8aa3b, v15
	v_exp_f32_e32 v16, v16
	v_exp_f32_e32 v17, v17
	v_exp_f32_e32 v18, v18
	v_exp_f32_e32 v19, v19
	v_lshlrev_b32_e32 v20, 16, v106
	v_and_b32_e32 v21, 0xffff0000, v106
	v_lshlrev_b32_e32 v22, 16, v107
	v_and_b32_e32 v23, 0xffff0000, v107
	v_add_f32_e32 v16, 1.0, v16
	v_add_f32_e32 v17, 1.0, v17
	v_add_f32_e32 v18, 1.0, v18
	v_add_f32_e32 v19, 1.0, v19
	v_rcp_f32_e32 v16, v16
	v_rcp_f32_e32 v17, v17
	v_rcp_f32_e32 v18, v18
	v_rcp_f32_e32 v19, v19
	v_sub_f32_e32 v20, v20, v227
	v_sub_f32_e32 v21, v21, v227
	v_sub_f32_e32 v22, v22, v227
	v_sub_f32_e32 v23, v23, v227
	v_mul_f32_e32 v20, v20, v228
	v_mul_f32_e32 v21, v21, v228
	v_mul_f32_e32 v22, v22, v228
	v_mul_f32_e32 v23, v23, v228
	v_mul_f32_e32 v12, v12, v16
	v_mul_f32_e32 v13, v13, v17
	v_mul_f32_e32 v14, v14, v18
	v_mul_f32_e32 v15, v15, v19
	v_mul_f32_e32 v20, v20, v80
	v_mul_f32_e32 v21, v21, v81
	v_mul_f32_e32 v22, v22, v82
	v_mul_f32_e32 v23, v23, v83
	v_mul_f32_e32 v20, v20, v12
	v_mul_f32_e32 v21, v21, v13
	v_mul_f32_e32 v22, v22, v14
	v_mul_f32_e32 v23, v23, v15
	v_cvt_pk_bf16_f32 v20, v20, v21
	v_cvt_pk_bf16_f32 v21, v22, v23
	global_store_dwordx2 v204, v[20:21], s[30:31] offset:96
	s_waitcnt vmcnt(13)
	v_lshlrev_b32_e32 v12, 16, v32
	v_and_b32_e32 v13, 0xffff0000, v32
	v_lshlrev_b32_e32 v14, 16, v33
	v_and_b32_e32 v15, 0xffff0000, v33
	v_mul_f32_e32 v16, 0xbfb8aa3b, v12
	v_mul_f32_e32 v17, 0xbfb8aa3b, v13
	v_mul_f32_e32 v18, 0xbfb8aa3b, v14
	v_mul_f32_e32 v19, 0xbfb8aa3b, v15
	v_exp_f32_e32 v16, v16
	v_exp_f32_e32 v17, v17
	v_exp_f32_e32 v18, v18
	v_exp_f32_e32 v19, v19
	v_lshlrev_b32_e32 v20, 16, v108
	v_and_b32_e32 v21, 0xffff0000, v108
	v_lshlrev_b32_e32 v22, 16, v109
	v_and_b32_e32 v23, 0xffff0000, v109
	v_add_f32_e32 v16, 1.0, v16
	v_add_f32_e32 v17, 1.0, v17
	v_add_f32_e32 v18, 1.0, v18
	v_add_f32_e32 v19, 1.0, v19
	v_rcp_f32_e32 v16, v16
	v_rcp_f32_e32 v17, v17
	v_rcp_f32_e32 v18, v18
	v_rcp_f32_e32 v19, v19
	v_sub_f32_e32 v20, v20, v227
	v_sub_f32_e32 v21, v21, v227
	v_sub_f32_e32 v22, v22, v227
	v_sub_f32_e32 v23, v23, v227
	v_mul_f32_e32 v20, v20, v228
	v_mul_f32_e32 v21, v21, v228
	v_mul_f32_e32 v22, v22, v228
	v_mul_f32_e32 v23, v23, v228
	v_mul_f32_e32 v12, v12, v16
	v_mul_f32_e32 v13, v13, v17
	v_mul_f32_e32 v14, v14, v18
	v_mul_f32_e32 v15, v15, v19
	v_mul_f32_e32 v20, v20, v84
	v_mul_f32_e32 v21, v21, v85
	v_mul_f32_e32 v22, v22, v86
	v_mul_f32_e32 v23, v23, v87
	v_mul_f32_e32 v20, v20, v12
	v_mul_f32_e32 v21, v21, v13
	v_mul_f32_e32 v22, v22, v14
	v_mul_f32_e32 v23, v23, v15
	v_cvt_pk_bf16_f32 v20, v20, v21
	v_cvt_pk_bf16_f32 v21, v22, v23
	global_store_dwordx2 v204, v[20:21], s[30:31] offset:128
	s_waitcnt vmcnt(11)
	v_lshlrev_b32_e32 v12, 16, v34
	v_and_b32_e32 v13, 0xffff0000, v34
	v_lshlrev_b32_e32 v14, 16, v35
	v_and_b32_e32 v15, 0xffff0000, v35
	v_mul_f32_e32 v16, 0xbfb8aa3b, v12
	v_mul_f32_e32 v17, 0xbfb8aa3b, v13
	v_mul_f32_e32 v18, 0xbfb8aa3b, v14
	v_mul_f32_e32 v19, 0xbfb8aa3b, v15
	v_exp_f32_e32 v16, v16
	v_exp_f32_e32 v17, v17
	v_exp_f32_e32 v18, v18
	v_exp_f32_e32 v19, v19
	v_lshlrev_b32_e32 v20, 16, v110
	v_and_b32_e32 v21, 0xffff0000, v110
	v_lshlrev_b32_e32 v22, 16, v111
	v_and_b32_e32 v23, 0xffff0000, v111
	v_add_f32_e32 v16, 1.0, v16
	v_add_f32_e32 v17, 1.0, v17
	v_add_f32_e32 v18, 1.0, v18
	v_add_f32_e32 v19, 1.0, v19
	v_rcp_f32_e32 v16, v16
	v_rcp_f32_e32 v17, v17
	v_rcp_f32_e32 v18, v18
	v_rcp_f32_e32 v19, v19
	v_sub_f32_e32 v20, v20, v227
	v_sub_f32_e32 v21, v21, v227
	v_sub_f32_e32 v22, v22, v227
	v_sub_f32_e32 v23, v23, v227
	v_mul_f32_e32 v20, v20, v228
	v_mul_f32_e32 v21, v21, v228
	v_mul_f32_e32 v22, v22, v228
	v_mul_f32_e32 v23, v23, v228
	v_mul_f32_e32 v12, v12, v16
	v_mul_f32_e32 v13, v13, v17
	v_mul_f32_e32 v14, v14, v18
	v_mul_f32_e32 v15, v15, v19
	v_mul_f32_e32 v20, v20, v88
	v_mul_f32_e32 v21, v21, v89
	v_mul_f32_e32 v22, v22, v90
	v_mul_f32_e32 v23, v23, v91
	v_mul_f32_e32 v20, v20, v12
	v_mul_f32_e32 v21, v21, v13
	v_mul_f32_e32 v22, v22, v14
	v_mul_f32_e32 v23, v23, v15
	v_cvt_pk_bf16_f32 v20, v20, v21
	v_cvt_pk_bf16_f32 v21, v22, v23
	global_store_dwordx2 v204, v[20:21], s[30:31] offset:160
	s_waitcnt vmcnt(9)
	v_lshlrev_b32_e32 v12, 16, v36
	v_and_b32_e32 v13, 0xffff0000, v36
	v_lshlrev_b32_e32 v14, 16, v37
	v_and_b32_e32 v15, 0xffff0000, v37
	v_mul_f32_e32 v16, 0xbfb8aa3b, v12
	v_mul_f32_e32 v17, 0xbfb8aa3b, v13
	v_mul_f32_e32 v18, 0xbfb8aa3b, v14
	v_mul_f32_e32 v19, 0xbfb8aa3b, v15
	v_exp_f32_e32 v16, v16
	v_exp_f32_e32 v17, v17
	v_exp_f32_e32 v18, v18
	v_exp_f32_e32 v19, v19
	v_lshlrev_b32_e32 v20, 16, v112
	v_and_b32_e32 v21, 0xffff0000, v112
	v_lshlrev_b32_e32 v22, 16, v113
	v_and_b32_e32 v23, 0xffff0000, v113
	v_add_f32_e32 v16, 1.0, v16
	v_add_f32_e32 v17, 1.0, v17
	v_add_f32_e32 v18, 1.0, v18
	v_add_f32_e32 v19, 1.0, v19
	v_rcp_f32_e32 v16, v16
	v_rcp_f32_e32 v17, v17
	v_rcp_f32_e32 v18, v18
	v_rcp_f32_e32 v19, v19
	v_sub_f32_e32 v20, v20, v227
	v_sub_f32_e32 v21, v21, v227
	v_sub_f32_e32 v22, v22, v227
	v_sub_f32_e32 v23, v23, v227
	v_mul_f32_e32 v20, v20, v228
	v_mul_f32_e32 v21, v21, v228
	v_mul_f32_e32 v22, v22, v228
	v_mul_f32_e32 v23, v23, v228
	v_mul_f32_e32 v12, v12, v16
	v_mul_f32_e32 v13, v13, v17
	v_mul_f32_e32 v14, v14, v18
	v_mul_f32_e32 v15, v15, v19
	v_mul_f32_e32 v20, v20, v92
	v_mul_f32_e32 v21, v21, v93
	v_mul_f32_e32 v22, v22, v94
	v_mul_f32_e32 v23, v23, v95
	v_mul_f32_e32 v20, v20, v12
	v_mul_f32_e32 v21, v21, v13
	v_mul_f32_e32 v22, v22, v14
	v_mul_f32_e32 v23, v23, v15
	v_cvt_pk_bf16_f32 v20, v20, v21
	v_cvt_pk_bf16_f32 v21, v22, v23
	global_store_dwordx2 v204, v[20:21], s[30:31] offset:192
	s_waitcnt vmcnt(7)
	v_lshlrev_b32_e32 v12, 16, v38
	v_and_b32_e32 v13, 0xffff0000, v38
	v_lshlrev_b32_e32 v14, 16, v39
	v_and_b32_e32 v15, 0xffff0000, v39
	v_mul_f32_e32 v16, 0xbfb8aa3b, v12
	v_mul_f32_e32 v17, 0xbfb8aa3b, v13
	v_mul_f32_e32 v18, 0xbfb8aa3b, v14
	v_mul_f32_e32 v19, 0xbfb8aa3b, v15
	v_exp_f32_e32 v16, v16
	v_exp_f32_e32 v17, v17
	v_exp_f32_e32 v18, v18
	v_exp_f32_e32 v19, v19
	v_lshlrev_b32_e32 v20, 16, v114
	v_and_b32_e32 v21, 0xffff0000, v114
	v_lshlrev_b32_e32 v22, 16, v115
	v_and_b32_e32 v23, 0xffff0000, v115
	v_add_f32_e32 v16, 1.0, v16
	v_add_f32_e32 v17, 1.0, v17
	v_add_f32_e32 v18, 1.0, v18
	v_add_f32_e32 v19, 1.0, v19
	v_rcp_f32_e32 v16, v16
	v_rcp_f32_e32 v17, v17
	v_rcp_f32_e32 v18, v18
	v_rcp_f32_e32 v19, v19
	v_sub_f32_e32 v20, v20, v227
	v_sub_f32_e32 v21, v21, v227
	v_sub_f32_e32 v22, v22, v227
	v_sub_f32_e32 v23, v23, v227
	v_mul_f32_e32 v20, v20, v228
	v_mul_f32_e32 v21, v21, v228
	v_mul_f32_e32 v22, v22, v228
	v_mul_f32_e32 v23, v23, v228
	v_mul_f32_e32 v12, v12, v16
	v_mul_f32_e32 v13, v13, v17
	v_mul_f32_e32 v14, v14, v18
	v_mul_f32_e32 v15, v15, v19
	v_mul_f32_e32 v20, v20, v96
	v_mul_f32_e32 v21, v21, v97
	v_mul_f32_e32 v22, v22, v98
	v_mul_f32_e32 v23, v23, v99
	v_mul_f32_e32 v20, v20, v12
	v_mul_f32_e32 v21, v21, v13
	v_mul_f32_e32 v22, v22, v14
	v_mul_f32_e32 v23, v23, v15
	v_cvt_pk_bf16_f32 v20, v20, v21
	v_cvt_pk_bf16_f32 v21, v22, v23
	global_store_dwordx2 v204, v[20:21], s[30:31] offset:224
	global_load_dwordx2 v[24:25], v205, s[34:35] offset:256
	global_load_dwordx2 v[100:101], v204, s[30:31] offset:256
	global_load_dwordx4 v[68:71], v206, s[28:29] offset:512
	global_load_dwordx2 v[26:27], v205, s[34:35] offset:288
	global_load_dwordx2 v[102:103], v204, s[30:31] offset:288
	global_load_dwordx4 v[72:75], v206, s[28:29] offset:576
	global_load_dwordx2 v[28:29], v205, s[34:35] offset:320
	global_load_dwordx2 v[104:105], v204, s[30:31] offset:320
	global_load_dwordx4 v[76:79], v206, s[28:29] offset:640
	global_load_dwordx2 v[30:31], v205, s[34:35] offset:352
	global_load_dwordx2 v[106:107], v204, s[30:31] offset:352
	global_load_dwordx4 v[80:83], v206, s[28:29] offset:704
	global_load_dwordx2 v[32:33], v205, s[34:35] offset:384
	global_load_dwordx2 v[108:109], v204, s[30:31] offset:384
	global_load_dwordx4 v[84:87], v206, s[28:29] offset:768
	global_load_dwordx2 v[34:35], v205, s[34:35] offset:416
	global_load_dwordx2 v[110:111], v204, s[30:31] offset:416
	global_load_dwordx4 v[88:91], v206, s[28:29] offset:832
	global_load_dwordx2 v[36:37], v205, s[34:35] offset:448
	global_load_dwordx2 v[112:113], v204, s[30:31] offset:448
	global_load_dwordx4 v[92:95], v206, s[28:29] offset:896
	global_load_dwordx2 v[38:39], v205, s[34:35] offset:480
	global_load_dwordx2 v[114:115], v204, s[30:31] offset:480
	global_load_dwordx4 v[96:99], v206, s[28:29] offset:960
	s_waitcnt vmcnt(21)
	v_lshlrev_b32_e32 v12, 16, v24
	v_and_b32_e32 v13, 0xffff0000, v24
	v_lshlrev_b32_e32 v14, 16, v25
	v_and_b32_e32 v15, 0xffff0000, v25
	v_mul_f32_e32 v16, 0xbfb8aa3b, v12
	v_mul_f32_e32 v17, 0xbfb8aa3b, v13
	v_mul_f32_e32 v18, 0xbfb8aa3b, v14
	v_mul_f32_e32 v19, 0xbfb8aa3b, v15
	v_exp_f32_e32 v16, v16
	v_exp_f32_e32 v17, v17
	v_exp_f32_e32 v18, v18
	v_exp_f32_e32 v19, v19
	v_lshlrev_b32_e32 v20, 16, v100
	v_and_b32_e32 v21, 0xffff0000, v100
	v_lshlrev_b32_e32 v22, 16, v101
	v_and_b32_e32 v23, 0xffff0000, v101
	v_add_f32_e32 v16, 1.0, v16
	v_add_f32_e32 v17, 1.0, v17
	v_add_f32_e32 v18, 1.0, v18
	v_add_f32_e32 v19, 1.0, v19
	v_rcp_f32_e32 v16, v16
	v_rcp_f32_e32 v17, v17
	v_rcp_f32_e32 v18, v18
	v_rcp_f32_e32 v19, v19
	v_sub_f32_e32 v20, v20, v227
	v_sub_f32_e32 v21, v21, v227
	v_sub_f32_e32 v22, v22, v227
	v_sub_f32_e32 v23, v23, v227
	v_mul_f32_e32 v20, v20, v228
	v_mul_f32_e32 v21, v21, v228
	v_mul_f32_e32 v22, v22, v228
	v_mul_f32_e32 v23, v23, v228
	v_mul_f32_e32 v12, v12, v16
	v_mul_f32_e32 v13, v13, v17
	v_mul_f32_e32 v14, v14, v18
	v_mul_f32_e32 v15, v15, v19
	v_mul_f32_e32 v20, v20, v68
	v_mul_f32_e32 v21, v21, v69
	v_mul_f32_e32 v22, v22, v70
	v_mul_f32_e32 v23, v23, v71
	v_mul_f32_e32 v20, v20, v12
	v_mul_f32_e32 v21, v21, v13
	v_mul_f32_e32 v22, v22, v14
	v_mul_f32_e32 v23, v23, v15
	v_cvt_pk_bf16_f32 v20, v20, v21
	v_cvt_pk_bf16_f32 v21, v22, v23
	global_store_dwordx2 v204, v[20:21], s[30:31] offset:256
	s_waitcnt vmcnt(19)
	v_lshlrev_b32_e32 v12, 16, v26
	v_and_b32_e32 v13, 0xffff0000, v26
	v_lshlrev_b32_e32 v14, 16, v27
	v_and_b32_e32 v15, 0xffff0000, v27
	v_mul_f32_e32 v16, 0xbfb8aa3b, v12
	v_mul_f32_e32 v17, 0xbfb8aa3b, v13
	v_mul_f32_e32 v18, 0xbfb8aa3b, v14
	v_mul_f32_e32 v19, 0xbfb8aa3b, v15
	v_exp_f32_e32 v16, v16
	v_exp_f32_e32 v17, v17
	v_exp_f32_e32 v18, v18
	v_exp_f32_e32 v19, v19
	v_lshlrev_b32_e32 v20, 16, v102
	v_and_b32_e32 v21, 0xffff0000, v102
	v_lshlrev_b32_e32 v22, 16, v103
	v_and_b32_e32 v23, 0xffff0000, v103
	v_add_f32_e32 v16, 1.0, v16
	v_add_f32_e32 v17, 1.0, v17
	v_add_f32_e32 v18, 1.0, v18
	v_add_f32_e32 v19, 1.0, v19
	v_rcp_f32_e32 v16, v16
	v_rcp_f32_e32 v17, v17
	v_rcp_f32_e32 v18, v18
	v_rcp_f32_e32 v19, v19
	v_sub_f32_e32 v20, v20, v227
	v_sub_f32_e32 v21, v21, v227
	v_sub_f32_e32 v22, v22, v227
	v_sub_f32_e32 v23, v23, v227
	v_mul_f32_e32 v20, v20, v228
	v_mul_f32_e32 v21, v21, v228
	v_mul_f32_e32 v22, v22, v228
	v_mul_f32_e32 v23, v23, v228
	v_mul_f32_e32 v12, v12, v16
	v_mul_f32_e32 v13, v13, v17
	v_mul_f32_e32 v14, v14, v18
	v_mul_f32_e32 v15, v15, v19
	v_mul_f32_e32 v20, v20, v72
	v_mul_f32_e32 v21, v21, v73
	v_mul_f32_e32 v22, v22, v74
	v_mul_f32_e32 v23, v23, v75
	v_mul_f32_e32 v20, v20, v12
	v_mul_f32_e32 v21, v21, v13
	v_mul_f32_e32 v22, v22, v14
	v_mul_f32_e32 v23, v23, v15
	v_cvt_pk_bf16_f32 v20, v20, v21
	v_cvt_pk_bf16_f32 v21, v22, v23
	global_store_dwordx2 v204, v[20:21], s[30:31] offset:288
	s_waitcnt vmcnt(17)
	v_lshlrev_b32_e32 v12, 16, v28
	v_and_b32_e32 v13, 0xffff0000, v28
	v_lshlrev_b32_e32 v14, 16, v29
	v_and_b32_e32 v15, 0xffff0000, v29
	v_mul_f32_e32 v16, 0xbfb8aa3b, v12
	v_mul_f32_e32 v17, 0xbfb8aa3b, v13
	v_mul_f32_e32 v18, 0xbfb8aa3b, v14
	v_mul_f32_e32 v19, 0xbfb8aa3b, v15
	v_exp_f32_e32 v16, v16
	v_exp_f32_e32 v17, v17
	v_exp_f32_e32 v18, v18
	v_exp_f32_e32 v19, v19
	v_lshlrev_b32_e32 v20, 16, v104
	v_and_b32_e32 v21, 0xffff0000, v104
	v_lshlrev_b32_e32 v22, 16, v105
	v_and_b32_e32 v23, 0xffff0000, v105
	v_add_f32_e32 v16, 1.0, v16
	v_add_f32_e32 v17, 1.0, v17
	v_add_f32_e32 v18, 1.0, v18
	v_add_f32_e32 v19, 1.0, v19
	v_rcp_f32_e32 v16, v16
	v_rcp_f32_e32 v17, v17
	v_rcp_f32_e32 v18, v18
	v_rcp_f32_e32 v19, v19
	v_sub_f32_e32 v20, v20, v227
	v_sub_f32_e32 v21, v21, v227
	v_sub_f32_e32 v22, v22, v227
	v_sub_f32_e32 v23, v23, v227
	v_mul_f32_e32 v20, v20, v228
	v_mul_f32_e32 v21, v21, v228
	v_mul_f32_e32 v22, v22, v228
	v_mul_f32_e32 v23, v23, v228
	v_mul_f32_e32 v12, v12, v16
	v_mul_f32_e32 v13, v13, v17
	v_mul_f32_e32 v14, v14, v18
	v_mul_f32_e32 v15, v15, v19
	v_mul_f32_e32 v20, v20, v76
	v_mul_f32_e32 v21, v21, v77
	v_mul_f32_e32 v22, v22, v78
	v_mul_f32_e32 v23, v23, v79
	v_mul_f32_e32 v20, v20, v12
	v_mul_f32_e32 v21, v21, v13
	v_mul_f32_e32 v22, v22, v14
	v_mul_f32_e32 v23, v23, v15
	v_cvt_pk_bf16_f32 v20, v20, v21
	v_cvt_pk_bf16_f32 v21, v22, v23
	global_store_dwordx2 v204, v[20:21], s[30:31] offset:320
	s_waitcnt vmcnt(15)
	v_lshlrev_b32_e32 v12, 16, v30
	v_and_b32_e32 v13, 0xffff0000, v30
	v_lshlrev_b32_e32 v14, 16, v31
	v_and_b32_e32 v15, 0xffff0000, v31
	v_mul_f32_e32 v16, 0xbfb8aa3b, v12
	v_mul_f32_e32 v17, 0xbfb8aa3b, v13
	v_mul_f32_e32 v18, 0xbfb8aa3b, v14
	v_mul_f32_e32 v19, 0xbfb8aa3b, v15
	v_exp_f32_e32 v16, v16
	v_exp_f32_e32 v17, v17
	v_exp_f32_e32 v18, v18
	v_exp_f32_e32 v19, v19
	v_lshlrev_b32_e32 v20, 16, v106
	v_and_b32_e32 v21, 0xffff0000, v106
	v_lshlrev_b32_e32 v22, 16, v107
	v_and_b32_e32 v23, 0xffff0000, v107
	v_add_f32_e32 v16, 1.0, v16
	v_add_f32_e32 v17, 1.0, v17
	v_add_f32_e32 v18, 1.0, v18
	v_add_f32_e32 v19, 1.0, v19
	v_rcp_f32_e32 v16, v16
	v_rcp_f32_e32 v17, v17
	v_rcp_f32_e32 v18, v18
	v_rcp_f32_e32 v19, v19
	v_sub_f32_e32 v20, v20, v227
	v_sub_f32_e32 v21, v21, v227
	v_sub_f32_e32 v22, v22, v227
	v_sub_f32_e32 v23, v23, v227
	v_mul_f32_e32 v20, v20, v228
	v_mul_f32_e32 v21, v21, v228
	v_mul_f32_e32 v22, v22, v228
	v_mul_f32_e32 v23, v23, v228
	v_mul_f32_e32 v12, v12, v16
	v_mul_f32_e32 v13, v13, v17
	v_mul_f32_e32 v14, v14, v18
	v_mul_f32_e32 v15, v15, v19
	v_mul_f32_e32 v20, v20, v80
	v_mul_f32_e32 v21, v21, v81
	v_mul_f32_e32 v22, v22, v82
	v_mul_f32_e32 v23, v23, v83
	v_mul_f32_e32 v20, v20, v12
	v_mul_f32_e32 v21, v21, v13
	v_mul_f32_e32 v22, v22, v14
	v_mul_f32_e32 v23, v23, v15
	v_cvt_pk_bf16_f32 v20, v20, v21
	v_cvt_pk_bf16_f32 v21, v22, v23
	global_store_dwordx2 v204, v[20:21], s[30:31] offset:352
	s_waitcnt vmcnt(13)
	v_lshlrev_b32_e32 v12, 16, v32
	v_and_b32_e32 v13, 0xffff0000, v32
	v_lshlrev_b32_e32 v14, 16, v33
	v_and_b32_e32 v15, 0xffff0000, v33
	v_mul_f32_e32 v16, 0xbfb8aa3b, v12
	v_mul_f32_e32 v17, 0xbfb8aa3b, v13
	v_mul_f32_e32 v18, 0xbfb8aa3b, v14
	v_mul_f32_e32 v19, 0xbfb8aa3b, v15
	v_exp_f32_e32 v16, v16
	v_exp_f32_e32 v17, v17
	v_exp_f32_e32 v18, v18
	v_exp_f32_e32 v19, v19
	v_lshlrev_b32_e32 v20, 16, v108
	v_and_b32_e32 v21, 0xffff0000, v108
	v_lshlrev_b32_e32 v22, 16, v109
	v_and_b32_e32 v23, 0xffff0000, v109
	v_add_f32_e32 v16, 1.0, v16
	v_add_f32_e32 v17, 1.0, v17
	v_add_f32_e32 v18, 1.0, v18
	v_add_f32_e32 v19, 1.0, v19
	v_rcp_f32_e32 v16, v16
	v_rcp_f32_e32 v17, v17
	v_rcp_f32_e32 v18, v18
	v_rcp_f32_e32 v19, v19
	v_sub_f32_e32 v20, v20, v227
	v_sub_f32_e32 v21, v21, v227
	v_sub_f32_e32 v22, v22, v227
	v_sub_f32_e32 v23, v23, v227
	v_mul_f32_e32 v20, v20, v228
	v_mul_f32_e32 v21, v21, v228
	v_mul_f32_e32 v22, v22, v228
	v_mul_f32_e32 v23, v23, v228
	v_mul_f32_e32 v12, v12, v16
	v_mul_f32_e32 v13, v13, v17
	v_mul_f32_e32 v14, v14, v18
	v_mul_f32_e32 v15, v15, v19
	v_mul_f32_e32 v20, v20, v84
	v_mul_f32_e32 v21, v21, v85
	v_mul_f32_e32 v22, v22, v86
	v_mul_f32_e32 v23, v23, v87
	v_mul_f32_e32 v20, v20, v12
	v_mul_f32_e32 v21, v21, v13
	v_mul_f32_e32 v22, v22, v14
	v_mul_f32_e32 v23, v23, v15
	v_cvt_pk_bf16_f32 v20, v20, v21
	v_cvt_pk_bf16_f32 v21, v22, v23
	global_store_dwordx2 v204, v[20:21], s[30:31] offset:384
	s_waitcnt vmcnt(11)
	v_lshlrev_b32_e32 v12, 16, v34
	v_and_b32_e32 v13, 0xffff0000, v34
	v_lshlrev_b32_e32 v14, 16, v35
	v_and_b32_e32 v15, 0xffff0000, v35
	v_mul_f32_e32 v16, 0xbfb8aa3b, v12
	v_mul_f32_e32 v17, 0xbfb8aa3b, v13
	v_mul_f32_e32 v18, 0xbfb8aa3b, v14
	v_mul_f32_e32 v19, 0xbfb8aa3b, v15
	v_exp_f32_e32 v16, v16
	v_exp_f32_e32 v17, v17
	v_exp_f32_e32 v18, v18
	v_exp_f32_e32 v19, v19
	v_lshlrev_b32_e32 v20, 16, v110
	v_and_b32_e32 v21, 0xffff0000, v110
	v_lshlrev_b32_e32 v22, 16, v111
	v_and_b32_e32 v23, 0xffff0000, v111
	v_add_f32_e32 v16, 1.0, v16
	v_add_f32_e32 v17, 1.0, v17
	v_add_f32_e32 v18, 1.0, v18
	v_add_f32_e32 v19, 1.0, v19
	v_rcp_f32_e32 v16, v16
	v_rcp_f32_e32 v17, v17
	v_rcp_f32_e32 v18, v18
	v_rcp_f32_e32 v19, v19
	v_sub_f32_e32 v20, v20, v227
	v_sub_f32_e32 v21, v21, v227
	v_sub_f32_e32 v22, v22, v227
	v_sub_f32_e32 v23, v23, v227
	v_mul_f32_e32 v20, v20, v228
	v_mul_f32_e32 v21, v21, v228
	v_mul_f32_e32 v22, v22, v228
	v_mul_f32_e32 v23, v23, v228
	v_mul_f32_e32 v12, v12, v16
	v_mul_f32_e32 v13, v13, v17
	v_mul_f32_e32 v14, v14, v18
	v_mul_f32_e32 v15, v15, v19
	v_mul_f32_e32 v20, v20, v88
	v_mul_f32_e32 v21, v21, v89
	v_mul_f32_e32 v22, v22, v90
	v_mul_f32_e32 v23, v23, v91
	v_mul_f32_e32 v20, v20, v12
	v_mul_f32_e32 v21, v21, v13
	v_mul_f32_e32 v22, v22, v14
	v_mul_f32_e32 v23, v23, v15
	v_cvt_pk_bf16_f32 v20, v20, v21
	v_cvt_pk_bf16_f32 v21, v22, v23
	global_store_dwordx2 v204, v[20:21], s[30:31] offset:416
	s_waitcnt vmcnt(9)
	v_lshlrev_b32_e32 v12, 16, v36
	v_and_b32_e32 v13, 0xffff0000, v36
	v_lshlrev_b32_e32 v14, 16, v37
	v_and_b32_e32 v15, 0xffff0000, v37
	v_mul_f32_e32 v16, 0xbfb8aa3b, v12
	v_mul_f32_e32 v17, 0xbfb8aa3b, v13
	v_mul_f32_e32 v18, 0xbfb8aa3b, v14
	v_mul_f32_e32 v19, 0xbfb8aa3b, v15
	v_exp_f32_e32 v16, v16
	v_exp_f32_e32 v17, v17
	v_exp_f32_e32 v18, v18
	v_exp_f32_e32 v19, v19
	v_lshlrev_b32_e32 v20, 16, v112
	v_and_b32_e32 v21, 0xffff0000, v112
	v_lshlrev_b32_e32 v22, 16, v113
	v_and_b32_e32 v23, 0xffff0000, v113
	v_add_f32_e32 v16, 1.0, v16
	v_add_f32_e32 v17, 1.0, v17
	v_add_f32_e32 v18, 1.0, v18
	v_add_f32_e32 v19, 1.0, v19
	v_rcp_f32_e32 v16, v16
	v_rcp_f32_e32 v17, v17
	v_rcp_f32_e32 v18, v18
	v_rcp_f32_e32 v19, v19
	v_sub_f32_e32 v20, v20, v227
	v_sub_f32_e32 v21, v21, v227
	v_sub_f32_e32 v22, v22, v227
	v_sub_f32_e32 v23, v23, v227
	v_mul_f32_e32 v20, v20, v228
	v_mul_f32_e32 v21, v21, v228
	v_mul_f32_e32 v22, v22, v228
	v_mul_f32_e32 v23, v23, v228
	v_mul_f32_e32 v12, v12, v16
	v_mul_f32_e32 v13, v13, v17
	v_mul_f32_e32 v14, v14, v18
	v_mul_f32_e32 v15, v15, v19
	v_mul_f32_e32 v20, v20, v92
	v_mul_f32_e32 v21, v21, v93
	v_mul_f32_e32 v22, v22, v94
	v_mul_f32_e32 v23, v23, v95
	v_mul_f32_e32 v20, v20, v12
	v_mul_f32_e32 v21, v21, v13
	v_mul_f32_e32 v22, v22, v14
	v_mul_f32_e32 v23, v23, v15
	v_cvt_pk_bf16_f32 v20, v20, v21
	v_cvt_pk_bf16_f32 v21, v22, v23
	global_store_dwordx2 v204, v[20:21], s[30:31] offset:448
	s_waitcnt vmcnt(7)
	v_lshlrev_b32_e32 v12, 16, v38
	v_and_b32_e32 v13, 0xffff0000, v38
	v_lshlrev_b32_e32 v14, 16, v39
	v_and_b32_e32 v15, 0xffff0000, v39
	v_mul_f32_e32 v16, 0xbfb8aa3b, v12
	v_mul_f32_e32 v17, 0xbfb8aa3b, v13
	v_mul_f32_e32 v18, 0xbfb8aa3b, v14
	v_mul_f32_e32 v19, 0xbfb8aa3b, v15
	v_exp_f32_e32 v16, v16
	v_exp_f32_e32 v17, v17
	v_exp_f32_e32 v18, v18
	v_exp_f32_e32 v19, v19
	v_lshlrev_b32_e32 v20, 16, v114
	v_and_b32_e32 v21, 0xffff0000, v114
	v_lshlrev_b32_e32 v22, 16, v115
	v_and_b32_e32 v23, 0xffff0000, v115
	v_add_f32_e32 v16, 1.0, v16
	v_add_f32_e32 v17, 1.0, v17
	v_add_f32_e32 v18, 1.0, v18
	v_add_f32_e32 v19, 1.0, v19
	v_rcp_f32_e32 v16, v16
	v_rcp_f32_e32 v17, v17
	v_rcp_f32_e32 v18, v18
	v_rcp_f32_e32 v19, v19
	v_sub_f32_e32 v20, v20, v227
	v_sub_f32_e32 v21, v21, v227
	v_sub_f32_e32 v22, v22, v227
	v_sub_f32_e32 v23, v23, v227
	v_mul_f32_e32 v20, v20, v228
	v_mul_f32_e32 v21, v21, v228
	v_mul_f32_e32 v22, v22, v228
	v_mul_f32_e32 v23, v23, v228
	v_mul_f32_e32 v12, v12, v16
	v_mul_f32_e32 v13, v13, v17
	v_mul_f32_e32 v14, v14, v18
	v_mul_f32_e32 v15, v15, v19
	v_mul_f32_e32 v20, v20, v96
	v_mul_f32_e32 v21, v21, v97
	v_mul_f32_e32 v22, v22, v98
	v_mul_f32_e32 v23, v23, v99
	v_mul_f32_e32 v20, v20, v12
	v_mul_f32_e32 v21, v21, v13
	v_mul_f32_e32 v22, v22, v14
	v_mul_f32_e32 v23, v23, v15
	v_cvt_pk_bf16_f32 v20, v20, v21
	v_cvt_pk_bf16_f32 v21, v22, v23
	global_store_dwordx2 v204, v[20:21], s[30:31] offset:480
	global_load_dwordx2 v[24:25], v205, s[34:35] offset:512
	global_load_dwordx2 v[100:101], v204, s[30:31] offset:512
	global_load_dwordx4 v[68:71], v206, s[28:29] offset:1024
	global_load_dwordx2 v[26:27], v205, s[34:35] offset:544
	global_load_dwordx2 v[102:103], v204, s[30:31] offset:544
	global_load_dwordx4 v[72:75], v206, s[28:29] offset:1088
	global_load_dwordx2 v[28:29], v205, s[34:35] offset:576
	global_load_dwordx2 v[104:105], v204, s[30:31] offset:576
	global_load_dwordx4 v[76:79], v206, s[28:29] offset:1152
	global_load_dwordx2 v[30:31], v205, s[34:35] offset:608
	global_load_dwordx2 v[106:107], v204, s[30:31] offset:608
	global_load_dwordx4 v[80:83], v206, s[28:29] offset:1216
	global_load_dwordx2 v[32:33], v205, s[34:35] offset:640
	global_load_dwordx2 v[108:109], v204, s[30:31] offset:640
	global_load_dwordx4 v[84:87], v206, s[28:29] offset:1280
	global_load_dwordx2 v[34:35], v205, s[34:35] offset:672
	global_load_dwordx2 v[110:111], v204, s[30:31] offset:672
	global_load_dwordx4 v[88:91], v206, s[28:29] offset:1344
	global_load_dwordx2 v[36:37], v205, s[34:35] offset:704
	global_load_dwordx2 v[112:113], v204, s[30:31] offset:704
	global_load_dwordx4 v[92:95], v206, s[28:29] offset:1408
	global_load_dwordx2 v[38:39], v205, s[34:35] offset:736
	global_load_dwordx2 v[114:115], v204, s[30:31] offset:736
	global_load_dwordx4 v[96:99], v206, s[28:29] offset:1472
	s_waitcnt vmcnt(21)
	v_lshlrev_b32_e32 v12, 16, v24
	v_and_b32_e32 v13, 0xffff0000, v24
	v_lshlrev_b32_e32 v14, 16, v25
	v_and_b32_e32 v15, 0xffff0000, v25
	v_mul_f32_e32 v16, 0xbfb8aa3b, v12
	v_mul_f32_e32 v17, 0xbfb8aa3b, v13
	v_mul_f32_e32 v18, 0xbfb8aa3b, v14
	v_mul_f32_e32 v19, 0xbfb8aa3b, v15
	v_exp_f32_e32 v16, v16
	v_exp_f32_e32 v17, v17
	v_exp_f32_e32 v18, v18
	v_exp_f32_e32 v19, v19
	v_lshlrev_b32_e32 v20, 16, v100
	v_and_b32_e32 v21, 0xffff0000, v100
	v_lshlrev_b32_e32 v22, 16, v101
	v_and_b32_e32 v23, 0xffff0000, v101
	v_add_f32_e32 v16, 1.0, v16
	v_add_f32_e32 v17, 1.0, v17
	v_add_f32_e32 v18, 1.0, v18
	v_add_f32_e32 v19, 1.0, v19
	v_rcp_f32_e32 v16, v16
	v_rcp_f32_e32 v17, v17
	v_rcp_f32_e32 v18, v18
	v_rcp_f32_e32 v19, v19
	v_sub_f32_e32 v20, v20, v227
	v_sub_f32_e32 v21, v21, v227
	v_sub_f32_e32 v22, v22, v227
	v_sub_f32_e32 v23, v23, v227
	v_mul_f32_e32 v20, v20, v228
	v_mul_f32_e32 v21, v21, v228
	v_mul_f32_e32 v22, v22, v228
	v_mul_f32_e32 v23, v23, v228
	v_mul_f32_e32 v12, v12, v16
	v_mul_f32_e32 v13, v13, v17
	v_mul_f32_e32 v14, v14, v18
	v_mul_f32_e32 v15, v15, v19
	v_mul_f32_e32 v20, v20, v68
	v_mul_f32_e32 v21, v21, v69
	v_mul_f32_e32 v22, v22, v70
	v_mul_f32_e32 v23, v23, v71
	v_mul_f32_e32 v20, v20, v12
	v_mul_f32_e32 v21, v21, v13
	v_mul_f32_e32 v22, v22, v14
	v_mul_f32_e32 v23, v23, v15
	v_cvt_pk_bf16_f32 v20, v20, v21
	v_cvt_pk_bf16_f32 v21, v22, v23
	global_store_dwordx2 v204, v[20:21], s[30:31] offset:512
	s_waitcnt vmcnt(19)
	v_lshlrev_b32_e32 v12, 16, v26
	v_and_b32_e32 v13, 0xffff0000, v26
	v_lshlrev_b32_e32 v14, 16, v27
	v_and_b32_e32 v15, 0xffff0000, v27
	v_mul_f32_e32 v16, 0xbfb8aa3b, v12
	v_mul_f32_e32 v17, 0xbfb8aa3b, v13
	v_mul_f32_e32 v18, 0xbfb8aa3b, v14
	v_mul_f32_e32 v19, 0xbfb8aa3b, v15
	v_exp_f32_e32 v16, v16
	v_exp_f32_e32 v17, v17
	v_exp_f32_e32 v18, v18
	v_exp_f32_e32 v19, v19
	v_lshlrev_b32_e32 v20, 16, v102
	v_and_b32_e32 v21, 0xffff0000, v102
	v_lshlrev_b32_e32 v22, 16, v103
	v_and_b32_e32 v23, 0xffff0000, v103
	v_add_f32_e32 v16, 1.0, v16
	v_add_f32_e32 v17, 1.0, v17
	v_add_f32_e32 v18, 1.0, v18
	v_add_f32_e32 v19, 1.0, v19
	v_rcp_f32_e32 v16, v16
	v_rcp_f32_e32 v17, v17
	v_rcp_f32_e32 v18, v18
	v_rcp_f32_e32 v19, v19
	v_sub_f32_e32 v20, v20, v227
	v_sub_f32_e32 v21, v21, v227
	v_sub_f32_e32 v22, v22, v227
	v_sub_f32_e32 v23, v23, v227
	v_mul_f32_e32 v20, v20, v228
	v_mul_f32_e32 v21, v21, v228
	v_mul_f32_e32 v22, v22, v228
	v_mul_f32_e32 v23, v23, v228
	v_mul_f32_e32 v12, v12, v16
	v_mul_f32_e32 v13, v13, v17
	v_mul_f32_e32 v14, v14, v18
	v_mul_f32_e32 v15, v15, v19
	v_mul_f32_e32 v20, v20, v72
	v_mul_f32_e32 v21, v21, v73
	v_mul_f32_e32 v22, v22, v74
	v_mul_f32_e32 v23, v23, v75
	v_mul_f32_e32 v20, v20, v12
	v_mul_f32_e32 v21, v21, v13
	v_mul_f32_e32 v22, v22, v14
	v_mul_f32_e32 v23, v23, v15
	v_cvt_pk_bf16_f32 v20, v20, v21
	v_cvt_pk_bf16_f32 v21, v22, v23
	global_store_dwordx2 v204, v[20:21], s[30:31] offset:544
	s_waitcnt vmcnt(17)
	v_lshlrev_b32_e32 v12, 16, v28
	v_and_b32_e32 v13, 0xffff0000, v28
	v_lshlrev_b32_e32 v14, 16, v29
	v_and_b32_e32 v15, 0xffff0000, v29
	v_mul_f32_e32 v16, 0xbfb8aa3b, v12
	v_mul_f32_e32 v17, 0xbfb8aa3b, v13
	v_mul_f32_e32 v18, 0xbfb8aa3b, v14
	v_mul_f32_e32 v19, 0xbfb8aa3b, v15
	v_exp_f32_e32 v16, v16
	v_exp_f32_e32 v17, v17
	v_exp_f32_e32 v18, v18
	v_exp_f32_e32 v19, v19
	v_lshlrev_b32_e32 v20, 16, v104
	v_and_b32_e32 v21, 0xffff0000, v104
	v_lshlrev_b32_e32 v22, 16, v105
	v_and_b32_e32 v23, 0xffff0000, v105
	v_add_f32_e32 v16, 1.0, v16
	v_add_f32_e32 v17, 1.0, v17
	v_add_f32_e32 v18, 1.0, v18
	v_add_f32_e32 v19, 1.0, v19
	v_rcp_f32_e32 v16, v16
	v_rcp_f32_e32 v17, v17
	v_rcp_f32_e32 v18, v18
	v_rcp_f32_e32 v19, v19
	v_sub_f32_e32 v20, v20, v227
	v_sub_f32_e32 v21, v21, v227
	v_sub_f32_e32 v22, v22, v227
	v_sub_f32_e32 v23, v23, v227
	v_mul_f32_e32 v20, v20, v228
	v_mul_f32_e32 v21, v21, v228
	v_mul_f32_e32 v22, v22, v228
	v_mul_f32_e32 v23, v23, v228
	v_mul_f32_e32 v12, v12, v16
	v_mul_f32_e32 v13, v13, v17
	v_mul_f32_e32 v14, v14, v18
	v_mul_f32_e32 v15, v15, v19
	v_mul_f32_e32 v20, v20, v76
	v_mul_f32_e32 v21, v21, v77
	v_mul_f32_e32 v22, v22, v78
	v_mul_f32_e32 v23, v23, v79
	v_mul_f32_e32 v20, v20, v12
	v_mul_f32_e32 v21, v21, v13
	v_mul_f32_e32 v22, v22, v14
	v_mul_f32_e32 v23, v23, v15
	v_cvt_pk_bf16_f32 v20, v20, v21
	v_cvt_pk_bf16_f32 v21, v22, v23
	global_store_dwordx2 v204, v[20:21], s[30:31] offset:576
	s_waitcnt vmcnt(15)
	v_lshlrev_b32_e32 v12, 16, v30
	v_and_b32_e32 v13, 0xffff0000, v30
	v_lshlrev_b32_e32 v14, 16, v31
	v_and_b32_e32 v15, 0xffff0000, v31
	v_mul_f32_e32 v16, 0xbfb8aa3b, v12
	v_mul_f32_e32 v17, 0xbfb8aa3b, v13
	v_mul_f32_e32 v18, 0xbfb8aa3b, v14
	v_mul_f32_e32 v19, 0xbfb8aa3b, v15
	v_exp_f32_e32 v16, v16
	v_exp_f32_e32 v17, v17
	v_exp_f32_e32 v18, v18
	v_exp_f32_e32 v19, v19
	v_lshlrev_b32_e32 v20, 16, v106
	v_and_b32_e32 v21, 0xffff0000, v106
	v_lshlrev_b32_e32 v22, 16, v107
	v_and_b32_e32 v23, 0xffff0000, v107
	v_add_f32_e32 v16, 1.0, v16
	v_add_f32_e32 v17, 1.0, v17
	v_add_f32_e32 v18, 1.0, v18
	v_add_f32_e32 v19, 1.0, v19
	v_rcp_f32_e32 v16, v16
	v_rcp_f32_e32 v17, v17
	v_rcp_f32_e32 v18, v18
	v_rcp_f32_e32 v19, v19
	v_sub_f32_e32 v20, v20, v227
	v_sub_f32_e32 v21, v21, v227
	v_sub_f32_e32 v22, v22, v227
	v_sub_f32_e32 v23, v23, v227
	v_mul_f32_e32 v20, v20, v228
	v_mul_f32_e32 v21, v21, v228
	v_mul_f32_e32 v22, v22, v228
	v_mul_f32_e32 v23, v23, v228
	v_mul_f32_e32 v12, v12, v16
	v_mul_f32_e32 v13, v13, v17
	v_mul_f32_e32 v14, v14, v18
	v_mul_f32_e32 v15, v15, v19
	v_mul_f32_e32 v20, v20, v80
	v_mul_f32_e32 v21, v21, v81
	v_mul_f32_e32 v22, v22, v82
	v_mul_f32_e32 v23, v23, v83
	v_mul_f32_e32 v20, v20, v12
	v_mul_f32_e32 v21, v21, v13
	v_mul_f32_e32 v22, v22, v14
	v_mul_f32_e32 v23, v23, v15
	v_cvt_pk_bf16_f32 v20, v20, v21
	v_cvt_pk_bf16_f32 v21, v22, v23
	global_store_dwordx2 v204, v[20:21], s[30:31] offset:608
	s_waitcnt vmcnt(13)
	v_lshlrev_b32_e32 v12, 16, v32
	v_and_b32_e32 v13, 0xffff0000, v32
	v_lshlrev_b32_e32 v14, 16, v33
	v_and_b32_e32 v15, 0xffff0000, v33
	v_mul_f32_e32 v16, 0xbfb8aa3b, v12
	v_mul_f32_e32 v17, 0xbfb8aa3b, v13
	v_mul_f32_e32 v18, 0xbfb8aa3b, v14
	v_mul_f32_e32 v19, 0xbfb8aa3b, v15
	v_exp_f32_e32 v16, v16
	v_exp_f32_e32 v17, v17
	v_exp_f32_e32 v18, v18
	v_exp_f32_e32 v19, v19
	v_lshlrev_b32_e32 v20, 16, v108
	v_and_b32_e32 v21, 0xffff0000, v108
	v_lshlrev_b32_e32 v22, 16, v109
	v_and_b32_e32 v23, 0xffff0000, v109
	v_add_f32_e32 v16, 1.0, v16
	v_add_f32_e32 v17, 1.0, v17
	v_add_f32_e32 v18, 1.0, v18
	v_add_f32_e32 v19, 1.0, v19
	v_rcp_f32_e32 v16, v16
	v_rcp_f32_e32 v17, v17
	v_rcp_f32_e32 v18, v18
	v_rcp_f32_e32 v19, v19
	v_sub_f32_e32 v20, v20, v227
	v_sub_f32_e32 v21, v21, v227
	v_sub_f32_e32 v22, v22, v227
	v_sub_f32_e32 v23, v23, v227
	v_mul_f32_e32 v20, v20, v228
	v_mul_f32_e32 v21, v21, v228
	v_mul_f32_e32 v22, v22, v228
	v_mul_f32_e32 v23, v23, v228
	v_mul_f32_e32 v12, v12, v16
	v_mul_f32_e32 v13, v13, v17
	v_mul_f32_e32 v14, v14, v18
	v_mul_f32_e32 v15, v15, v19
	v_mul_f32_e32 v20, v20, v84
	v_mul_f32_e32 v21, v21, v85
	v_mul_f32_e32 v22, v22, v86
	v_mul_f32_e32 v23, v23, v87
	v_mul_f32_e32 v20, v20, v12
	v_mul_f32_e32 v21, v21, v13
	v_mul_f32_e32 v22, v22, v14
	v_mul_f32_e32 v23, v23, v15
	v_cvt_pk_bf16_f32 v20, v20, v21
	v_cvt_pk_bf16_f32 v21, v22, v23
	global_store_dwordx2 v204, v[20:21], s[30:31] offset:640
	s_waitcnt vmcnt(11)
	v_lshlrev_b32_e32 v12, 16, v34
	v_and_b32_e32 v13, 0xffff0000, v34
	v_lshlrev_b32_e32 v14, 16, v35
	v_and_b32_e32 v15, 0xffff0000, v35
	v_mul_f32_e32 v16, 0xbfb8aa3b, v12
	v_mul_f32_e32 v17, 0xbfb8aa3b, v13
	v_mul_f32_e32 v18, 0xbfb8aa3b, v14
	v_mul_f32_e32 v19, 0xbfb8aa3b, v15
	v_exp_f32_e32 v16, v16
	v_exp_f32_e32 v17, v17
	v_exp_f32_e32 v18, v18
	v_exp_f32_e32 v19, v19
	v_lshlrev_b32_e32 v20, 16, v110
	v_and_b32_e32 v21, 0xffff0000, v110
	v_lshlrev_b32_e32 v22, 16, v111
	v_and_b32_e32 v23, 0xffff0000, v111
	v_add_f32_e32 v16, 1.0, v16
	v_add_f32_e32 v17, 1.0, v17
	v_add_f32_e32 v18, 1.0, v18
	v_add_f32_e32 v19, 1.0, v19
	v_rcp_f32_e32 v16, v16
	v_rcp_f32_e32 v17, v17
	v_rcp_f32_e32 v18, v18
	v_rcp_f32_e32 v19, v19
	v_sub_f32_e32 v20, v20, v227
	v_sub_f32_e32 v21, v21, v227
	v_sub_f32_e32 v22, v22, v227
	v_sub_f32_e32 v23, v23, v227
	v_mul_f32_e32 v20, v20, v228
	v_mul_f32_e32 v21, v21, v228
	v_mul_f32_e32 v22, v22, v228
	v_mul_f32_e32 v23, v23, v228
	v_mul_f32_e32 v12, v12, v16
	v_mul_f32_e32 v13, v13, v17
	v_mul_f32_e32 v14, v14, v18
	v_mul_f32_e32 v15, v15, v19
	v_mul_f32_e32 v20, v20, v88
	v_mul_f32_e32 v21, v21, v89
	v_mul_f32_e32 v22, v22, v90
	v_mul_f32_e32 v23, v23, v91
	v_mul_f32_e32 v20, v20, v12
	v_mul_f32_e32 v21, v21, v13
	v_mul_f32_e32 v22, v22, v14
	v_mul_f32_e32 v23, v23, v15
	v_cvt_pk_bf16_f32 v20, v20, v21
	v_cvt_pk_bf16_f32 v21, v22, v23
	global_store_dwordx2 v204, v[20:21], s[30:31] offset:672
	s_waitcnt vmcnt(9)
	v_lshlrev_b32_e32 v12, 16, v36
	v_and_b32_e32 v13, 0xffff0000, v36
	v_lshlrev_b32_e32 v14, 16, v37
	v_and_b32_e32 v15, 0xffff0000, v37
	v_mul_f32_e32 v16, 0xbfb8aa3b, v12
	v_mul_f32_e32 v17, 0xbfb8aa3b, v13
	v_mul_f32_e32 v18, 0xbfb8aa3b, v14
	v_mul_f32_e32 v19, 0xbfb8aa3b, v15
	v_exp_f32_e32 v16, v16
	v_exp_f32_e32 v17, v17
	v_exp_f32_e32 v18, v18
	v_exp_f32_e32 v19, v19
	v_lshlrev_b32_e32 v20, 16, v112
	v_and_b32_e32 v21, 0xffff0000, v112
	v_lshlrev_b32_e32 v22, 16, v113
	v_and_b32_e32 v23, 0xffff0000, v113
	v_add_f32_e32 v16, 1.0, v16
	v_add_f32_e32 v17, 1.0, v17
	v_add_f32_e32 v18, 1.0, v18
	v_add_f32_e32 v19, 1.0, v19
	v_rcp_f32_e32 v16, v16
	v_rcp_f32_e32 v17, v17
	v_rcp_f32_e32 v18, v18
	v_rcp_f32_e32 v19, v19
	v_sub_f32_e32 v20, v20, v227
	v_sub_f32_e32 v21, v21, v227
	v_sub_f32_e32 v22, v22, v227
	v_sub_f32_e32 v23, v23, v227
	v_mul_f32_e32 v20, v20, v228
	v_mul_f32_e32 v21, v21, v228
	v_mul_f32_e32 v22, v22, v228
	v_mul_f32_e32 v23, v23, v228
	v_mul_f32_e32 v12, v12, v16
	v_mul_f32_e32 v13, v13, v17
	v_mul_f32_e32 v14, v14, v18
	v_mul_f32_e32 v15, v15, v19
	v_mul_f32_e32 v20, v20, v92
	v_mul_f32_e32 v21, v21, v93
	v_mul_f32_e32 v22, v22, v94
	v_mul_f32_e32 v23, v23, v95
	v_mul_f32_e32 v20, v20, v12
	v_mul_f32_e32 v21, v21, v13
	v_mul_f32_e32 v22, v22, v14
	v_mul_f32_e32 v23, v23, v15
	v_cvt_pk_bf16_f32 v20, v20, v21
	v_cvt_pk_bf16_f32 v21, v22, v23
	global_store_dwordx2 v204, v[20:21], s[30:31] offset:704
	s_waitcnt vmcnt(7)
	v_lshlrev_b32_e32 v12, 16, v38
	v_and_b32_e32 v13, 0xffff0000, v38
	v_lshlrev_b32_e32 v14, 16, v39
	v_and_b32_e32 v15, 0xffff0000, v39
	v_mul_f32_e32 v16, 0xbfb8aa3b, v12
	v_mul_f32_e32 v17, 0xbfb8aa3b, v13
	v_mul_f32_e32 v18, 0xbfb8aa3b, v14
	v_mul_f32_e32 v19, 0xbfb8aa3b, v15
	v_exp_f32_e32 v16, v16
	v_exp_f32_e32 v17, v17
	v_exp_f32_e32 v18, v18
	v_exp_f32_e32 v19, v19
	v_lshlrev_b32_e32 v20, 16, v114
	v_and_b32_e32 v21, 0xffff0000, v114
	v_lshlrev_b32_e32 v22, 16, v115
	v_and_b32_e32 v23, 0xffff0000, v115
	v_add_f32_e32 v16, 1.0, v16
	v_add_f32_e32 v17, 1.0, v17
	v_add_f32_e32 v18, 1.0, v18
	v_add_f32_e32 v19, 1.0, v19
	v_rcp_f32_e32 v16, v16
	v_rcp_f32_e32 v17, v17
	v_rcp_f32_e32 v18, v18
	v_rcp_f32_e32 v19, v19
	v_sub_f32_e32 v20, v20, v227
	v_sub_f32_e32 v21, v21, v227
	v_sub_f32_e32 v22, v22, v227
	v_sub_f32_e32 v23, v23, v227
	v_mul_f32_e32 v20, v20, v228
	v_mul_f32_e32 v21, v21, v228
	v_mul_f32_e32 v22, v22, v228
	v_mul_f32_e32 v23, v23, v228
	v_mul_f32_e32 v12, v12, v16
	v_mul_f32_e32 v13, v13, v17
	v_mul_f32_e32 v14, v14, v18
	v_mul_f32_e32 v15, v15, v19
	v_mul_f32_e32 v20, v20, v96
	v_mul_f32_e32 v21, v21, v97
	v_mul_f32_e32 v22, v22, v98
	v_mul_f32_e32 v23, v23, v99
	v_mul_f32_e32 v20, v20, v12
	v_mul_f32_e32 v21, v21, v13
	v_mul_f32_e32 v22, v22, v14
	v_mul_f32_e32 v23, v23, v15
	v_cvt_pk_bf16_f32 v20, v20, v21
	v_cvt_pk_bf16_f32 v21, v22, v23
	global_store_dwordx2 v204, v[20:21], s[30:31] offset:736
	global_load_dwordx2 v[24:25], v205, s[34:35] offset:768
	global_load_dwordx2 v[100:101], v204, s[30:31] offset:768
	global_load_dwordx4 v[68:71], v206, s[28:29] offset:1536
	global_load_dwordx2 v[26:27], v205, s[34:35] offset:800
	global_load_dwordx2 v[102:103], v204, s[30:31] offset:800
	global_load_dwordx4 v[72:75], v206, s[28:29] offset:1600
	global_load_dwordx2 v[28:29], v205, s[34:35] offset:832
	global_load_dwordx2 v[104:105], v204, s[30:31] offset:832
	global_load_dwordx4 v[76:79], v206, s[28:29] offset:1664
	global_load_dwordx2 v[30:31], v205, s[34:35] offset:864
	global_load_dwordx2 v[106:107], v204, s[30:31] offset:864
	global_load_dwordx4 v[80:83], v206, s[28:29] offset:1728
	global_load_dwordx2 v[32:33], v205, s[34:35] offset:896
	global_load_dwordx2 v[108:109], v204, s[30:31] offset:896
	global_load_dwordx4 v[84:87], v206, s[28:29] offset:1792
	global_load_dwordx2 v[34:35], v205, s[34:35] offset:928
	global_load_dwordx2 v[110:111], v204, s[30:31] offset:928
	global_load_dwordx4 v[88:91], v206, s[28:29] offset:1856
	global_load_dwordx2 v[36:37], v205, s[34:35] offset:960
	global_load_dwordx2 v[112:113], v204, s[30:31] offset:960
	global_load_dwordx4 v[92:95], v206, s[28:29] offset:1920
	global_load_dwordx2 v[38:39], v205, s[34:35] offset:992
	global_load_dwordx2 v[114:115], v204, s[30:31] offset:992
	global_load_dwordx4 v[96:99], v206, s[28:29] offset:1984
	s_waitcnt vmcnt(21)
	v_lshlrev_b32_e32 v12, 16, v24
	v_and_b32_e32 v13, 0xffff0000, v24
	v_lshlrev_b32_e32 v14, 16, v25
	v_and_b32_e32 v15, 0xffff0000, v25
	v_mul_f32_e32 v16, 0xbfb8aa3b, v12
	v_mul_f32_e32 v17, 0xbfb8aa3b, v13
	v_mul_f32_e32 v18, 0xbfb8aa3b, v14
	v_mul_f32_e32 v19, 0xbfb8aa3b, v15
	v_exp_f32_e32 v16, v16
	v_exp_f32_e32 v17, v17
	v_exp_f32_e32 v18, v18
	v_exp_f32_e32 v19, v19
	v_lshlrev_b32_e32 v20, 16, v100
	v_and_b32_e32 v21, 0xffff0000, v100
	v_lshlrev_b32_e32 v22, 16, v101
	v_and_b32_e32 v23, 0xffff0000, v101
	v_add_f32_e32 v16, 1.0, v16
	v_add_f32_e32 v17, 1.0, v17
	v_add_f32_e32 v18, 1.0, v18
	v_add_f32_e32 v19, 1.0, v19
	v_rcp_f32_e32 v16, v16
	v_rcp_f32_e32 v17, v17
	v_rcp_f32_e32 v18, v18
	v_rcp_f32_e32 v19, v19
	v_sub_f32_e32 v20, v20, v227
	v_sub_f32_e32 v21, v21, v227
	v_sub_f32_e32 v22, v22, v227
	v_sub_f32_e32 v23, v23, v227
	v_mul_f32_e32 v20, v20, v228
	v_mul_f32_e32 v21, v21, v228
	v_mul_f32_e32 v22, v22, v228
	v_mul_f32_e32 v23, v23, v228
	v_mul_f32_e32 v12, v12, v16
	v_mul_f32_e32 v13, v13, v17
	v_mul_f32_e32 v14, v14, v18
	v_mul_f32_e32 v15, v15, v19
	v_mul_f32_e32 v20, v20, v68
	v_mul_f32_e32 v21, v21, v69
	v_mul_f32_e32 v22, v22, v70
	v_mul_f32_e32 v23, v23, v71
	v_mul_f32_e32 v20, v20, v12
	v_mul_f32_e32 v21, v21, v13
	v_mul_f32_e32 v22, v22, v14
	v_mul_f32_e32 v23, v23, v15
	v_cvt_pk_bf16_f32 v20, v20, v21
	v_cvt_pk_bf16_f32 v21, v22, v23
	global_store_dwordx2 v204, v[20:21], s[30:31] offset:768
	s_waitcnt vmcnt(19)
	v_lshlrev_b32_e32 v12, 16, v26
	v_and_b32_e32 v13, 0xffff0000, v26
	v_lshlrev_b32_e32 v14, 16, v27
	v_and_b32_e32 v15, 0xffff0000, v27
	v_mul_f32_e32 v16, 0xbfb8aa3b, v12
	v_mul_f32_e32 v17, 0xbfb8aa3b, v13
	v_mul_f32_e32 v18, 0xbfb8aa3b, v14
	v_mul_f32_e32 v19, 0xbfb8aa3b, v15
	v_exp_f32_e32 v16, v16
	v_exp_f32_e32 v17, v17
	v_exp_f32_e32 v18, v18
	v_exp_f32_e32 v19, v19
	v_lshlrev_b32_e32 v20, 16, v102
	v_and_b32_e32 v21, 0xffff0000, v102
	v_lshlrev_b32_e32 v22, 16, v103
	v_and_b32_e32 v23, 0xffff0000, v103
	v_add_f32_e32 v16, 1.0, v16
	v_add_f32_e32 v17, 1.0, v17
	v_add_f32_e32 v18, 1.0, v18
	v_add_f32_e32 v19, 1.0, v19
	v_rcp_f32_e32 v16, v16
	v_rcp_f32_e32 v17, v17
	v_rcp_f32_e32 v18, v18
	v_rcp_f32_e32 v19, v19
	v_sub_f32_e32 v20, v20, v227
	v_sub_f32_e32 v21, v21, v227
	v_sub_f32_e32 v22, v22, v227
	v_sub_f32_e32 v23, v23, v227
	v_mul_f32_e32 v20, v20, v228
	v_mul_f32_e32 v21, v21, v228
	v_mul_f32_e32 v22, v22, v228
	v_mul_f32_e32 v23, v23, v228
	v_mul_f32_e32 v12, v12, v16
	v_mul_f32_e32 v13, v13, v17
	v_mul_f32_e32 v14, v14, v18
	v_mul_f32_e32 v15, v15, v19
	v_mul_f32_e32 v20, v20, v72
	v_mul_f32_e32 v21, v21, v73
	v_mul_f32_e32 v22, v22, v74
	v_mul_f32_e32 v23, v23, v75
	v_mul_f32_e32 v20, v20, v12
	v_mul_f32_e32 v21, v21, v13
	v_mul_f32_e32 v22, v22, v14
	v_mul_f32_e32 v23, v23, v15
	v_cvt_pk_bf16_f32 v20, v20, v21
	v_cvt_pk_bf16_f32 v21, v22, v23
	global_store_dwordx2 v204, v[20:21], s[30:31] offset:800
	s_waitcnt vmcnt(17)
	v_lshlrev_b32_e32 v12, 16, v28
	v_and_b32_e32 v13, 0xffff0000, v28
	v_lshlrev_b32_e32 v14, 16, v29
	v_and_b32_e32 v15, 0xffff0000, v29
	v_mul_f32_e32 v16, 0xbfb8aa3b, v12
	v_mul_f32_e32 v17, 0xbfb8aa3b, v13
	v_mul_f32_e32 v18, 0xbfb8aa3b, v14
	v_mul_f32_e32 v19, 0xbfb8aa3b, v15
	v_exp_f32_e32 v16, v16
	v_exp_f32_e32 v17, v17
	v_exp_f32_e32 v18, v18
	v_exp_f32_e32 v19, v19
	v_lshlrev_b32_e32 v20, 16, v104
	v_and_b32_e32 v21, 0xffff0000, v104
	v_lshlrev_b32_e32 v22, 16, v105
	v_and_b32_e32 v23, 0xffff0000, v105
	v_add_f32_e32 v16, 1.0, v16
	v_add_f32_e32 v17, 1.0, v17
	v_add_f32_e32 v18, 1.0, v18
	v_add_f32_e32 v19, 1.0, v19
	v_rcp_f32_e32 v16, v16
	v_rcp_f32_e32 v17, v17
	v_rcp_f32_e32 v18, v18
	v_rcp_f32_e32 v19, v19
	v_sub_f32_e32 v20, v20, v227
	v_sub_f32_e32 v21, v21, v227
	v_sub_f32_e32 v22, v22, v227
	v_sub_f32_e32 v23, v23, v227
	v_mul_f32_e32 v20, v20, v228
	v_mul_f32_e32 v21, v21, v228
	v_mul_f32_e32 v22, v22, v228
	v_mul_f32_e32 v23, v23, v228
	v_mul_f32_e32 v12, v12, v16
	v_mul_f32_e32 v13, v13, v17
	v_mul_f32_e32 v14, v14, v18
	v_mul_f32_e32 v15, v15, v19
	v_mul_f32_e32 v20, v20, v76
	v_mul_f32_e32 v21, v21, v77
	v_mul_f32_e32 v22, v22, v78
	v_mul_f32_e32 v23, v23, v79
	v_mul_f32_e32 v20, v20, v12
	v_mul_f32_e32 v21, v21, v13
	v_mul_f32_e32 v22, v22, v14
	v_mul_f32_e32 v23, v23, v15
	v_cvt_pk_bf16_f32 v20, v20, v21
	v_cvt_pk_bf16_f32 v21, v22, v23
	global_store_dwordx2 v204, v[20:21], s[30:31] offset:832
	s_waitcnt vmcnt(15)
	v_lshlrev_b32_e32 v12, 16, v30
	v_and_b32_e32 v13, 0xffff0000, v30
	v_lshlrev_b32_e32 v14, 16, v31
	v_and_b32_e32 v15, 0xffff0000, v31
	v_mul_f32_e32 v16, 0xbfb8aa3b, v12
	v_mul_f32_e32 v17, 0xbfb8aa3b, v13
	v_mul_f32_e32 v18, 0xbfb8aa3b, v14
	v_mul_f32_e32 v19, 0xbfb8aa3b, v15
	v_exp_f32_e32 v16, v16
	v_exp_f32_e32 v17, v17
	v_exp_f32_e32 v18, v18
	v_exp_f32_e32 v19, v19
	v_lshlrev_b32_e32 v20, 16, v106
	v_and_b32_e32 v21, 0xffff0000, v106
	v_lshlrev_b32_e32 v22, 16, v107
	v_and_b32_e32 v23, 0xffff0000, v107
	v_add_f32_e32 v16, 1.0, v16
	v_add_f32_e32 v17, 1.0, v17
	v_add_f32_e32 v18, 1.0, v18
	v_add_f32_e32 v19, 1.0, v19
	v_rcp_f32_e32 v16, v16
	v_rcp_f32_e32 v17, v17
	v_rcp_f32_e32 v18, v18
	v_rcp_f32_e32 v19, v19
	v_sub_f32_e32 v20, v20, v227
	v_sub_f32_e32 v21, v21, v227
	v_sub_f32_e32 v22, v22, v227
	v_sub_f32_e32 v23, v23, v227
	v_mul_f32_e32 v20, v20, v228
	v_mul_f32_e32 v21, v21, v228
	v_mul_f32_e32 v22, v22, v228
	v_mul_f32_e32 v23, v23, v228
	v_mul_f32_e32 v12, v12, v16
	v_mul_f32_e32 v13, v13, v17
	v_mul_f32_e32 v14, v14, v18
	v_mul_f32_e32 v15, v15, v19
	v_mul_f32_e32 v20, v20, v80
	v_mul_f32_e32 v21, v21, v81
	v_mul_f32_e32 v22, v22, v82
	v_mul_f32_e32 v23, v23, v83
	v_mul_f32_e32 v20, v20, v12
	v_mul_f32_e32 v21, v21, v13
	v_mul_f32_e32 v22, v22, v14
	v_mul_f32_e32 v23, v23, v15
	v_cvt_pk_bf16_f32 v20, v20, v21
	v_cvt_pk_bf16_f32 v21, v22, v23
	global_store_dwordx2 v204, v[20:21], s[30:31] offset:864
	s_waitcnt vmcnt(13)
	v_lshlrev_b32_e32 v12, 16, v32
	v_and_b32_e32 v13, 0xffff0000, v32
	v_lshlrev_b32_e32 v14, 16, v33
	v_and_b32_e32 v15, 0xffff0000, v33
	v_mul_f32_e32 v16, 0xbfb8aa3b, v12
	v_mul_f32_e32 v17, 0xbfb8aa3b, v13
	v_mul_f32_e32 v18, 0xbfb8aa3b, v14
	v_mul_f32_e32 v19, 0xbfb8aa3b, v15
	v_exp_f32_e32 v16, v16
	v_exp_f32_e32 v17, v17
	v_exp_f32_e32 v18, v18
	v_exp_f32_e32 v19, v19
	v_lshlrev_b32_e32 v20, 16, v108
	v_and_b32_e32 v21, 0xffff0000, v108
	v_lshlrev_b32_e32 v22, 16, v109
	v_and_b32_e32 v23, 0xffff0000, v109
	v_add_f32_e32 v16, 1.0, v16
	v_add_f32_e32 v17, 1.0, v17
	v_add_f32_e32 v18, 1.0, v18
	v_add_f32_e32 v19, 1.0, v19
	v_rcp_f32_e32 v16, v16
	v_rcp_f32_e32 v17, v17
	v_rcp_f32_e32 v18, v18
	v_rcp_f32_e32 v19, v19
	v_sub_f32_e32 v20, v20, v227
	v_sub_f32_e32 v21, v21, v227
	v_sub_f32_e32 v22, v22, v227
	v_sub_f32_e32 v23, v23, v227
	v_mul_f32_e32 v20, v20, v228
	v_mul_f32_e32 v21, v21, v228
	v_mul_f32_e32 v22, v22, v228
	v_mul_f32_e32 v23, v23, v228
	v_mul_f32_e32 v12, v12, v16
	v_mul_f32_e32 v13, v13, v17
	v_mul_f32_e32 v14, v14, v18
	v_mul_f32_e32 v15, v15, v19
	v_mul_f32_e32 v20, v20, v84
	v_mul_f32_e32 v21, v21, v85
	v_mul_f32_e32 v22, v22, v86
	v_mul_f32_e32 v23, v23, v87
	v_mul_f32_e32 v20, v20, v12
	v_mul_f32_e32 v21, v21, v13
	v_mul_f32_e32 v22, v22, v14
	v_mul_f32_e32 v23, v23, v15
	v_cvt_pk_bf16_f32 v20, v20, v21
	v_cvt_pk_bf16_f32 v21, v22, v23
	global_store_dwordx2 v204, v[20:21], s[30:31] offset:896
	s_waitcnt vmcnt(11)
	v_lshlrev_b32_e32 v12, 16, v34
	v_and_b32_e32 v13, 0xffff0000, v34
	v_lshlrev_b32_e32 v14, 16, v35
	v_and_b32_e32 v15, 0xffff0000, v35
	v_mul_f32_e32 v16, 0xbfb8aa3b, v12
	v_mul_f32_e32 v17, 0xbfb8aa3b, v13
	v_mul_f32_e32 v18, 0xbfb8aa3b, v14
	v_mul_f32_e32 v19, 0xbfb8aa3b, v15
	v_exp_f32_e32 v16, v16
	v_exp_f32_e32 v17, v17
	v_exp_f32_e32 v18, v18
	v_exp_f32_e32 v19, v19
	v_lshlrev_b32_e32 v20, 16, v110
	v_and_b32_e32 v21, 0xffff0000, v110
	v_lshlrev_b32_e32 v22, 16, v111
	v_and_b32_e32 v23, 0xffff0000, v111
	v_add_f32_e32 v16, 1.0, v16
	v_add_f32_e32 v17, 1.0, v17
	v_add_f32_e32 v18, 1.0, v18
	v_add_f32_e32 v19, 1.0, v19
	v_rcp_f32_e32 v16, v16
	v_rcp_f32_e32 v17, v17
	v_rcp_f32_e32 v18, v18
	v_rcp_f32_e32 v19, v19
	v_sub_f32_e32 v20, v20, v227
	v_sub_f32_e32 v21, v21, v227
	v_sub_f32_e32 v22, v22, v227
	v_sub_f32_e32 v23, v23, v227
	v_mul_f32_e32 v20, v20, v228
	v_mul_f32_e32 v21, v21, v228
	v_mul_f32_e32 v22, v22, v228
	v_mul_f32_e32 v23, v23, v228
	v_mul_f32_e32 v12, v12, v16
	v_mul_f32_e32 v13, v13, v17
	v_mul_f32_e32 v14, v14, v18
	v_mul_f32_e32 v15, v15, v19
	v_mul_f32_e32 v20, v20, v88
	v_mul_f32_e32 v21, v21, v89
	v_mul_f32_e32 v22, v22, v90
	v_mul_f32_e32 v23, v23, v91
	v_mul_f32_e32 v20, v20, v12
	v_mul_f32_e32 v21, v21, v13
	v_mul_f32_e32 v22, v22, v14
	v_mul_f32_e32 v23, v23, v15
	v_cvt_pk_bf16_f32 v20, v20, v21
	v_cvt_pk_bf16_f32 v21, v22, v23
	global_store_dwordx2 v204, v[20:21], s[30:31] offset:928
	s_waitcnt vmcnt(9)
	v_lshlrev_b32_e32 v12, 16, v36
	v_and_b32_e32 v13, 0xffff0000, v36
	v_lshlrev_b32_e32 v14, 16, v37
	v_and_b32_e32 v15, 0xffff0000, v37
	v_mul_f32_e32 v16, 0xbfb8aa3b, v12
	v_mul_f32_e32 v17, 0xbfb8aa3b, v13
	v_mul_f32_e32 v18, 0xbfb8aa3b, v14
	v_mul_f32_e32 v19, 0xbfb8aa3b, v15
	v_exp_f32_e32 v16, v16
	v_exp_f32_e32 v17, v17
	v_exp_f32_e32 v18, v18
	v_exp_f32_e32 v19, v19
	v_lshlrev_b32_e32 v20, 16, v112
	v_and_b32_e32 v21, 0xffff0000, v112
	v_lshlrev_b32_e32 v22, 16, v113
	v_and_b32_e32 v23, 0xffff0000, v113
	v_add_f32_e32 v16, 1.0, v16
	v_add_f32_e32 v17, 1.0, v17
	v_add_f32_e32 v18, 1.0, v18
	v_add_f32_e32 v19, 1.0, v19
	v_rcp_f32_e32 v16, v16
	v_rcp_f32_e32 v17, v17
	v_rcp_f32_e32 v18, v18
	v_rcp_f32_e32 v19, v19
	v_sub_f32_e32 v20, v20, v227
	v_sub_f32_e32 v21, v21, v227
	v_sub_f32_e32 v22, v22, v227
	v_sub_f32_e32 v23, v23, v227
	v_mul_f32_e32 v20, v20, v228
	v_mul_f32_e32 v21, v21, v228
	v_mul_f32_e32 v22, v22, v228
	v_mul_f32_e32 v23, v23, v228
	v_mul_f32_e32 v12, v12, v16
	v_mul_f32_e32 v13, v13, v17
	v_mul_f32_e32 v14, v14, v18
	v_mul_f32_e32 v15, v15, v19
	v_mul_f32_e32 v20, v20, v92
	v_mul_f32_e32 v21, v21, v93
	v_mul_f32_e32 v22, v22, v94
	v_mul_f32_e32 v23, v23, v95
	v_mul_f32_e32 v20, v20, v12
	v_mul_f32_e32 v21, v21, v13
	v_mul_f32_e32 v22, v22, v14
	v_mul_f32_e32 v23, v23, v15
	v_cvt_pk_bf16_f32 v20, v20, v21
	v_cvt_pk_bf16_f32 v21, v22, v23
	global_store_dwordx2 v204, v[20:21], s[30:31] offset:960
	s_waitcnt vmcnt(7)
	v_lshlrev_b32_e32 v12, 16, v38
	v_and_b32_e32 v13, 0xffff0000, v38
	v_lshlrev_b32_e32 v14, 16, v39
	v_and_b32_e32 v15, 0xffff0000, v39
	v_mul_f32_e32 v16, 0xbfb8aa3b, v12
	v_mul_f32_e32 v17, 0xbfb8aa3b, v13
	v_mul_f32_e32 v18, 0xbfb8aa3b, v14
	v_mul_f32_e32 v19, 0xbfb8aa3b, v15
	v_exp_f32_e32 v16, v16
	v_exp_f32_e32 v17, v17
	v_exp_f32_e32 v18, v18
	v_exp_f32_e32 v19, v19
	v_lshlrev_b32_e32 v20, 16, v114
	v_and_b32_e32 v21, 0xffff0000, v114
	v_lshlrev_b32_e32 v22, 16, v115
	v_and_b32_e32 v23, 0xffff0000, v115
	v_add_f32_e32 v16, 1.0, v16
	v_add_f32_e32 v17, 1.0, v17
	v_add_f32_e32 v18, 1.0, v18
	v_add_f32_e32 v19, 1.0, v19
	v_rcp_f32_e32 v16, v16
	v_rcp_f32_e32 v17, v17
	v_rcp_f32_e32 v18, v18
	v_rcp_f32_e32 v19, v19
	v_sub_f32_e32 v20, v20, v227
	v_sub_f32_e32 v21, v21, v227
	v_sub_f32_e32 v22, v22, v227
	v_sub_f32_e32 v23, v23, v227
	v_mul_f32_e32 v20, v20, v228
	v_mul_f32_e32 v21, v21, v228
	v_mul_f32_e32 v22, v22, v228
	v_mul_f32_e32 v23, v23, v228
	v_mul_f32_e32 v12, v12, v16
	v_mul_f32_e32 v13, v13, v17
	v_mul_f32_e32 v14, v14, v18
	v_mul_f32_e32 v15, v15, v19
	v_mul_f32_e32 v20, v20, v96
	v_mul_f32_e32 v21, v21, v97
	v_mul_f32_e32 v22, v22, v98
	v_mul_f32_e32 v23, v23, v99
	v_mul_f32_e32 v20, v20, v12
	v_mul_f32_e32 v21, v21, v13
	v_mul_f32_e32 v22, v22, v14
	v_mul_f32_e32 v23, v23, v15
	v_cvt_pk_bf16_f32 v20, v20, v21
	v_cvt_pk_bf16_f32 v21, v22, v23
	global_store_dwordx2 v204, v[20:21], s[30:31] offset:992
	s_waitcnt vmcnt(0)
	s_add_i32 s6, s6, 1
	s_cmp_lt_i32 s6, 2
	s_cbranch_scc1 .Lintra_unit
	s_branch .LBB0_748
.Lintra_orig:
	s_load_dwordx2 s[0:1], s[0:1], 0x48
	v_and_b32_e32 v149, 15, v0
	v_readlane_b32 s2, v254, 39
	v_lshlrev_b32_e32 v64, 6, v149
	v_and_b32_e32 v4, 63, v0
	v_bfe_u32 v5, v0, 4, 2
	v_readlane_b32 s3, v254, 40
	s_waitcnt lgkmcnt(0)
	s_add_u32 s0, s0, s2
	v_lshl_add_u64 v[2:3], s[26:27], 0, v[64:65]
	v_and_b32_e32 v0, 48, v0
	v_mov_b32_e32 v1, v65
	s_addc_u32 s1, s1, s3
	v_lshl_add_u64 v[2:3], v[2:3], 0, v[0:1]
	s_mov_b64 s[2:3], 0xcd00000
	v_lshl_add_u64 v[132:133], v[2:3], 0, s[2:3]
	s_mov_b64 s[2:3], 0xed00000
	v_lshlrev_b32_e32 v130, 3, v5
	v_mov_b32_e32 v131, v65
	v_lshl_add_u64 v[134:135], v[2:3], 0, s[2:3]
	v_lshlrev_b32_e32 v2, 2, v4
	v_xor_b32_e32 v222, 64, v2
	v_xor_b32_e32 v223, 0x80, v2
	v_lshl_add_u64 v[2:3], s[26:27], 0, v[130:131]
	s_mov_b64 s[2:3], 0x16d00000
	v_lshl_add_u64 v[138:139], v[2:3], 0, s[2:3]
	v_readlane_b32 s3, v254, 47
	v_sub_u32_e32 v143, 15, v220
	v_lshlrev_b32_e32 v221, 2, v5
	v_lshl_add_u64 v[136:137], s[24:25], 0, v[130:131]
	v_lshl_add_u64 v[140:141], s[0:1], 0, v[0:1]
	v_or_b32_e32 v148, v64, v0
	s_lshl_b32 s2, s3, 4
	s_branch .LBB0_702

.LBB0_703:
	ds_bpermute_b32 v1, v222, v177
	ds_bpermute_b32 v0, v222, v176
	v_mad_i64_i32 v[4:5], s[0:1], v164, s94, v[154:155]
	s_mov_b32 s0, 0x3b000000
	s_waitcnt lgkmcnt(0)
	v_pk_add_f32 v[0:1], v[176:177], v[0:1]
	ds_bpermute_b32 v3, v223, v1
	ds_bpermute_b32 v2, v223, v0
	s_waitcnt lgkmcnt(0)
	v_pk_add_f32 v[0:1], v[0:1], v[2:3]
	s_nop 0
	v_pk_mul_f32 v[6:7], v[0:1], s[0:1] op_sel_hi:[1,0]
	s_nop 0
	v_fma_f32 v0, -v7, v7, v6
	v_cmp_ngt_f32_e32 vcc, 0, v0
	s_nop 1
	v_cndmask_b32_e32 v0, 0, v0, vcc
	v_add_f32_e32 v0, 0x3727c5ac, v0
	v_cmp_gt_f32_e32 vcc, s96, v0
	v_mul_f32_e32 v1, 0x4b800000, v0
	s_nop 0
	v_cndmask_b32_e32 v0, v0, v1, vcc
	v_rsq_f32_e32 v0, v0
	s_nop 0
	v_mul_f32_e32 v1, 0x45800000, v0
	v_cndmask_b32_e32 v8, v0, v1, vcc
	v_lshlrev_b64 v[0:1], 12, v[164:165]
	v_lshl_add_u64 v[10:11], v[156:157], 0, v[0:1]
	global_load_dwordx2 v[24:25], v[10:11], off offset:0
	global_load_dwordx2 v[40:41], v[4:5], off offset:0
	global_load_dwordx4 v[68:71], v[158:159], off offset:0
	global_load_dwordx2 v[26:27], v[10:11], off offset:32
	global_load_dwordx2 v[42:43], v[4:5], off offset:32
	global_load_dwordx4 v[72:75], v[158:159], off offset:64
	global_load_dwordx2 v[28:29], v[10:11], off offset:64
	global_load_dwordx2 v[44:45], v[4:5], off offset:64
	global_load_dwordx4 v[76:79], v[158:159], off offset:128
	global_load_dwordx2 v[30:31], v[10:11], off offset:96
	global_load_dwordx2 v[46:47], v[4:5], off offset:96
	global_load_dwordx4 v[80:83], v[158:159], off offset:192
	global_load_dwordx2 v[32:33], v[10:11], off offset:128
	global_load_dwordx2 v[48:49], v[4:5], off offset:128
	global_load_dwordx4 v[84:87], v[158:159], off offset:256
	global_load_dwordx2 v[34:35], v[10:11], off offset:160
	global_load_dwordx2 v[50:51], v[4:5], off offset:160
	global_load_dwordx4 v[88:91], v[158:159], off offset:320
	global_load_dwordx2 v[36:37], v[10:11], off offset:192
	global_load_dwordx2 v[52:53], v[4:5], off offset:192
	global_load_dwordx4 v[92:95], v[158:159], off offset:384
	global_load_dwordx2 v[38:39], v[10:11], off offset:224
	global_load_dwordx2 v[54:55], v[4:5], off offset:224
	global_load_dwordx4 v[96:99], v[158:159], off offset:448
	s_waitcnt vmcnt(21)
	v_lshlrev_b32_e32 v12, 16, v24
	v_and_b32_e32 v13, 0xffff0000, v24
	v_lshlrev_b32_e32 v14, 16, v25
	v_and_b32_e32 v15, 0xffff0000, v25
	v_mul_f32_e32 v16, 0xbfb8aa3b, v12
	v_mul_f32_e32 v17, 0xbfb8aa3b, v13
	v_mul_f32_e32 v18, 0xbfb8aa3b, v14
	v_mul_f32_e32 v19, 0xbfb8aa3b, v15
	v_exp_f32_e32 v16, v16
	v_exp_f32_e32 v17, v17
	v_exp_f32_e32 v18, v18
	v_exp_f32_e32 v19, v19
	v_lshlrev_b32_e32 v20, 16, v40
	v_and_b32_e32 v21, 0xffff0000, v40
	v_lshlrev_b32_e32 v22, 16, v41
	v_and_b32_e32 v23, 0xffff0000, v41
	v_add_f32_e32 v16, 1.0, v16
	v_add_f32_e32 v17, 1.0, v17
	v_add_f32_e32 v18, 1.0, v18
	v_add_f32_e32 v19, 1.0, v19
	v_rcp_f32_e32 v16, v16
	v_rcp_f32_e32 v17, v17
	v_rcp_f32_e32 v18, v18
	v_rcp_f32_e32 v19, v19
	v_sub_f32_e32 v20, v20, v7
	v_sub_f32_e32 v21, v21, v7
	v_sub_f32_e32 v22, v22, v7
	v_sub_f32_e32 v23, v23, v7
	v_mul_f32_e32 v20, v20, v8
	v_mul_f32_e32 v21, v21, v8
	v_mul_f32_e32 v22, v22, v8
	v_mul_f32_e32 v23, v23, v8
	v_mul_f32_e32 v12, v12, v16
	v_mul_f32_e32 v13, v13, v17
	v_mul_f32_e32 v14, v14, v18
	v_mul_f32_e32 v15, v15, v19
	v_mul_f32_e32 v20, v20, v68
	v_mul_f32_e32 v21, v21, v69
	v_mul_f32_e32 v22, v22, v70
	v_mul_f32_e32 v23, v23, v71
	v_mul_f32_e32 v20, v20, v12
	v_mul_f32_e32 v21, v21, v13
	v_mul_f32_e32 v22, v22, v14
	v_mul_f32_e32 v23, v23, v15
	v_cvt_pk_bf16_f32 v20, v20, v21
	v_cvt_pk_bf16_f32 v21, v22, v23
	global_store_dwordx2 v[4:5], v[20:21], off offset:0
	s_waitcnt vmcnt(19)
	v_lshlrev_b32_e32 v12, 16, v26
	v_and_b32_e32 v13, 0xffff0000, v26
	v_lshlrev_b32_e32 v14, 16, v27
	v_and_b32_e32 v15, 0xffff0000, v27
	v_mul_f32_e32 v16, 0xbfb8aa3b, v12
	v_mul_f32_e32 v17, 0xbfb8aa3b, v13
	v_mul_f32_e32 v18, 0xbfb8aa3b, v14
	v_mul_f32_e32 v19, 0xbfb8aa3b, v15
	v_exp_f32_e32 v16, v16
	v_exp_f32_e32 v17, v17
	v_exp_f32_e32 v18, v18
	v_exp_f32_e32 v19, v19
	v_lshlrev_b32_e32 v20, 16, v42
	v_and_b32_e32 v21, 0xffff0000, v42
	v_lshlrev_b32_e32 v22, 16, v43
	v_and_b32_e32 v23, 0xffff0000, v43
	v_add_f32_e32 v16, 1.0, v16
	v_add_f32_e32 v17, 1.0, v17
	v_add_f32_e32 v18, 1.0, v18
	v_add_f32_e32 v19, 1.0, v19
	v_rcp_f32_e32 v16, v16
	v_rcp_f32_e32 v17, v17
	v_rcp_f32_e32 v18, v18
	v_rcp_f32_e32 v19, v19
	v_sub_f32_e32 v20, v20, v7
	v_sub_f32_e32 v21, v21, v7
	v_sub_f32_e32 v22, v22, v7
	v_sub_f32_e32 v23, v23, v7
	v_mul_f32_e32 v20, v20, v8
	v_mul_f32_e32 v21, v21, v8
	v_mul_f32_e32 v22, v22, v8
	v_mul_f32_e32 v23, v23, v8
	v_mul_f32_e32 v12, v12, v16
	v_mul_f32_e32 v13, v13, v17
	v_mul_f32_e32 v14, v14, v18
	v_mul_f32_e32 v15, v15, v19
	v_mul_f32_e32 v20, v20, v72
	v_mul_f32_e32 v21, v21, v73
	v_mul_f32_e32 v22, v22, v74
	v_mul_f32_e32 v23, v23, v75
	v_mul_f32_e32 v20, v20, v12
	v_mul_f32_e32 v21, v21, v13
	v_mul_f32_e32 v22, v22, v14
	v_mul_f32_e32 v23, v23, v15
	v_cvt_pk_bf16_f32 v20, v20, v21
	v_cvt_pk_bf16_f32 v21, v22, v23
	global_store_dwordx2 v[4:5], v[20:21], off offset:32
	s_waitcnt vmcnt(17)
	v_lshlrev_b32_e32 v12, 16, v28
	v_and_b32_e32 v13, 0xffff0000, v28
	v_lshlrev_b32_e32 v14, 16, v29
	v_and_b32_e32 v15, 0xffff0000, v29
	v_mul_f32_e32 v16, 0xbfb8aa3b, v12
	v_mul_f32_e32 v17, 0xbfb8aa3b, v13
	v_mul_f32_e32 v18, 0xbfb8aa3b, v14
	v_mul_f32_e32 v19, 0xbfb8aa3b, v15
	v_exp_f32_e32 v16, v16
	v_exp_f32_e32 v17, v17
	v_exp_f32_e32 v18, v18
	v_exp_f32_e32 v19, v19
	v_lshlrev_b32_e32 v20, 16, v44
	v_and_b32_e32 v21, 0xffff0000, v44
	v_lshlrev_b32_e32 v22, 16, v45
	v_and_b32_e32 v23, 0xffff0000, v45
	v_add_f32_e32 v16, 1.0, v16
	v_add_f32_e32 v17, 1.0, v17
	v_add_f32_e32 v18, 1.0, v18
	v_add_f32_e32 v19, 1.0, v19
	v_rcp_f32_e32 v16, v16
	v_rcp_f32_e32 v17, v17
	v_rcp_f32_e32 v18, v18
	v_rcp_f32_e32 v19, v19
	v_sub_f32_e32 v20, v20, v7
	v_sub_f32_e32 v21, v21, v7
	v_sub_f32_e32 v22, v22, v7
	v_sub_f32_e32 v23, v23, v7
	v_mul_f32_e32 v20, v20, v8
	v_mul_f32_e32 v21, v21, v8
	v_mul_f32_e32 v22, v22, v8
	v_mul_f32_e32 v23, v23, v8
	v_mul_f32_e32 v12, v12, v16
	v_mul_f32_e32 v13, v13, v17
	v_mul_f32_e32 v14, v14, v18
	v_mul_f32_e32 v15, v15, v19
	v_mul_f32_e32 v20, v20, v76
	v_mul_f32_e32 v21, v21, v77
	v_mul_f32_e32 v22, v22, v78
	v_mul_f32_e32 v23, v23, v79
	v_mul_f32_e32 v20, v20, v12
	v_mul_f32_e32 v21, v21, v13
	v_mul_f32_e32 v22, v22, v14
	v_mul_f32_e32 v23, v23, v15
	v_cvt_pk_bf16_f32 v20, v20, v21
	v_cvt_pk_bf16_f32 v21, v22, v23
	global_store_dwordx2 v[4:5], v[20:21], off offset:64
	s_waitcnt vmcnt(15)
	v_lshlrev_b32_e32 v12, 16, v30
	v_and_b32_e32 v13, 0xffff0000, v30
	v_lshlrev_b32_e32 v14, 16, v31
	v_and_b32_e32 v15, 0xffff0000, v31
	v_mul_f32_e32 v16, 0xbfb8aa3b, v12
	v_mul_f32_e32 v17, 0xbfb8aa3b, v13
	v_mul_f32_e32 v18, 0xbfb8aa3b, v14
	v_mul_f32_e32 v19, 0xbfb8aa3b, v15
	v_exp_f32_e32 v16, v16
	v_exp_f32_e32 v17, v17
	v_exp_f32_e32 v18, v18
	v_exp_f32_e32 v19, v19
	v_lshlrev_b32_e32 v20, 16, v46
	v_and_b32_e32 v21, 0xffff0000, v46
	v_lshlrev_b32_e32 v22, 16, v47
	v_and_b32_e32 v23, 0xffff0000, v47
	v_add_f32_e32 v16, 1.0, v16
	v_add_f32_e32 v17, 1.0, v17
	v_add_f32_e32 v18, 1.0, v18
	v_add_f32_e32 v19, 1.0, v19
	v_rcp_f32_e32 v16, v16
	v_rcp_f32_e32 v17, v17
	v_rcp_f32_e32 v18, v18
	v_rcp_f32_e32 v19, v19
	v_sub_f32_e32 v20, v20, v7
	v_sub_f32_e32 v21, v21, v7
	v_sub_f32_e32 v22, v22, v7
	v_sub_f32_e32 v23, v23, v7
	v_mul_f32_e32 v20, v20, v8
	v_mul_f32_e32 v21, v21, v8
	v_mul_f32_e32 v22, v22, v8
	v_mul_f32_e32 v23, v23, v8
	v_mul_f32_e32 v12, v12, v16
	v_mul_f32_e32 v13, v13, v17
	v_mul_f32_e32 v14, v14, v18
	v_mul_f32_e32 v15, v15, v19
	v_mul_f32_e32 v20, v20, v80
	v_mul_f32_e32 v21, v21, v81
	v_mul_f32_e32 v22, v22, v82
	v_mul_f32_e32 v23, v23, v83
	v_mul_f32_e32 v20, v20, v12
	v_mul_f32_e32 v21, v21, v13
	v_mul_f32_e32 v22, v22, v14
	v_mul_f32_e32 v23, v23, v15
	v_cvt_pk_bf16_f32 v20, v20, v21
	v_cvt_pk_bf16_f32 v21, v22, v23
	global_store_dwordx2 v[4:5], v[20:21], off offset:96
	s_waitcnt vmcnt(13)
	v_lshlrev_b32_e32 v12, 16, v32
	v_and_b32_e32 v13, 0xffff0000, v32
	v_lshlrev_b32_e32 v14, 16, v33
	v_and_b32_e32 v15, 0xffff0000, v33
	v_mul_f32_e32 v16, 0xbfb8aa3b, v12
	v_mul_f32_e32 v17, 0xbfb8aa3b, v13
	v_mul_f32_e32 v18, 0xbfb8aa3b, v14
	v_mul_f32_e32 v19, 0xbfb8aa3b, v15
	v_exp_f32_e32 v16, v16
	v_exp_f32_e32 v17, v17
	v_exp_f32_e32 v18, v18
	v_exp_f32_e32 v19, v19
	v_lshlrev_b32_e32 v20, 16, v48
	v_and_b32_e32 v21, 0xffff0000, v48
	v_lshlrev_b32_e32 v22, 16, v49
	v_and_b32_e32 v23, 0xffff0000, v49
	v_add_f32_e32 v16, 1.0, v16
	v_add_f32_e32 v17, 1.0, v17
	v_add_f32_e32 v18, 1.0, v18
	v_add_f32_e32 v19, 1.0, v19
	v_rcp_f32_e32 v16, v16
	v_rcp_f32_e32 v17, v17
	v_rcp_f32_e32 v18, v18
	v_rcp_f32_e32 v19, v19
	v_sub_f32_e32 v20, v20, v7
	v_sub_f32_e32 v21, v21, v7
	v_sub_f32_e32 v22, v22, v7
	v_sub_f32_e32 v23, v23, v7
	v_mul_f32_e32 v20, v20, v8
	v_mul_f32_e32 v21, v21, v8
	v_mul_f32_e32 v22, v22, v8
	v_mul_f32_e32 v23, v23, v8
	v_mul_f32_e32 v12, v12, v16
	v_mul_f32_e32 v13, v13, v17
	v_mul_f32_e32 v14, v14, v18
	v_mul_f32_e32 v15, v15, v19
	v_mul_f32_e32 v20, v20, v84
	v_mul_f32_e32 v21, v21, v85
	v_mul_f32_e32 v22, v22, v86
	v_mul_f32_e32 v23, v23, v87
	v_mul_f32_e32 v20, v20, v12
	v_mul_f32_e32 v21, v21, v13
	v_mul_f32_e32 v22, v22, v14
	v_mul_f32_e32 v23, v23, v15
	v_cvt_pk_bf16_f32 v20, v20, v21
	v_cvt_pk_bf16_f32 v21, v22, v23
	global_store_dwordx2 v[4:5], v[20:21], off offset:128
	s_waitcnt vmcnt(11)
	v_lshlrev_b32_e32 v12, 16, v34
	v_and_b32_e32 v13, 0xffff0000, v34
	v_lshlrev_b32_e32 v14, 16, v35
	v_and_b32_e32 v15, 0xffff0000, v35
	v_mul_f32_e32 v16, 0xbfb8aa3b, v12
	v_mul_f32_e32 v17, 0xbfb8aa3b, v13
	v_mul_f32_e32 v18, 0xbfb8aa3b, v14
	v_mul_f32_e32 v19, 0xbfb8aa3b, v15
	v_exp_f32_e32 v16, v16
	v_exp_f32_e32 v17, v17
	v_exp_f32_e32 v18, v18
	v_exp_f32_e32 v19, v19
	v_lshlrev_b32_e32 v20, 16, v50
	v_and_b32_e32 v21, 0xffff0000, v50
	v_lshlrev_b32_e32 v22, 16, v51
	v_and_b32_e32 v23, 0xffff0000, v51
	v_add_f32_e32 v16, 1.0, v16
	v_add_f32_e32 v17, 1.0, v17
	v_add_f32_e32 v18, 1.0, v18
	v_add_f32_e32 v19, 1.0, v19
	v_rcp_f32_e32 v16, v16
	v_rcp_f32_e32 v17, v17
	v_rcp_f32_e32 v18, v18
	v_rcp_f32_e32 v19, v19
	v_sub_f32_e32 v20, v20, v7
	v_sub_f32_e32 v21, v21, v7
	v_sub_f32_e32 v22, v22, v7
	v_sub_f32_e32 v23, v23, v7
	v_mul_f32_e32 v20, v20, v8
	v_mul_f32_e32 v21, v21, v8
	v_mul_f32_e32 v22, v22, v8
	v_mul_f32_e32 v23, v23, v8
	v_mul_f32_e32 v12, v12, v16
	v_mul_f32_e32 v13, v13, v17
	v_mul_f32_e32 v14, v14, v18
	v_mul_f32_e32 v15, v15, v19
	v_mul_f32_e32 v20, v20, v88
	v_mul_f32_e32 v21, v21, v89
	v_mul_f32_e32 v22, v22, v90
	v_mul_f32_e32 v23, v23, v91
	v_mul_f32_e32 v20, v20, v12
	v_mul_f32_e32 v21, v21, v13
	v_mul_f32_e32 v22, v22, v14
	v_mul_f32_e32 v23, v23, v15
	v_cvt_pk_bf16_f32 v20, v20, v21
	v_cvt_pk_bf16_f32 v21, v22, v23
	global_store_dwordx2 v[4:5], v[20:21], off offset:160
	s_waitcnt vmcnt(9)
	v_lshlrev_b32_e32 v12, 16, v36
	v_and_b32_e32 v13, 0xffff0000, v36
	v_lshlrev_b32_e32 v14, 16, v37
	v_and_b32_e32 v15, 0xffff0000, v37
	v_mul_f32_e32 v16, 0xbfb8aa3b, v12
	v_mul_f32_e32 v17, 0xbfb8aa3b, v13
	v_mul_f32_e32 v18, 0xbfb8aa3b, v14
	v_mul_f32_e32 v19, 0xbfb8aa3b, v15
	v_exp_f32_e32 v16, v16
	v_exp_f32_e32 v17, v17
	v_exp_f32_e32 v18, v18
	v_exp_f32_e32 v19, v19
	v_lshlrev_b32_e32 v20, 16, v52
	v_and_b32_e32 v21, 0xffff0000, v52
	v_lshlrev_b32_e32 v22, 16, v53
	v_and_b32_e32 v23, 0xffff0000, v53
	v_add_f32_e32 v16, 1.0, v16
	v_add_f32_e32 v17, 1.0, v17
	v_add_f32_e32 v18, 1.0, v18
	v_add_f32_e32 v19, 1.0, v19
	v_rcp_f32_e32 v16, v16
	v_rcp_f32_e32 v17, v17
	v_rcp_f32_e32 v18, v18
	v_rcp_f32_e32 v19, v19
	v_sub_f32_e32 v20, v20, v7
	v_sub_f32_e32 v21, v21, v7
	v_sub_f32_e32 v22, v22, v7
	v_sub_f32_e32 v23, v23, v7
	v_mul_f32_e32 v20, v20, v8
	v_mul_f32_e32 v21, v21, v8
	v_mul_f32_e32 v22, v22, v8
	v_mul_f32_e32 v23, v23, v8
	v_mul_f32_e32 v12, v12, v16
	v_mul_f32_e32 v13, v13, v17
	v_mul_f32_e32 v14, v14, v18
	v_mul_f32_e32 v15, v15, v19
	v_mul_f32_e32 v20, v20, v92
	v_mul_f32_e32 v21, v21, v93
	v_mul_f32_e32 v22, v22, v94
	v_mul_f32_e32 v23, v23, v95
	v_mul_f32_e32 v20, v20, v12
	v_mul_f32_e32 v21, v21, v13
	v_mul_f32_e32 v22, v22, v14
	v_mul_f32_e32 v23, v23, v15
	v_cvt_pk_bf16_f32 v20, v20, v21
	v_cvt_pk_bf16_f32 v21, v22, v23
	global_store_dwordx2 v[4:5], v[20:21], off offset:192
	s_waitcnt vmcnt(7)
	v_lshlrev_b32_e32 v12, 16, v38
	v_and_b32_e32 v13, 0xffff0000, v38
	v_lshlrev_b32_e32 v14, 16, v39
	v_and_b32_e32 v15, 0xffff0000, v39
	v_mul_f32_e32 v16, 0xbfb8aa3b, v12
	v_mul_f32_e32 v17, 0xbfb8aa3b, v13
	v_mul_f32_e32 v18, 0xbfb8aa3b, v14
	v_mul_f32_e32 v19, 0xbfb8aa3b, v15
	v_exp_f32_e32 v16, v16
	v_exp_f32_e32 v17, v17
	v_exp_f32_e32 v18, v18
	v_exp_f32_e32 v19, v19
	v_lshlrev_b32_e32 v20, 16, v54
	v_and_b32_e32 v21, 0xffff0000, v54
	v_lshlrev_b32_e32 v22, 16, v55
	v_and_b32_e32 v23, 0xffff0000, v55
	v_add_f32_e32 v16, 1.0, v16
	v_add_f32_e32 v17, 1.0, v17
	v_add_f32_e32 v18, 1.0, v18
	v_add_f32_e32 v19, 1.0, v19
	v_rcp_f32_e32 v16, v16
	v_rcp_f32_e32 v17, v17
	v_rcp_f32_e32 v18, v18
	v_rcp_f32_e32 v19, v19
	v_sub_f32_e32 v20, v20, v7
	v_sub_f32_e32 v21, v21, v7
	v_sub_f32_e32 v22, v22, v7
	v_sub_f32_e32 v23, v23, v7
	v_mul_f32_e32 v20, v20, v8
	v_mul_f32_e32 v21, v21, v8
	v_mul_f32_e32 v22, v22, v8
	v_mul_f32_e32 v23, v23, v8
	v_mul_f32_e32 v12, v12, v16
	v_mul_f32_e32 v13, v13, v17
	v_mul_f32_e32 v14, v14, v18
	v_mul_f32_e32 v15, v15, v19
	v_mul_f32_e32 v20, v20, v96
	v_mul_f32_e32 v21, v21, v97
	v_mul_f32_e32 v22, v22, v98
	v_mul_f32_e32 v23, v23, v99
	v_mul_f32_e32 v20, v20, v12
	v_mul_f32_e32 v21, v21, v13
	v_mul_f32_e32 v22, v22, v14
	v_mul_f32_e32 v23, v23, v15
	v_cvt_pk_bf16_f32 v20, v20, v21
	v_cvt_pk_bf16_f32 v21, v22, v23
	global_store_dwordx2 v[4:5], v[20:21], off offset:224
	global_load_dwordx2 v[24:25], v[10:11], off offset:256
	global_load_dwordx2 v[40:41], v[4:5], off offset:256
	global_load_dwordx4 v[68:71], v[158:159], off offset:512
	global_load_dwordx2 v[26:27], v[10:11], off offset:288
	global_load_dwordx2 v[42:43], v[4:5], off offset:288
	global_load_dwordx4 v[72:75], v[158:159], off offset:576
	global_load_dwordx2 v[28:29], v[10:11], off offset:320
	global_load_dwordx2 v[44:45], v[4:5], off offset:320
	global_load_dwordx4 v[76:79], v[158:159], off offset:640
	global_load_dwordx2 v[30:31], v[10:11], off offset:352
	global_load_dwordx2 v[46:47], v[4:5], off offset:352
	global_load_dwordx4 v[80:83], v[158:159], off offset:704
	global_load_dwordx2 v[32:33], v[10:11], off offset:384
	global_load_dwordx2 v[48:49], v[4:5], off offset:384
	global_load_dwordx4 v[84:87], v[158:159], off offset:768
	global_load_dwordx2 v[34:35], v[10:11], off offset:416
	global_load_dwordx2 v[50:51], v[4:5], off offset:416
	global_load_dwordx4 v[88:91], v[158:159], off offset:832
	global_load_dwordx2 v[36:37], v[10:11], off offset:448
	global_load_dwordx2 v[52:53], v[4:5], off offset:448
	global_load_dwordx4 v[92:95], v[158:159], off offset:896
	global_load_dwordx2 v[38:39], v[10:11], off offset:480
	global_load_dwordx2 v[54:55], v[4:5], off offset:480
	global_load_dwordx4 v[96:99], v[158:159], off offset:960
	s_waitcnt vmcnt(21)
	v_lshlrev_b32_e32 v12, 16, v24
	v_and_b32_e32 v13, 0xffff0000, v24
	v_lshlrev_b32_e32 v14, 16, v25
	v_and_b32_e32 v15, 0xffff0000, v25
	v_mul_f32_e32 v16, 0xbfb8aa3b, v12
	v_mul_f32_e32 v17, 0xbfb8aa3b, v13
	v_mul_f32_e32 v18, 0xbfb8aa3b, v14
	v_mul_f32_e32 v19, 0xbfb8aa3b, v15
	v_exp_f32_e32 v16, v16
	v_exp_f32_e32 v17, v17
	v_exp_f32_e32 v18, v18
	v_exp_f32_e32 v19, v19
	v_lshlrev_b32_e32 v20, 16, v40
	v_and_b32_e32 v21, 0xffff0000, v40
	v_lshlrev_b32_e32 v22, 16, v41
	v_and_b32_e32 v23, 0xffff0000, v41
	v_add_f32_e32 v16, 1.0, v16
	v_add_f32_e32 v17, 1.0, v17
	v_add_f32_e32 v18, 1.0, v18
	v_add_f32_e32 v19, 1.0, v19
	v_rcp_f32_e32 v16, v16
	v_rcp_f32_e32 v17, v17
	v_rcp_f32_e32 v18, v18
	v_rcp_f32_e32 v19, v19
	v_sub_f32_e32 v20, v20, v7
	v_sub_f32_e32 v21, v21, v7
	v_sub_f32_e32 v22, v22, v7
	v_sub_f32_e32 v23, v23, v7
	v_mul_f32_e32 v20, v20, v8
	v_mul_f32_e32 v21, v21, v8
	v_mul_f32_e32 v22, v22, v8
	v_mul_f32_e32 v23, v23, v8
	v_mul_f32_e32 v12, v12, v16
	v_mul_f32_e32 v13, v13, v17
	v_mul_f32_e32 v14, v14, v18
	v_mul_f32_e32 v15, v15, v19
	v_mul_f32_e32 v20, v20, v68
	v_mul_f32_e32 v21, v21, v69
	v_mul_f32_e32 v22, v22, v70
	v_mul_f32_e32 v23, v23, v71
	v_mul_f32_e32 v20, v20, v12
	v_mul_f32_e32 v21, v21, v13
	v_mul_f32_e32 v22, v22, v14
	v_mul_f32_e32 v23, v23, v15
	v_cvt_pk_bf16_f32 v20, v20, v21
	v_cvt_pk_bf16_f32 v21, v22, v23
	global_store_dwordx2 v[4:5], v[20:21], off offset:256
	s_waitcnt vmcnt(19)
	v_lshlrev_b32_e32 v12, 16, v26
	v_and_b32_e32 v13, 0xffff0000, v26
	v_lshlrev_b32_e32 v14, 16, v27
	v_and_b32_e32 v15, 0xffff0000, v27
	v_mul_f32_e32 v16, 0xbfb8aa3b, v12
	v_mul_f32_e32 v17, 0xbfb8aa3b, v13
	v_mul_f32_e32 v18, 0xbfb8aa3b, v14
	v_mul_f32_e32 v19, 0xbfb8aa3b, v15
	v_exp_f32_e32 v16, v16
	v_exp_f32_e32 v17, v17
	v_exp_f32_e32 v18, v18
	v_exp_f32_e32 v19, v19
	v_lshlrev_b32_e32 v20, 16, v42
	v_and_b32_e32 v21, 0xffff0000, v42
	v_lshlrev_b32_e32 v22, 16, v43
	v_and_b32_e32 v23, 0xffff0000, v43
	v_add_f32_e32 v16, 1.0, v16
	v_add_f32_e32 v17, 1.0, v17
	v_add_f32_e32 v18, 1.0, v18
	v_add_f32_e32 v19, 1.0, v19
	v_rcp_f32_e32 v16, v16
	v_rcp_f32_e32 v17, v17
	v_rcp_f32_e32 v18, v18
	v_rcp_f32_e32 v19, v19
	v_sub_f32_e32 v20, v20, v7
	v_sub_f32_e32 v21, v21, v7
	v_sub_f32_e32 v22, v22, v7
	v_sub_f32_e32 v23, v23, v7
	v_mul_f32_e32 v20, v20, v8
	v_mul_f32_e32 v21, v21, v8
	v_mul_f32_e32 v22, v22, v8
	v_mul_f32_e32 v23, v23, v8
	v_mul_f32_e32 v12, v12, v16
	v_mul_f32_e32 v13, v13, v17
	v_mul_f32_e32 v14, v14, v18
	v_mul_f32_e32 v15, v15, v19
	v_mul_f32_e32 v20, v20, v72
	v_mul_f32_e32 v21, v21, v73
	v_mul_f32_e32 v22, v22, v74
	v_mul_f32_e32 v23, v23, v75
	v_mul_f32_e32 v20, v20, v12
	v_mul_f32_e32 v21, v21, v13
	v_mul_f32_e32 v22, v22, v14
	v_mul_f32_e32 v23, v23, v15
	v_cvt_pk_bf16_f32 v20, v20, v21
	v_cvt_pk_bf16_f32 v21, v22, v23
	global_store_dwordx2 v[4:5], v[20:21], off offset:288
	s_waitcnt vmcnt(17)
	v_lshlrev_b32_e32 v12, 16, v28
	v_and_b32_e32 v13, 0xffff0000, v28
	v_lshlrev_b32_e32 v14, 16, v29
	v_and_b32_e32 v15, 0xffff0000, v29
	v_mul_f32_e32 v16, 0xbfb8aa3b, v12
	v_mul_f32_e32 v17, 0xbfb8aa3b, v13
	v_mul_f32_e32 v18, 0xbfb8aa3b, v14
	v_mul_f32_e32 v19, 0xbfb8aa3b, v15
	v_exp_f32_e32 v16, v16
	v_exp_f32_e32 v17, v17
	v_exp_f32_e32 v18, v18
	v_exp_f32_e32 v19, v19
	v_lshlrev_b32_e32 v20, 16, v44
	v_and_b32_e32 v21, 0xffff0000, v44
	v_lshlrev_b32_e32 v22, 16, v45
	v_and_b32_e32 v23, 0xffff0000, v45
	v_add_f32_e32 v16, 1.0, v16
	v_add_f32_e32 v17, 1.0, v17
	v_add_f32_e32 v18, 1.0, v18
	v_add_f32_e32 v19, 1.0, v19
	v_rcp_f32_e32 v16, v16
	v_rcp_f32_e32 v17, v17
	v_rcp_f32_e32 v18, v18
	v_rcp_f32_e32 v19, v19
	v_sub_f32_e32 v20, v20, v7
	v_sub_f32_e32 v21, v21, v7
	v_sub_f32_e32 v22, v22, v7
	v_sub_f32_e32 v23, v23, v7
	v_mul_f32_e32 v20, v20, v8
	v_mul_f32_e32 v21, v21, v8
	v_mul_f32_e32 v22, v22, v8
	v_mul_f32_e32 v23, v23, v8
	v_mul_f32_e32 v12, v12, v16
	v_mul_f32_e32 v13, v13, v17
	v_mul_f32_e32 v14, v14, v18
	v_mul_f32_e32 v15, v15, v19
	v_mul_f32_e32 v20, v20, v76
	v_mul_f32_e32 v21, v21, v77
	v_mul_f32_e32 v22, v22, v78
	v_mul_f32_e32 v23, v23, v79
	v_mul_f32_e32 v20, v20, v12
	v_mul_f32_e32 v21, v21, v13
	v_mul_f32_e32 v22, v22, v14
	v_mul_f32_e32 v23, v23, v15
	v_cvt_pk_bf16_f32 v20, v20, v21
	v_cvt_pk_bf16_f32 v21, v22, v23
	global_store_dwordx2 v[4:5], v[20:21], off offset:320
	s_waitcnt vmcnt(15)
	v_lshlrev_b32_e32 v12, 16, v30
	v_and_b32_e32 v13, 0xffff0000, v30
	v_lshlrev_b32_e32 v14, 16, v31
	v_and_b32_e32 v15, 0xffff0000, v31
	v_mul_f32_e32 v16, 0xbfb8aa3b, v12
	v_mul_f32_e32 v17, 0xbfb8aa3b, v13
	v_mul_f32_e32 v18, 0xbfb8aa3b, v14
	v_mul_f32_e32 v19, 0xbfb8aa3b, v15
	v_exp_f32_e32 v16, v16
	v_exp_f32_e32 v17, v17
	v_exp_f32_e32 v18, v18
	v_exp_f32_e32 v19, v19
	v_lshlrev_b32_e32 v20, 16, v46
	v_and_b32_e32 v21, 0xffff0000, v46
	v_lshlrev_b32_e32 v22, 16, v47
	v_and_b32_e32 v23, 0xffff0000, v47
	v_add_f32_e32 v16, 1.0, v16
	v_add_f32_e32 v17, 1.0, v17
	v_add_f32_e32 v18, 1.0, v18
	v_add_f32_e32 v19, 1.0, v19
	v_rcp_f32_e32 v16, v16
	v_rcp_f32_e32 v17, v17
	v_rcp_f32_e32 v18, v18
	v_rcp_f32_e32 v19, v19
	v_sub_f32_e32 v20, v20, v7
	v_sub_f32_e32 v21, v21, v7
	v_sub_f32_e32 v22, v22, v7
	v_sub_f32_e32 v23, v23, v7
	v_mul_f32_e32 v20, v20, v8
	v_mul_f32_e32 v21, v21, v8
	v_mul_f32_e32 v22, v22, v8
	v_mul_f32_e32 v23, v23, v8
	v_mul_f32_e32 v12, v12, v16
	v_mul_f32_e32 v13, v13, v17
	v_mul_f32_e32 v14, v14, v18
	v_mul_f32_e32 v15, v15, v19
	v_mul_f32_e32 v20, v20, v80
	v_mul_f32_e32 v21, v21, v81
	v_mul_f32_e32 v22, v22, v82
	v_mul_f32_e32 v23, v23, v83
	v_mul_f32_e32 v20, v20, v12
	v_mul_f32_e32 v21, v21, v13
	v_mul_f32_e32 v22, v22, v14
	v_mul_f32_e32 v23, v23, v15
	v_cvt_pk_bf16_f32 v20, v20, v21
	v_cvt_pk_bf16_f32 v21, v22, v23
	global_store_dwordx2 v[4:5], v[20:21], off offset:352
	s_waitcnt vmcnt(13)
	v_lshlrev_b32_e32 v12, 16, v32
	v_and_b32_e32 v13, 0xffff0000, v32
	v_lshlrev_b32_e32 v14, 16, v33
	v_and_b32_e32 v15, 0xffff0000, v33
	v_mul_f32_e32 v16, 0xbfb8aa3b, v12
	v_mul_f32_e32 v17, 0xbfb8aa3b, v13
	v_mul_f32_e32 v18, 0xbfb8aa3b, v14
	v_mul_f32_e32 v19, 0xbfb8aa3b, v15
	v_exp_f32_e32 v16, v16
	v_exp_f32_e32 v17, v17
	v_exp_f32_e32 v18, v18
	v_exp_f32_e32 v19, v19
	v_lshlrev_b32_e32 v20, 16, v48
	v_and_b32_e32 v21, 0xffff0000, v48
	v_lshlrev_b32_e32 v22, 16, v49
	v_and_b32_e32 v23, 0xffff0000, v49
	v_add_f32_e32 v16, 1.0, v16
	v_add_f32_e32 v17, 1.0, v17
	v_add_f32_e32 v18, 1.0, v18
	v_add_f32_e32 v19, 1.0, v19
	v_rcp_f32_e32 v16, v16
	v_rcp_f32_e32 v17, v17
	v_rcp_f32_e32 v18, v18
	v_rcp_f32_e32 v19, v19
	v_sub_f32_e32 v20, v20, v7
	v_sub_f32_e32 v21, v21, v7
	v_sub_f32_e32 v22, v22, v7
	v_sub_f32_e32 v23, v23, v7
	v_mul_f32_e32 v20, v20, v8
	v_mul_f32_e32 v21, v21, v8
	v_mul_f32_e32 v22, v22, v8
	v_mul_f32_e32 v23, v23, v8
	v_mul_f32_e32 v12, v12, v16
	v_mul_f32_e32 v13, v13, v17
	v_mul_f32_e32 v14, v14, v18
	v_mul_f32_e32 v15, v15, v19
	v_mul_f32_e32 v20, v20, v84
	v_mul_f32_e32 v21, v21, v85
	v_mul_f32_e32 v22, v22, v86
	v_mul_f32_e32 v23, v23, v87
	v_mul_f32_e32 v20, v20, v12
	v_mul_f32_e32 v21, v21, v13
	v_mul_f32_e32 v22, v22, v14
	v_mul_f32_e32 v23, v23, v15
	v_cvt_pk_bf16_f32 v20, v20, v21
	v_cvt_pk_bf16_f32 v21, v22, v23
	global_store_dwordx2 v[4:5], v[20:21], off offset:384
	s_waitcnt vmcnt(11)
	v_lshlrev_b32_e32 v12, 16, v34
	v_and_b32_e32 v13, 0xffff0000, v34
	v_lshlrev_b32_e32 v14, 16, v35
	v_and_b32_e32 v15, 0xffff0000, v35
	v_mul_f32_e32 v16, 0xbfb8aa3b, v12
	v_mul_f32_e32 v17, 0xbfb8aa3b, v13
	v_mul_f32_e32 v18, 0xbfb8aa3b, v14
	v_mul_f32_e32 v19, 0xbfb8aa3b, v15
	v_exp_f32_e32 v16, v16
	v_exp_f32_e32 v17, v17
	v_exp_f32_e32 v18, v18
	v_exp_f32_e32 v19, v19
	v_lshlrev_b32_e32 v20, 16, v50
	v_and_b32_e32 v21, 0xffff0000, v50
	v_lshlrev_b32_e32 v22, 16, v51
	v_and_b32_e32 v23, 0xffff0000, v51
	v_add_f32_e32 v16, 1.0, v16
	v_add_f32_e32 v17, 1.0, v17
	v_add_f32_e32 v18, 1.0, v18
	v_add_f32_e32 v19, 1.0, v19
	v_rcp_f32_e32 v16, v16
	v_rcp_f32_e32 v17, v17
	v_rcp_f32_e32 v18, v18
	v_rcp_f32_e32 v19, v19
	v_sub_f32_e32 v20, v20, v7
	v_sub_f32_e32 v21, v21, v7
	v_sub_f32_e32 v22, v22, v7
	v_sub_f32_e32 v23, v23, v7
	v_mul_f32_e32 v20, v20, v8
	v_mul_f32_e32 v21, v21, v8
	v_mul_f32_e32 v22, v22, v8
	v_mul_f32_e32 v23, v23, v8
	v_mul_f32_e32 v12, v12, v16
	v_mul_f32_e32 v13, v13, v17
	v_mul_f32_e32 v14, v14, v18
	v_mul_f32_e32 v15, v15, v19
	v_mul_f32_e32 v20, v20, v88
	v_mul_f32_e32 v21, v21, v89
	v_mul_f32_e32 v22, v22, v90
	v_mul_f32_e32 v23, v23, v91
	v_mul_f32_e32 v20, v20, v12
	v_mul_f32_e32 v21, v21, v13
	v_mul_f32_e32 v22, v22, v14
	v_mul_f32_e32 v23, v23, v15
	v_cvt_pk_bf16_f32 v20, v20, v21
	v_cvt_pk_bf16_f32 v21, v22, v23
	global_store_dwordx2 v[4:5], v[20:21], off offset:416
	s_waitcnt vmcnt(9)
	v_lshlrev_b32_e32 v12, 16, v36
	v_and_b32_e32 v13, 0xffff0000, v36
	v_lshlrev_b32_e32 v14, 16, v37
	v_and_b32_e32 v15, 0xffff0000, v37
	v_mul_f32_e32 v16, 0xbfb8aa3b, v12
	v_mul_f32_e32 v17, 0xbfb8aa3b, v13
	v_mul_f32_e32 v18, 0xbfb8aa3b, v14
	v_mul_f32_e32 v19, 0xbfb8aa3b, v15
	v_exp_f32_e32 v16, v16
	v_exp_f32_e32 v17, v17
	v_exp_f32_e32 v18, v18
	v_exp_f32_e32 v19, v19
	v_lshlrev_b32_e32 v20, 16, v52
	v_and_b32_e32 v21, 0xffff0000, v52
	v_lshlrev_b32_e32 v22, 16, v53
	v_and_b32_e32 v23, 0xffff0000, v53
	v_add_f32_e32 v16, 1.0, v16
	v_add_f32_e32 v17, 1.0, v17
	v_add_f32_e32 v18, 1.0, v18
	v_add_f32_e32 v19, 1.0, v19
	v_rcp_f32_e32 v16, v16
	v_rcp_f32_e32 v17, v17
	v_rcp_f32_e32 v18, v18
	v_rcp_f32_e32 v19, v19
	v_sub_f32_e32 v20, v20, v7
	v_sub_f32_e32 v21, v21, v7
	v_sub_f32_e32 v22, v22, v7
	v_sub_f32_e32 v23, v23, v7
	v_mul_f32_e32 v20, v20, v8
	v_mul_f32_e32 v21, v21, v8
	v_mul_f32_e32 v22, v22, v8
	v_mul_f32_e32 v23, v23, v8
	v_mul_f32_e32 v12, v12, v16
	v_mul_f32_e32 v13, v13, v17
	v_mul_f32_e32 v14, v14, v18
	v_mul_f32_e32 v15, v15, v19
	v_mul_f32_e32 v20, v20, v92
	v_mul_f32_e32 v21, v21, v93
	v_mul_f32_e32 v22, v22, v94
	v_mul_f32_e32 v23, v23, v95
	v_mul_f32_e32 v20, v20, v12
	v_mul_f32_e32 v21, v21, v13
	v_mul_f32_e32 v22, v22, v14
	v_mul_f32_e32 v23, v23, v15
	v_cvt_pk_bf16_f32 v20, v20, v21
	v_cvt_pk_bf16_f32 v21, v22, v23
	global_store_dwordx2 v[4:5], v[20:21], off offset:448
	s_waitcnt vmcnt(7)
	v_lshlrev_b32_e32 v12, 16, v38
	v_and_b32_e32 v13, 0xffff0000, v38
	v_lshlrev_b32_e32 v14, 16, v39
	v_and_b32_e32 v15, 0xffff0000, v39
	v_mul_f32_e32 v16, 0xbfb8aa3b, v12
	v_mul_f32_e32 v17, 0xbfb8aa3b, v13
	v_mul_f32_e32 v18, 0xbfb8aa3b, v14
	v_mul_f32_e32 v19, 0xbfb8aa3b, v15
	v_exp_f32_e32 v16, v16
	v_exp_f32_e32 v17, v17
	v_exp_f32_e32 v18, v18
	v_exp_f32_e32 v19, v19
	v_lshlrev_b32_e32 v20, 16, v54
	v_and_b32_e32 v21, 0xffff0000, v54
	v_lshlrev_b32_e32 v22, 16, v55
	v_and_b32_e32 v23, 0xffff0000, v55
	v_add_f32_e32 v16, 1.0, v16
	v_add_f32_e32 v17, 1.0, v17
	v_add_f32_e32 v18, 1.0, v18
	v_add_f32_e32 v19, 1.0, v19
	v_rcp_f32_e32 v16, v16
	v_rcp_f32_e32 v17, v17
	v_rcp_f32_e32 v18, v18
	v_rcp_f32_e32 v19, v19
	v_sub_f32_e32 v20, v20, v7
	v_sub_f32_e32 v21, v21, v7
	v_sub_f32_e32 v22, v22, v7
	v_sub_f32_e32 v23, v23, v7
	v_mul_f32_e32 v20, v20, v8
	v_mul_f32_e32 v21, v21, v8
	v_mul_f32_e32 v22, v22, v8
	v_mul_f32_e32 v23, v23, v8
	v_mul_f32_e32 v12, v12, v16
	v_mul_f32_e32 v13, v13, v17
	v_mul_f32_e32 v14, v14, v18
	v_mul_f32_e32 v15, v15, v19
	v_mul_f32_e32 v20, v20, v96
	v_mul_f32_e32 v21, v21, v97
	v_mul_f32_e32 v22, v22, v98
	v_mul_f32_e32 v23, v23, v99
	v_mul_f32_e32 v20, v20, v12
	v_mul_f32_e32 v21, v21, v13
	v_mul_f32_e32 v22, v22, v14
	v_mul_f32_e32 v23, v23, v15
	v_cvt_pk_bf16_f32 v20, v20, v21
	v_cvt_pk_bf16_f32 v21, v22, v23
	global_store_dwordx2 v[4:5], v[20:21], off offset:480
	global_load_dwordx2 v[24:25], v[10:11], off offset:512
	global_load_dwordx2 v[40:41], v[4:5], off offset:512
	global_load_dwordx4 v[68:71], v[158:159], off offset:1024
	global_load_dwordx2 v[26:27], v[10:11], off offset:544
	global_load_dwordx2 v[42:43], v[4:5], off offset:544
	global_load_dwordx4 v[72:75], v[158:159], off offset:1088
	global_load_dwordx2 v[28:29], v[10:11], off offset:576
	global_load_dwordx2 v[44:45], v[4:5], off offset:576
	global_load_dwordx4 v[76:79], v[158:159], off offset:1152
	global_load_dwordx2 v[30:31], v[10:11], off offset:608
	global_load_dwordx2 v[46:47], v[4:5], off offset:608
	global_load_dwordx4 v[80:83], v[158:159], off offset:1216
	global_load_dwordx2 v[32:33], v[10:11], off offset:640
	global_load_dwordx2 v[48:49], v[4:5], off offset:640
	global_load_dwordx4 v[84:87], v[158:159], off offset:1280
	global_load_dwordx2 v[34:35], v[10:11], off offset:672
	global_load_dwordx2 v[50:51], v[4:5], off offset:672
	global_load_dwordx4 v[88:91], v[158:159], off offset:1344
	global_load_dwordx2 v[36:37], v[10:11], off offset:704
	global_load_dwordx2 v[52:53], v[4:5], off offset:704
	global_load_dwordx4 v[92:95], v[158:159], off offset:1408
	global_load_dwordx2 v[38:39], v[10:11], off offset:736
	global_load_dwordx2 v[54:55], v[4:5], off offset:736
	global_load_dwordx4 v[96:99], v[158:159], off offset:1472
	s_waitcnt vmcnt(21)
	v_lshlrev_b32_e32 v12, 16, v24
	v_and_b32_e32 v13, 0xffff0000, v24
	v_lshlrev_b32_e32 v14, 16, v25
	v_and_b32_e32 v15, 0xffff0000, v25
	v_mul_f32_e32 v16, 0xbfb8aa3b, v12
	v_mul_f32_e32 v17, 0xbfb8aa3b, v13
	v_mul_f32_e32 v18, 0xbfb8aa3b, v14
	v_mul_f32_e32 v19, 0xbfb8aa3b, v15
	v_exp_f32_e32 v16, v16
	v_exp_f32_e32 v17, v17
	v_exp_f32_e32 v18, v18
	v_exp_f32_e32 v19, v19
	v_lshlrev_b32_e32 v20, 16, v40
	v_and_b32_e32 v21, 0xffff0000, v40
	v_lshlrev_b32_e32 v22, 16, v41
	v_and_b32_e32 v23, 0xffff0000, v41
	v_add_f32_e32 v16, 1.0, v16
	v_add_f32_e32 v17, 1.0, v17
	v_add_f32_e32 v18, 1.0, v18
	v_add_f32_e32 v19, 1.0, v19
	v_rcp_f32_e32 v16, v16
	v_rcp_f32_e32 v17, v17
	v_rcp_f32_e32 v18, v18
	v_rcp_f32_e32 v19, v19
	v_sub_f32_e32 v20, v20, v7
	v_sub_f32_e32 v21, v21, v7
	v_sub_f32_e32 v22, v22, v7
	v_sub_f32_e32 v23, v23, v7
	v_mul_f32_e32 v20, v20, v8
	v_mul_f32_e32 v21, v21, v8
	v_mul_f32_e32 v22, v22, v8
	v_mul_f32_e32 v23, v23, v8
	v_mul_f32_e32 v12, v12, v16
	v_mul_f32_e32 v13, v13, v17
	v_mul_f32_e32 v14, v14, v18
	v_mul_f32_e32 v15, v15, v19
	v_mul_f32_e32 v20, v20, v68
	v_mul_f32_e32 v21, v21, v69
	v_mul_f32_e32 v22, v22, v70
	v_mul_f32_e32 v23, v23, v71
	v_mul_f32_e32 v20, v20, v12
	v_mul_f32_e32 v21, v21, v13
	v_mul_f32_e32 v22, v22, v14
	v_mul_f32_e32 v23, v23, v15
	v_cvt_pk_bf16_f32 v20, v20, v21
	v_cvt_pk_bf16_f32 v21, v22, v23
	global_store_dwordx2 v[4:5], v[20:21], off offset:512
	s_waitcnt vmcnt(19)
	v_lshlrev_b32_e32 v12, 16, v26
	v_and_b32_e32 v13, 0xffff0000, v26
	v_lshlrev_b32_e32 v14, 16, v27
	v_and_b32_e32 v15, 0xffff0000, v27
	v_mul_f32_e32 v16, 0xbfb8aa3b, v12
	v_mul_f32_e32 v17, 0xbfb8aa3b, v13
	v_mul_f32_e32 v18, 0xbfb8aa3b, v14
	v_mul_f32_e32 v19, 0xbfb8aa3b, v15
	v_exp_f32_e32 v16, v16
	v_exp_f32_e32 v17, v17
	v_exp_f32_e32 v18, v18
	v_exp_f32_e32 v19, v19
	v_lshlrev_b32_e32 v20, 16, v42
	v_and_b32_e32 v21, 0xffff0000, v42
	v_lshlrev_b32_e32 v22, 16, v43
	v_and_b32_e32 v23, 0xffff0000, v43
	v_add_f32_e32 v16, 1.0, v16
	v_add_f32_e32 v17, 1.0, v17
	v_add_f32_e32 v18, 1.0, v18
	v_add_f32_e32 v19, 1.0, v19
	v_rcp_f32_e32 v16, v16
	v_rcp_f32_e32 v17, v17
	v_rcp_f32_e32 v18, v18
	v_rcp_f32_e32 v19, v19
	v_sub_f32_e32 v20, v20, v7
	v_sub_f32_e32 v21, v21, v7
	v_sub_f32_e32 v22, v22, v7
	v_sub_f32_e32 v23, v23, v7
	v_mul_f32_e32 v20, v20, v8
	v_mul_f32_e32 v21, v21, v8
	v_mul_f32_e32 v22, v22, v8
	v_mul_f32_e32 v23, v23, v8
	v_mul_f32_e32 v12, v12, v16
	v_mul_f32_e32 v13, v13, v17
	v_mul_f32_e32 v14, v14, v18
	v_mul_f32_e32 v15, v15, v19
	v_mul_f32_e32 v20, v20, v72
	v_mul_f32_e32 v21, v21, v73
	v_mul_f32_e32 v22, v22, v74
	v_mul_f32_e32 v23, v23, v75
	v_mul_f32_e32 v20, v20, v12
	v_mul_f32_e32 v21, v21, v13
	v_mul_f32_e32 v22, v22, v14
	v_mul_f32_e32 v23, v23, v15
	v_cvt_pk_bf16_f32 v20, v20, v21
	v_cvt_pk_bf16_f32 v21, v22, v23
	global_store_dwordx2 v[4:5], v[20:21], off offset:544
	s_waitcnt vmcnt(17)
	v_lshlrev_b32_e32 v12, 16, v28
	v_and_b32_e32 v13, 0xffff0000, v28
	v_lshlrev_b32_e32 v14, 16, v29
	v_and_b32_e32 v15, 0xffff0000, v29
	v_mul_f32_e32 v16, 0xbfb8aa3b, v12
	v_mul_f32_e32 v17, 0xbfb8aa3b, v13
	v_mul_f32_e32 v18, 0xbfb8aa3b, v14
	v_mul_f32_e32 v19, 0xbfb8aa3b, v15
	v_exp_f32_e32 v16, v16
	v_exp_f32_e32 v17, v17
	v_exp_f32_e32 v18, v18
	v_exp_f32_e32 v19, v19
	v_lshlrev_b32_e32 v20, 16, v44
	v_and_b32_e32 v21, 0xffff0000, v44
	v_lshlrev_b32_e32 v22, 16, v45
	v_and_b32_e32 v23, 0xffff0000, v45
	v_add_f32_e32 v16, 1.0, v16
	v_add_f32_e32 v17, 1.0, v17
	v_add_f32_e32 v18, 1.0, v18
	v_add_f32_e32 v19, 1.0, v19
	v_rcp_f32_e32 v16, v16
	v_rcp_f32_e32 v17, v17
	v_rcp_f32_e32 v18, v18
	v_rcp_f32_e32 v19, v19
	v_sub_f32_e32 v20, v20, v7
	v_sub_f32_e32 v21, v21, v7
	v_sub_f32_e32 v22, v22, v7
	v_sub_f32_e32 v23, v23, v7
	v_mul_f32_e32 v20, v20, v8
	v_mul_f32_e32 v21, v21, v8
	v_mul_f32_e32 v22, v22, v8
	v_mul_f32_e32 v23, v23, v8
	v_mul_f32_e32 v12, v12, v16
	v_mul_f32_e32 v13, v13, v17
	v_mul_f32_e32 v14, v14, v18
	v_mul_f32_e32 v15, v15, v19
	v_mul_f32_e32 v20, v20, v76
	v_mul_f32_e32 v21, v21, v77
	v_mul_f32_e32 v22, v22, v78
	v_mul_f32_e32 v23, v23, v79
	v_mul_f32_e32 v20, v20, v12
	v_mul_f32_e32 v21, v21, v13
	v_mul_f32_e32 v22, v22, v14
	v_mul_f32_e32 v23, v23, v15
	v_cvt_pk_bf16_f32 v20, v20, v21
	v_cvt_pk_bf16_f32 v21, v22, v23
	global_store_dwordx2 v[4:5], v[20:21], off offset:576
	s_waitcnt vmcnt(15)
	v_lshlrev_b32_e32 v12, 16, v30
	v_and_b32_e32 v13, 0xffff0000, v30
	v_lshlrev_b32_e32 v14, 16, v31
	v_and_b32_e32 v15, 0xffff0000, v31
	v_mul_f32_e32 v16, 0xbfb8aa3b, v12
	v_mul_f32_e32 v17, 0xbfb8aa3b, v13
	v_mul_f32_e32 v18, 0xbfb8aa3b, v14
	v_mul_f32_e32 v19, 0xbfb8aa3b, v15
	v_exp_f32_e32 v16, v16
	v_exp_f32_e32 v17, v17
	v_exp_f32_e32 v18, v18
	v_exp_f32_e32 v19, v19
	v_lshlrev_b32_e32 v20, 16, v46
	v_and_b32_e32 v21, 0xffff0000, v46
	v_lshlrev_b32_e32 v22, 16, v47
	v_and_b32_e32 v23, 0xffff0000, v47
	v_add_f32_e32 v16, 1.0, v16
	v_add_f32_e32 v17, 1.0, v17
	v_add_f32_e32 v18, 1.0, v18
	v_add_f32_e32 v19, 1.0, v19
	v_rcp_f32_e32 v16, v16
	v_rcp_f32_e32 v17, v17
	v_rcp_f32_e32 v18, v18
	v_rcp_f32_e32 v19, v19
	v_sub_f32_e32 v20, v20, v7
	v_sub_f32_e32 v21, v21, v7
	v_sub_f32_e32 v22, v22, v7
	v_sub_f32_e32 v23, v23, v7
	v_mul_f32_e32 v20, v20, v8
	v_mul_f32_e32 v21, v21, v8
	v_mul_f32_e32 v22, v22, v8
	v_mul_f32_e32 v23, v23, v8
	v_mul_f32_e32 v12, v12, v16
	v_mul_f32_e32 v13, v13, v17
	v_mul_f32_e32 v14, v14, v18
	v_mul_f32_e32 v15, v15, v19
	v_mul_f32_e32 v20, v20, v80
	v_mul_f32_e32 v21, v21, v81
	v_mul_f32_e32 v22, v22, v82
	v_mul_f32_e32 v23, v23, v83
	v_mul_f32_e32 v20, v20, v12
	v_mul_f32_e32 v21, v21, v13
	v_mul_f32_e32 v22, v22, v14
	v_mul_f32_e32 v23, v23, v15
	v_cvt_pk_bf16_f32 v20, v20, v21
	v_cvt_pk_bf16_f32 v21, v22, v23
	global_store_dwordx2 v[4:5], v[20:21], off offset:608
	s_waitcnt vmcnt(13)
	v_lshlrev_b32_e32 v12, 16, v32
	v_and_b32_e32 v13, 0xffff0000, v32
	v_lshlrev_b32_e32 v14, 16, v33
	v_and_b32_e32 v15, 0xffff0000, v33
	v_mul_f32_e32 v16, 0xbfb8aa3b, v12
	v_mul_f32_e32 v17, 0xbfb8aa3b, v13
	v_mul_f32_e32 v18, 0xbfb8aa3b, v14
	v_mul_f32_e32 v19, 0xbfb8aa3b, v15
	v_exp_f32_e32 v16, v16
	v_exp_f32_e32 v17, v17
	v_exp_f32_e32 v18, v18
	v_exp_f32_e32 v19, v19
	v_lshlrev_b32_e32 v20, 16, v48
	v_and_b32_e32 v21, 0xffff0000, v48
	v_lshlrev_b32_e32 v22, 16, v49
	v_and_b32_e32 v23, 0xffff0000, v49
	v_add_f32_e32 v16, 1.0, v16
	v_add_f32_e32 v17, 1.0, v17
	v_add_f32_e32 v18, 1.0, v18
	v_add_f32_e32 v19, 1.0, v19
	v_rcp_f32_e32 v16, v16
	v_rcp_f32_e32 v17, v17
	v_rcp_f32_e32 v18, v18
	v_rcp_f32_e32 v19, v19
	v_sub_f32_e32 v20, v20, v7
	v_sub_f32_e32 v21, v21, v7
	v_sub_f32_e32 v22, v22, v7
	v_sub_f32_e32 v23, v23, v7
	v_mul_f32_e32 v20, v20, v8
	v_mul_f32_e32 v21, v21, v8
	v_mul_f32_e32 v22, v22, v8
	v_mul_f32_e32 v23, v23, v8
	v_mul_f32_e32 v12, v12, v16
	v_mul_f32_e32 v13, v13, v17
	v_mul_f32_e32 v14, v14, v18
	v_mul_f32_e32 v15, v15, v19
	v_mul_f32_e32 v20, v20, v84
	v_mul_f32_e32 v21, v21, v85
	v_mul_f32_e32 v22, v22, v86
	v_mul_f32_e32 v23, v23, v87
	v_mul_f32_e32 v20, v20, v12
	v_mul_f32_e32 v21, v21, v13
	v_mul_f32_e32 v22, v22, v14
	v_mul_f32_e32 v23, v23, v15
	v_cvt_pk_bf16_f32 v20, v20, v21
	v_cvt_pk_bf16_f32 v21, v22, v23
	global_store_dwordx2 v[4:5], v[20:21], off offset:640
	s_waitcnt vmcnt(11)
	v_lshlrev_b32_e32 v12, 16, v34
	v_and_b32_e32 v13, 0xffff0000, v34
	v_lshlrev_b32_e32 v14, 16, v35
	v_and_b32_e32 v15, 0xffff0000, v35
	v_mul_f32_e32 v16, 0xbfb8aa3b, v12
	v_mul_f32_e32 v17, 0xbfb8aa3b, v13
	v_mul_f32_e32 v18, 0xbfb8aa3b, v14
	v_mul_f32_e32 v19, 0xbfb8aa3b, v15
	v_exp_f32_e32 v16, v16
	v_exp_f32_e32 v17, v17
	v_exp_f32_e32 v18, v18
	v_exp_f32_e32 v19, v19
	v_lshlrev_b32_e32 v20, 16, v50
	v_and_b32_e32 v21, 0xffff0000, v50
	v_lshlrev_b32_e32 v22, 16, v51
	v_and_b32_e32 v23, 0xffff0000, v51
	v_add_f32_e32 v16, 1.0, v16
	v_add_f32_e32 v17, 1.0, v17
	v_add_f32_e32 v18, 1.0, v18
	v_add_f32_e32 v19, 1.0, v19
	v_rcp_f32_e32 v16, v16
	v_rcp_f32_e32 v17, v17
	v_rcp_f32_e32 v18, v18
	v_rcp_f32_e32 v19, v19
	v_sub_f32_e32 v20, v20, v7
	v_sub_f32_e32 v21, v21, v7
	v_sub_f32_e32 v22, v22, v7
	v_sub_f32_e32 v23, v23, v7
	v_mul_f32_e32 v20, v20, v8
	v_mul_f32_e32 v21, v21, v8
	v_mul_f32_e32 v22, v22, v8
	v_mul_f32_e32 v23, v23, v8
	v_mul_f32_e32 v12, v12, v16
	v_mul_f32_e32 v13, v13, v17
	v_mul_f32_e32 v14, v14, v18
	v_mul_f32_e32 v15, v15, v19
	v_mul_f32_e32 v20, v20, v88
	v_mul_f32_e32 v21, v21, v89
	v_mul_f32_e32 v22, v22, v90
	v_mul_f32_e32 v23, v23, v91
	v_mul_f32_e32 v20, v20, v12
	v_mul_f32_e32 v21, v21, v13
	v_mul_f32_e32 v22, v22, v14
	v_mul_f32_e32 v23, v23, v15
	v_cvt_pk_bf16_f32 v20, v20, v21
	v_cvt_pk_bf16_f32 v21, v22, v23
	global_store_dwordx2 v[4:5], v[20:21], off offset:672
	s_waitcnt vmcnt(9)
	v_lshlrev_b32_e32 v12, 16, v36
	v_and_b32_e32 v13, 0xffff0000, v36
	v_lshlrev_b32_e32 v14, 16, v37
	v_and_b32_e32 v15, 0xffff0000, v37
	v_mul_f32_e32 v16, 0xbfb8aa3b, v12
	v_mul_f32_e32 v17, 0xbfb8aa3b, v13
	v_mul_f32_e32 v18, 0xbfb8aa3b, v14
	v_mul_f32_e32 v19, 0xbfb8aa3b, v15
	v_exp_f32_e32 v16, v16
	v_exp_f32_e32 v17, v17
	v_exp_f32_e32 v18, v18
	v_exp_f32_e32 v19, v19
	v_lshlrev_b32_e32 v20, 16, v52
	v_and_b32_e32 v21, 0xffff0000, v52
	v_lshlrev_b32_e32 v22, 16, v53
	v_and_b32_e32 v23, 0xffff0000, v53
	v_add_f32_e32 v16, 1.0, v16
	v_add_f32_e32 v17, 1.0, v17
	v_add_f32_e32 v18, 1.0, v18
	v_add_f32_e32 v19, 1.0, v19
	v_rcp_f32_e32 v16, v16
	v_rcp_f32_e32 v17, v17
	v_rcp_f32_e32 v18, v18
	v_rcp_f32_e32 v19, v19
	v_sub_f32_e32 v20, v20, v7
	v_sub_f32_e32 v21, v21, v7
	v_sub_f32_e32 v22, v22, v7
	v_sub_f32_e32 v23, v23, v7
	v_mul_f32_e32 v20, v20, v8
	v_mul_f32_e32 v21, v21, v8
	v_mul_f32_e32 v22, v22, v8
	v_mul_f32_e32 v23, v23, v8
	v_mul_f32_e32 v12, v12, v16
	v_mul_f32_e32 v13, v13, v17
	v_mul_f32_e32 v14, v14, v18
	v_mul_f32_e32 v15, v15, v19
	v_mul_f32_e32 v20, v20, v92
	v_mul_f32_e32 v21, v21, v93
	v_mul_f32_e32 v22, v22, v94
	v_mul_f32_e32 v23, v23, v95
	v_mul_f32_e32 v20, v20, v12
	v_mul_f32_e32 v21, v21, v13
	v_mul_f32_e32 v22, v22, v14
	v_mul_f32_e32 v23, v23, v15
	v_cvt_pk_bf16_f32 v20, v20, v21
	v_cvt_pk_bf16_f32 v21, v22, v23
	global_store_dwordx2 v[4:5], v[20:21], off offset:704
	s_waitcnt vmcnt(7)
	v_lshlrev_b32_e32 v12, 16, v38
	v_and_b32_e32 v13, 0xffff0000, v38
	v_lshlrev_b32_e32 v14, 16, v39
	v_and_b32_e32 v15, 0xffff0000, v39
	v_mul_f32_e32 v16, 0xbfb8aa3b, v12
	v_mul_f32_e32 v17, 0xbfb8aa3b, v13
	v_mul_f32_e32 v18, 0xbfb8aa3b, v14
	v_mul_f32_e32 v19, 0xbfb8aa3b, v15
	v_exp_f32_e32 v16, v16
	v_exp_f32_e32 v17, v17
	v_exp_f32_e32 v18, v18
	v_exp_f32_e32 v19, v19
	v_lshlrev_b32_e32 v20, 16, v54
	v_and_b32_e32 v21, 0xffff0000, v54
	v_lshlrev_b32_e32 v22, 16, v55
	v_and_b32_e32 v23, 0xffff0000, v55
	v_add_f32_e32 v16, 1.0, v16
	v_add_f32_e32 v17, 1.0, v17
	v_add_f32_e32 v18, 1.0, v18
	v_add_f32_e32 v19, 1.0, v19
	v_rcp_f32_e32 v16, v16
	v_rcp_f32_e32 v17, v17
	v_rcp_f32_e32 v18, v18
	v_rcp_f32_e32 v19, v19
	v_sub_f32_e32 v20, v20, v7
	v_sub_f32_e32 v21, v21, v7
	v_sub_f32_e32 v22, v22, v7
	v_sub_f32_e32 v23, v23, v7
	v_mul_f32_e32 v20, v20, v8
	v_mul_f32_e32 v21, v21, v8
	v_mul_f32_e32 v22, v22, v8
	v_mul_f32_e32 v23, v23, v8
	v_mul_f32_e32 v12, v12, v16
	v_mul_f32_e32 v13, v13, v17
	v_mul_f32_e32 v14, v14, v18
	v_mul_f32_e32 v15, v15, v19
	v_mul_f32_e32 v20, v20, v96
	v_mul_f32_e32 v21, v21, v97
	v_mul_f32_e32 v22, v22, v98
	v_mul_f32_e32 v23, v23, v99
	v_mul_f32_e32 v20, v20, v12
	v_mul_f32_e32 v21, v21, v13
	v_mul_f32_e32 v22, v22, v14
	v_mul_f32_e32 v23, v23, v15
	v_cvt_pk_bf16_f32 v20, v20, v21
	v_cvt_pk_bf16_f32 v21, v22, v23
	global_store_dwordx2 v[4:5], v[20:21], off offset:736
	global_load_dwordx2 v[24:25], v[10:11], off offset:768
	global_load_dwordx2 v[40:41], v[4:5], off offset:768
	global_load_dwordx4 v[68:71], v[158:159], off offset:1536
	global_load_dwordx2 v[26:27], v[10:11], off offset:800
	global_load_dwordx2 v[42:43], v[4:5], off offset:800
	global_load_dwordx4 v[72:75], v[158:159], off offset:1600
	global_load_dwordx2 v[28:29], v[10:11], off offset:832
	global_load_dwordx2 v[44:45], v[4:5], off offset:832
	global_load_dwordx4 v[76:79], v[158:159], off offset:1664
	global_load_dwordx2 v[30:31], v[10:11], off offset:864
	global_load_dwordx2 v[46:47], v[4:5], off offset:864
	global_load_dwordx4 v[80:83], v[158:159], off offset:1728
	global_load_dwordx2 v[32:33], v[10:11], off offset:896
	global_load_dwordx2 v[48:49], v[4:5], off offset:896
	global_load_dwordx4 v[84:87], v[158:159], off offset:1792
	global_load_dwordx2 v[34:35], v[10:11], off offset:928
	global_load_dwordx2 v[50:51], v[4:5], off offset:928
	global_load_dwordx4 v[88:91], v[158:159], off offset:1856
	global_load_dwordx2 v[36:37], v[10:11], off offset:960
	global_load_dwordx2 v[52:53], v[4:5], off offset:960
	global_load_dwordx4 v[92:95], v[158:159], off offset:1920
	global_load_dwordx2 v[38:39], v[10:11], off offset:992
	global_load_dwordx2 v[54:55], v[4:5], off offset:992
	global_load_dwordx4 v[96:99], v[158:159], off offset:1984
	s_waitcnt vmcnt(21)
	v_lshlrev_b32_e32 v12, 16, v24
	v_and_b32_e32 v13, 0xffff0000, v24
	v_lshlrev_b32_e32 v14, 16, v25
	v_and_b32_e32 v15, 0xffff0000, v25
	v_mul_f32_e32 v16, 0xbfb8aa3b, v12
	v_mul_f32_e32 v17, 0xbfb8aa3b, v13
	v_mul_f32_e32 v18, 0xbfb8aa3b, v14
	v_mul_f32_e32 v19, 0xbfb8aa3b, v15
	v_exp_f32_e32 v16, v16
	v_exp_f32_e32 v17, v17
	v_exp_f32_e32 v18, v18
	v_exp_f32_e32 v19, v19
	v_lshlrev_b32_e32 v20, 16, v40
	v_and_b32_e32 v21, 0xffff0000, v40
	v_lshlrev_b32_e32 v22, 16, v41
	v_and_b32_e32 v23, 0xffff0000, v41
	v_add_f32_e32 v16, 1.0, v16
	v_add_f32_e32 v17, 1.0, v17
	v_add_f32_e32 v18, 1.0, v18
	v_add_f32_e32 v19, 1.0, v19
	v_rcp_f32_e32 v16, v16
	v_rcp_f32_e32 v17, v17
	v_rcp_f32_e32 v18, v18
	v_rcp_f32_e32 v19, v19
	v_sub_f32_e32 v20, v20, v7
	v_sub_f32_e32 v21, v21, v7
	v_sub_f32_e32 v22, v22, v7
	v_sub_f32_e32 v23, v23, v7
	v_mul_f32_e32 v20, v20, v8
	v_mul_f32_e32 v21, v21, v8
	v_mul_f32_e32 v22, v22, v8
	v_mul_f32_e32 v23, v23, v8
	v_mul_f32_e32 v12, v12, v16
	v_mul_f32_e32 v13, v13, v17
	v_mul_f32_e32 v14, v14, v18
	v_mul_f32_e32 v15, v15, v19
	v_mul_f32_e32 v20, v20, v68
	v_mul_f32_e32 v21, v21, v69
	v_mul_f32_e32 v22, v22, v70
	v_mul_f32_e32 v23, v23, v71
	v_mul_f32_e32 v20, v20, v12
	v_mul_f32_e32 v21, v21, v13
	v_mul_f32_e32 v22, v22, v14
	v_mul_f32_e32 v23, v23, v15
	v_cvt_pk_bf16_f32 v20, v20, v21
	v_cvt_pk_bf16_f32 v21, v22, v23
	global_store_dwordx2 v[4:5], v[20:21], off offset:768
	s_waitcnt vmcnt(19)
	v_lshlrev_b32_e32 v12, 16, v26
	v_and_b32_e32 v13, 0xffff0000, v26
	v_lshlrev_b32_e32 v14, 16, v27
	v_and_b32_e32 v15, 0xffff0000, v27
	v_mul_f32_e32 v16, 0xbfb8aa3b, v12
	v_mul_f32_e32 v17, 0xbfb8aa3b, v13
	v_mul_f32_e32 v18, 0xbfb8aa3b, v14
	v_mul_f32_e32 v19, 0xbfb8aa3b, v15
	v_exp_f32_e32 v16, v16
	v_exp_f32_e32 v17, v17
	v_exp_f32_e32 v18, v18
	v_exp_f32_e32 v19, v19
	v_lshlrev_b32_e32 v20, 16, v42
	v_and_b32_e32 v21, 0xffff0000, v42
	v_lshlrev_b32_e32 v22, 16, v43
	v_and_b32_e32 v23, 0xffff0000, v43
	v_add_f32_e32 v16, 1.0, v16
	v_add_f32_e32 v17, 1.0, v17
	v_add_f32_e32 v18, 1.0, v18
	v_add_f32_e32 v19, 1.0, v19
	v_rcp_f32_e32 v16, v16
	v_rcp_f32_e32 v17, v17
	v_rcp_f32_e32 v18, v18
	v_rcp_f32_e32 v19, v19
	v_sub_f32_e32 v20, v20, v7
	v_sub_f32_e32 v21, v21, v7
	v_sub_f32_e32 v22, v22, v7
	v_sub_f32_e32 v23, v23, v7
	v_mul_f32_e32 v20, v20, v8
	v_mul_f32_e32 v21, v21, v8
	v_mul_f32_e32 v22, v22, v8
	v_mul_f32_e32 v23, v23, v8
	v_mul_f32_e32 v12, v12, v16
	v_mul_f32_e32 v13, v13, v17
	v_mul_f32_e32 v14, v14, v18
	v_mul_f32_e32 v15, v15, v19
	v_mul_f32_e32 v20, v20, v72
	v_mul_f32_e32 v21, v21, v73
	v_mul_f32_e32 v22, v22, v74
	v_mul_f32_e32 v23, v23, v75
	v_mul_f32_e32 v20, v20, v12
	v_mul_f32_e32 v21, v21, v13
	v_mul_f32_e32 v22, v22, v14
	v_mul_f32_e32 v23, v23, v15
	v_cvt_pk_bf16_f32 v20, v20, v21
	v_cvt_pk_bf16_f32 v21, v22, v23
	global_store_dwordx2 v[4:5], v[20:21], off offset:800
	s_waitcnt vmcnt(17)
	v_lshlrev_b32_e32 v12, 16, v28
	v_and_b32_e32 v13, 0xffff0000, v28
	v_lshlrev_b32_e32 v14, 16, v29
	v_and_b32_e32 v15, 0xffff0000, v29
	v_mul_f32_e32 v16, 0xbfb8aa3b, v12
	v_mul_f32_e32 v17, 0xbfb8aa3b, v13
	v_mul_f32_e32 v18, 0xbfb8aa3b, v14
	v_mul_f32_e32 v19, 0xbfb8aa3b, v15
	v_exp_f32_e32 v16, v16
	v_exp_f32_e32 v17, v17
	v_exp_f32_e32 v18, v18
	v_exp_f32_e32 v19, v19
	v_lshlrev_b32_e32 v20, 16, v44
	v_and_b32_e32 v21, 0xffff0000, v44
	v_lshlrev_b32_e32 v22, 16, v45
	v_and_b32_e32 v23, 0xffff0000, v45
	v_add_f32_e32 v16, 1.0, v16
	v_add_f32_e32 v17, 1.0, v17
	v_add_f32_e32 v18, 1.0, v18
	v_add_f32_e32 v19, 1.0, v19
	v_rcp_f32_e32 v16, v16
	v_rcp_f32_e32 v17, v17
	v_rcp_f32_e32 v18, v18
	v_rcp_f32_e32 v19, v19
	v_sub_f32_e32 v20, v20, v7
	v_sub_f32_e32 v21, v21, v7
	v_sub_f32_e32 v22, v22, v7
	v_sub_f32_e32 v23, v23, v7
	v_mul_f32_e32 v20, v20, v8
	v_mul_f32_e32 v21, v21, v8
	v_mul_f32_e32 v22, v22, v8
	v_mul_f32_e32 v23, v23, v8
	v_mul_f32_e32 v12, v12, v16
	v_mul_f32_e32 v13, v13, v17
	v_mul_f32_e32 v14, v14, v18
	v_mul_f32_e32 v15, v15, v19
	v_mul_f32_e32 v20, v20, v76
	v_mul_f32_e32 v21, v21, v77
	v_mul_f32_e32 v22, v22, v78
	v_mul_f32_e32 v23, v23, v79
	v_mul_f32_e32 v20, v20, v12
	v_mul_f32_e32 v21, v21, v13
	v_mul_f32_e32 v22, v22, v14
	v_mul_f32_e32 v23, v23, v15
	v_cvt_pk_bf16_f32 v20, v20, v21
	v_cvt_pk_bf16_f32 v21, v22, v23
	global_store_dwordx2 v[4:5], v[20:21], off offset:832
	s_waitcnt vmcnt(15)
	v_lshlrev_b32_e32 v12, 16, v30
	v_and_b32_e32 v13, 0xffff0000, v30
	v_lshlrev_b32_e32 v14, 16, v31
	v_and_b32_e32 v15, 0xffff0000, v31
	v_mul_f32_e32 v16, 0xbfb8aa3b, v12
	v_mul_f32_e32 v17, 0xbfb8aa3b, v13
	v_mul_f32_e32 v18, 0xbfb8aa3b, v14
	v_mul_f32_e32 v19, 0xbfb8aa3b, v15
	v_exp_f32_e32 v16, v16
	v_exp_f32_e32 v17, v17
	v_exp_f32_e32 v18, v18
	v_exp_f32_e32 v19, v19
	v_lshlrev_b32_e32 v20, 16, v46
	v_and_b32_e32 v21, 0xffff0000, v46
	v_lshlrev_b32_e32 v22, 16, v47
	v_and_b32_e32 v23, 0xffff0000, v47
	v_add_f32_e32 v16, 1.0, v16
	v_add_f32_e32 v17, 1.0, v17
	v_add_f32_e32 v18, 1.0, v18
	v_add_f32_e32 v19, 1.0, v19
	v_rcp_f32_e32 v16, v16
	v_rcp_f32_e32 v17, v17
	v_rcp_f32_e32 v18, v18
	v_rcp_f32_e32 v19, v19
	v_sub_f32_e32 v20, v20, v7
	v_sub_f32_e32 v21, v21, v7
	v_sub_f32_e32 v22, v22, v7
	v_sub_f32_e32 v23, v23, v7
	v_mul_f32_e32 v20, v20, v8
	v_mul_f32_e32 v21, v21, v8
	v_mul_f32_e32 v22, v22, v8
	v_mul_f32_e32 v23, v23, v8
	v_mul_f32_e32 v12, v12, v16
	v_mul_f32_e32 v13, v13, v17
	v_mul_f32_e32 v14, v14, v18
	v_mul_f32_e32 v15, v15, v19
	v_mul_f32_e32 v20, v20, v80
	v_mul_f32_e32 v21, v21, v81
	v_mul_f32_e32 v22, v22, v82
	v_mul_f32_e32 v23, v23, v83
	v_mul_f32_e32 v20, v20, v12
	v_mul_f32_e32 v21, v21, v13
	v_mul_f32_e32 v22, v22, v14
	v_mul_f32_e32 v23, v23, v15
	v_cvt_pk_bf16_f32 v20, v20, v21
	v_cvt_pk_bf16_f32 v21, v22, v23
	global_store_dwordx2 v[4:5], v[20:21], off offset:864
	s_waitcnt vmcnt(13)
	v_lshlrev_b32_e32 v12, 16, v32
	v_and_b32_e32 v13, 0xffff0000, v32
	v_lshlrev_b32_e32 v14, 16, v33
	v_and_b32_e32 v15, 0xffff0000, v33
	v_mul_f32_e32 v16, 0xbfb8aa3b, v12
	v_mul_f32_e32 v17, 0xbfb8aa3b, v13
	v_mul_f32_e32 v18, 0xbfb8aa3b, v14
	v_mul_f32_e32 v19, 0xbfb8aa3b, v15
	v_exp_f32_e32 v16, v16
	v_exp_f32_e32 v17, v17
	v_exp_f32_e32 v18, v18
	v_exp_f32_e32 v19, v19
	v_lshlrev_b32_e32 v20, 16, v48
	v_and_b32_e32 v21, 0xffff0000, v48
	v_lshlrev_b32_e32 v22, 16, v49
	v_and_b32_e32 v23, 0xffff0000, v49
	v_add_f32_e32 v16, 1.0, v16
	v_add_f32_e32 v17, 1.0, v17
	v_add_f32_e32 v18, 1.0, v18
	v_add_f32_e32 v19, 1.0, v19
	v_rcp_f32_e32 v16, v16
	v_rcp_f32_e32 v17, v17
	v_rcp_f32_e32 v18, v18
	v_rcp_f32_e32 v19, v19
	v_sub_f32_e32 v20, v20, v7
	v_sub_f32_e32 v21, v21, v7
	v_sub_f32_e32 v22, v22, v7
	v_sub_f32_e32 v23, v23, v7
	v_mul_f32_e32 v20, v20, v8
	v_mul_f32_e32 v21, v21, v8
	v_mul_f32_e32 v22, v22, v8
	v_mul_f32_e32 v23, v23, v8
	v_mul_f32_e32 v12, v12, v16
	v_mul_f32_e32 v13, v13, v17
	v_mul_f32_e32 v14, v14, v18
	v_mul_f32_e32 v15, v15, v19
	v_mul_f32_e32 v20, v20, v84
	v_mul_f32_e32 v21, v21, v85
	v_mul_f32_e32 v22, v22, v86
	v_mul_f32_e32 v23, v23, v87
	v_mul_f32_e32 v20, v20, v12
	v_mul_f32_e32 v21, v21, v13
	v_mul_f32_e32 v22, v22, v14
	v_mul_f32_e32 v23, v23, v15
	v_cvt_pk_bf16_f32 v20, v20, v21
	v_cvt_pk_bf16_f32 v21, v22, v23
	global_store_dwordx2 v[4:5], v[20:21], off offset:896
	s_waitcnt vmcnt(11)
	v_lshlrev_b32_e32 v12, 16, v34
	v_and_b32_e32 v13, 0xffff0000, v34
	v_lshlrev_b32_e32 v14, 16, v35
	v_and_b32_e32 v15, 0xffff0000, v35
	v_mul_f32_e32 v16, 0xbfb8aa3b, v12
	v_mul_f32_e32 v17, 0xbfb8aa3b, v13
	v_mul_f32_e32 v18, 0xbfb8aa3b, v14
	v_mul_f32_e32 v19, 0xbfb8aa3b, v15
	v_exp_f32_e32 v16, v16
	v_exp_f32_e32 v17, v17
	v_exp_f32_e32 v18, v18
	v_exp_f32_e32 v19, v19
	v_lshlrev_b32_e32 v20, 16, v50
	v_and_b32_e32 v21, 0xffff0000, v50
	v_lshlrev_b32_e32 v22, 16, v51
	v_and_b32_e32 v23, 0xffff0000, v51
	v_add_f32_e32 v16, 1.0, v16
	v_add_f32_e32 v17, 1.0, v17
	v_add_f32_e32 v18, 1.0, v18
	v_add_f32_e32 v19, 1.0, v19
	v_rcp_f32_e32 v16, v16
	v_rcp_f32_e32 v17, v17
	v_rcp_f32_e32 v18, v18
	v_rcp_f32_e32 v19, v19
	v_sub_f32_e32 v20, v20, v7
	v_sub_f32_e32 v21, v21, v7
	v_sub_f32_e32 v22, v22, v7
	v_sub_f32_e32 v23, v23, v7
	v_mul_f32_e32 v20, v20, v8
	v_mul_f32_e32 v21, v21, v8
	v_mul_f32_e32 v22, v22, v8
	v_mul_f32_e32 v23, v23, v8
	v_mul_f32_e32 v12, v12, v16
	v_mul_f32_e32 v13, v13, v17
	v_mul_f32_e32 v14, v14, v18
	v_mul_f32_e32 v15, v15, v19
	v_mul_f32_e32 v20, v20, v88
	v_mul_f32_e32 v21, v21, v89
	v_mul_f32_e32 v22, v22, v90
	v_mul_f32_e32 v23, v23, v91
	v_mul_f32_e32 v20, v20, v12
	v_mul_f32_e32 v21, v21, v13
	v_mul_f32_e32 v22, v22, v14
	v_mul_f32_e32 v23, v23, v15
	v_cvt_pk_bf16_f32 v20, v20, v21
	v_cvt_pk_bf16_f32 v21, v22, v23
	global_store_dwordx2 v[4:5], v[20:21], off offset:928
	s_waitcnt vmcnt(9)
	v_lshlrev_b32_e32 v12, 16, v36
	v_and_b32_e32 v13, 0xffff0000, v36
	v_lshlrev_b32_e32 v14, 16, v37
	v_and_b32_e32 v15, 0xffff0000, v37
	v_mul_f32_e32 v16, 0xbfb8aa3b, v12
	v_mul_f32_e32 v17, 0xbfb8aa3b, v13
	v_mul_f32_e32 v18, 0xbfb8aa3b, v14
	v_mul_f32_e32 v19, 0xbfb8aa3b, v15
	v_exp_f32_e32 v16, v16
	v_exp_f32_e32 v17, v17
	v_exp_f32_e32 v18, v18
	v_exp_f32_e32 v19, v19
	v_lshlrev_b32_e32 v20, 16, v52
	v_and_b32_e32 v21, 0xffff0000, v52
	v_lshlrev_b32_e32 v22, 16, v53
	v_and_b32_e32 v23, 0xffff0000, v53
	v_add_f32_e32 v16, 1.0, v16
	v_add_f32_e32 v17, 1.0, v17
	v_add_f32_e32 v18, 1.0, v18
	v_add_f32_e32 v19, 1.0, v19
	v_rcp_f32_e32 v16, v16
	v_rcp_f32_e32 v17, v17
	v_rcp_f32_e32 v18, v18
	v_rcp_f32_e32 v19, v19
	v_sub_f32_e32 v20, v20, v7
	v_sub_f32_e32 v21, v21, v7
	v_sub_f32_e32 v22, v22, v7
	v_sub_f32_e32 v23, v23, v7
	v_mul_f32_e32 v20, v20, v8
	v_mul_f32_e32 v21, v21, v8
	v_mul_f32_e32 v22, v22, v8
	v_mul_f32_e32 v23, v23, v8
	v_mul_f32_e32 v12, v12, v16
	v_mul_f32_e32 v13, v13, v17
	v_mul_f32_e32 v14, v14, v18
	v_mul_f32_e32 v15, v15, v19
	v_mul_f32_e32 v20, v20, v92
	v_mul_f32_e32 v21, v21, v93
	v_mul_f32_e32 v22, v22, v94
	v_mul_f32_e32 v23, v23, v95
	v_mul_f32_e32 v20, v20, v12
	v_mul_f32_e32 v21, v21, v13
	v_mul_f32_e32 v22, v22, v14
	v_mul_f32_e32 v23, v23, v15
	v_cvt_pk_bf16_f32 v20, v20, v21
	v_cvt_pk_bf16_f32 v21, v22, v23
	global_store_dwordx2 v[4:5], v[20:21], off offset:960
	s_waitcnt vmcnt(7)
	v_lshlrev_b32_e32 v12, 16, v38
	v_and_b32_e32 v13, 0xffff0000, v38
	v_lshlrev_b32_e32 v14, 16, v39
	v_and_b32_e32 v15, 0xffff0000, v39
	v_mul_f32_e32 v16, 0xbfb8aa3b, v12
	v_mul_f32_e32 v17, 0xbfb8aa3b, v13
	v_mul_f32_e32 v18, 0xbfb8aa3b, v14
	v_mul_f32_e32 v19, 0xbfb8aa3b, v15
	v_exp_f32_e32 v16, v16
	v_exp_f32_e32 v17, v17
	v_exp_f32_e32 v18, v18
	v_exp_f32_e32 v19, v19
	v_lshlrev_b32_e32 v20, 16, v54
	v_and_b32_e32 v21, 0xffff0000, v54
	v_lshlrev_b32_e32 v22, 16, v55
	v_and_b32_e32 v23, 0xffff0000, v55
	v_add_f32_e32 v16, 1.0, v16
	v_add_f32_e32 v17, 1.0, v17
	v_add_f32_e32 v18, 1.0, v18
	v_add_f32_e32 v19, 1.0, v19
	v_rcp_f32_e32 v16, v16
	v_rcp_f32_e32 v17, v17
	v_rcp_f32_e32 v18, v18
	v_rcp_f32_e32 v19, v19
	v_sub_f32_e32 v20, v20, v7
	v_sub_f32_e32 v21, v21, v7
	v_sub_f32_e32 v22, v22, v7
	v_sub_f32_e32 v23, v23, v7
	v_mul_f32_e32 v20, v20, v8
	v_mul_f32_e32 v21, v21, v8
	v_mul_f32_e32 v22, v22, v8
	v_mul_f32_e32 v23, v23, v8
	v_mul_f32_e32 v12, v12, v16
	v_mul_f32_e32 v13, v13, v17
	v_mul_f32_e32 v14, v14, v18
	v_mul_f32_e32 v15, v15, v19
	v_mul_f32_e32 v20, v20, v96
	v_mul_f32_e32 v21, v21, v97
	v_mul_f32_e32 v22, v22, v98
	v_mul_f32_e32 v23, v23, v99
	v_mul_f32_e32 v20, v20, v12
	v_mul_f32_e32 v21, v21, v13
	v_mul_f32_e32 v22, v22, v14
	v_mul_f32_e32 v23, v23, v15
	v_cvt_pk_bf16_f32 v20, v20, v21
	v_cvt_pk_bf16_f32 v21, v22, v23
	global_store_dwordx2 v[4:5], v[20:21], off offset:992
	s_mov_b64 s[34:35], 0
	s_and_b64 vcc, exec, s[30:31]
	s_cbranch_vccnz .LBB0_701

.LBB0_748:
	s_add_u32 s12, s26, 0x1e800000
	s_addc_u32 s13, s27, 0
	s_add_u32 s18, s26, 0x1d500000
	s_addc_u32 s19, s27, 0
	s_add_u32 s16, s26, 0x1d900000
	s_addc_u32 s17, s27, 0
	v_mov_b32_e32 v0, v208
	s_add_u32 s14, s26, 0x1ad00000
	s_addc_u32 s15, s27, 0
	v_and_b32_e32 v1, 63, v0
	v_bfe_u32 v2, v0, 4, 2
	v_readlane_b32 s2, v254, 9
	v_and_b32_e32 v3, 15, v0
	v_and_b32_e32 v200, 7, v0
	v_lshlrev_b32_e32 v0, 2, v1
	v_lshlrev_b32_e32 v182, 2, v2
	s_add_u32 s20, s26, 0x1e500002
	v_readlane_b32 s3, v254, 10
	v_lshlrev_b32_e32 v198, 3, v2
	v_lshlrev_b32_e32 v199, 5, v3
	v_xor_b32_e32 v180, 64, v0
	v_xor_b32_e32 v181, 0x80, v0
	v_or_b32_e32 v183, 1, v182
	v_or_b32_e32 v184, 2, v182
	v_or_b32_e32 v185, 3, v182
	v_or_b32_e32 v186, 16, v182
	v_or_b32_e32 v187, 17, v182
	v_or_b32_e32 v188, 18, v182
	v_or_b32_e32 v189, 19, v182
	v_or_b32_e32 v190, 32, v182
	v_or_b32_e32 v191, 33, v182
	v_or_b32_e32 v192, 34, v182
	v_or_b32_e32 v193, 35, v182
	v_or_b32_e32 v194, 48, v182
	v_or_b32_e32 v195, 49, v182
	v_or_b32_e32 v196, 50, v182
	v_or_b32_e32 v197, 51, v182
	v_cmp_gt_u32_e64 s[8:9], 8, v3
	s_addc_u32 s21, s27, 0
	s_mov_b64 s[0:1], -1
	s_and_b64 vcc, exec, s[2:3]
	s_cbranch_vccz .LBB0_841
	s_mov_b64 s[22:23], exec

.Lsel_maxA:
	v_max3_f32 v66, v184, v185, v186
	v_max3_f32 v67, v187, v188, v189
	v_max3_f32 v144, v190, v191, v192
	v_max3_f32 v145, v193, v194, v195
	v_max3_f32 v66, v66, v172, v173
	v_max3_f32 v67, v67, v174, v175
	v_max3_f32 v66, v66, v67, v144
	v_max_f32_e32 v66, v66, v145
	v_mov_b32_e32 v67, v66
	s_nop 1
	v_permlane16_swap_b32_e32 v67, v66
	v_max_f32_e32 v66, v66, v67
	v_mov_b32_e32 v67, v66
	s_nop 1
	v_permlane32_swap_b32_e32 v67, v66
	v_max_f32_e32 v143, v66, v67
	v_cmp_gt_f32_e32 vcc, v143, v196
	s_cbranch_vccz .Lsel_norescA
	v_max_f32_e32 v143, v196, v143
	v_sub_f32_e32 v66, v196, v143
	v_exp_f32_e32 v66, v66
	v_mov_b32_e32 v196, v143
	s_nop 0
	v_pk_mul_f32 v[0:1], v[0:1], v[66:67] op_sel_hi:[1,0]
	v_pk_mul_f32 v[2:3], v[2:3], v[66:67] op_sel_hi:[1,0]
	v_pk_mul_f32 v[4:5], v[4:5], v[66:67] op_sel_hi:[1,0]
	v_pk_mul_f32 v[6:7], v[6:7], v[66:67] op_sel_hi:[1,0]
	v_pk_mul_f32 v[8:9], v[8:9], v[66:67] op_sel_hi:[1,0]
	v_pk_mul_f32 v[10:11], v[10:11], v[66:67] op_sel_hi:[1,0]
	v_pk_mul_f32 v[12:13], v[12:13], v[66:67] op_sel_hi:[1,0]
	v_pk_mul_f32 v[14:15], v[14:15], v[66:67] op_sel_hi:[1,0]
	v_mul_f32_e32 v197, v197, v66
